# P5 wave-0 triangular inverse regenerated: packed f32 FMAs (even/odd partial sums), two interleaved row chains, LDS read stream prefetched 7 chunks ahead (f32 as baseline)
# speedup vs baseline: 1.0058x; 1.0058x over previous
; __device__ __forceinline__ void gdn_chunk_prep(Frame& F) {
;     ...
;         if (wave == 0) {
;             float T[64];
; #pragma unroll
;             for (int i = 0; i < 50; i += 2) {
;                 float a = (i == lane) ? 1.f : 0.f, bq = (i + 1 == lane) ? 1.f : 0.f;
; #pragma unroll
;                 for (int j = 0; j < i; ++j) { a = fmaf(-Amat[i * 68 + j], T[j], a); bq = fmaf(-Amat[(i + 1) * 68 + j], T[j], bq); }
;                 T[i] = a;
;                 T[i + 1] = fmaf(-Amat[(i + 1) * 68 + i], a, bq);
;                 asm volatile("" ::: "memory");
;             }
.LBB0_1084:
	s_and_b64 vcc, exec, s[18:19]
	s_cbranch_vccz .LBB0_1086
	s_waitcnt vmcnt(0)
	v_cmp_eq_u32_e32 vcc, 0, v127
	v_mov_b32_e32 v3, 0
	v_mov_b32_e32 v5, 0
	v_cndmask_b32_e64 v2, 0, 1.0, vcc
	v_cmp_eq_u32_e32 vcc, 1, v127
	s_nop 1
	v_cndmask_b32_e64 v4, 0, 1.0, vcc
	ds_read_b32 v68, v115 offset:2320
	s_waitcnt lgkmcnt(0)
	ds_read_b128 v[72:75], v115 offset:2592
	ds_read_b128 v[76:79], v115 offset:2864
	ds_read_b128 v[80:83], v115 offset:3136
	ds_read_b128 v[84:87], v115 offset:3408
	ds_read_b32 v88, v115 offset:3424
	ds_read_b128 v[92:95], v115 offset:3680
	ds_read_b128 v[96:99], v115 offset:3952
	v_add_f32_e32 v2, v2, v3
	v_add_f32_e32 v4, v4, v5
	v_fma_f32 v3, -v68, v2, v4
	v_cmp_eq_u32_e32 vcc, 2, v127
	v_mov_b32_e32 v5, 0
	v_mov_b32_e32 v7, 0
	v_cndmask_b32_e64 v4, 0, 1.0, vcc
	v_cmp_eq_u32_e32 vcc, 3, v127
	s_nop 1
	v_cndmask_b32_e64 v6, 0, 1.0, vcc
	s_waitcnt lgkmcnt(5)
	v_pk_fma_f32 v[4:5], v[72:73], v[2:3], v[4:5] neg_lo:[1,0,0] neg_hi:[1,0,0]
	v_pk_fma_f32 v[6:7], v[76:77], v[2:3], v[6:7] neg_lo:[1,0,0] neg_hi:[1,0,0]
	ds_read_b128 v[68:71], v115 offset:3696
	ds_read_b128 v[72:75], v115 offset:3968
	v_add_f32_e32 v4, v4, v5
	v_add_f32_e32 v6, v6, v7
	v_fma_f32 v5, -v78, v4, v6
	v_cmp_eq_u32_e32 vcc, 4, v127
	v_mov_b32_e32 v7, 0
	v_mov_b32_e32 v9, 0
	v_cndmask_b32_e64 v6, 0, 1.0, vcc
	v_cmp_eq_u32_e32 vcc, 5, v127
	s_nop 1
	v_cndmask_b32_e64 v8, 0, 1.0, vcc
	s_waitcnt lgkmcnt(5)
	v_pk_fma_f32 v[6:7], v[80:81], v[2:3], v[6:7] neg_lo:[1,0,0] neg_hi:[1,0,0]
	v_pk_fma_f32 v[8:9], v[84:85], v[2:3], v[8:9] neg_lo:[1,0,0] neg_hi:[1,0,0]
	v_pk_fma_f32 v[6:7], v[82:83], v[4:5], v[6:7] neg_lo:[1,0,0] neg_hi:[1,0,0]
	v_pk_fma_f32 v[8:9], v[86:87], v[4:5], v[8:9] neg_lo:[1,0,0] neg_hi:[1,0,0]
	ds_read_b128 v[76:79], v115 offset:4224
	ds_read_b128 v[80:83], v115 offset:4496
	s_waitcnt lgkmcnt(6)
	ds_read_b128 v[84:87], v115 offset:4240
	v_add_f32_e32 v6, v6, v7
	v_add_f32_e32 v8, v8, v9
	v_fma_f32 v7, -v88, v6, v8
	v_cmp_eq_u32_e32 vcc, 6, v127
	v_mov_b32_e32 v9, 0
	v_mov_b32_e32 v11, 0
	v_cndmask_b32_e64 v8, 0, 1.0, vcc
	v_cmp_eq_u32_e32 vcc, 7, v127
	s_nop 1
	v_cndmask_b32_e64 v10, 0, 1.0, vcc
	s_waitcnt lgkmcnt(5)
	v_pk_fma_f32 v[8:9], v[92:93], v[2:3], v[8:9] neg_lo:[1,0,0] neg_hi:[1,0,0]
	v_pk_fma_f32 v[10:11], v[96:97], v[2:3], v[10:11] neg_lo:[1,0,0] neg_hi:[1,0,0]
	v_pk_fma_f32 v[8:9], v[94:95], v[4:5], v[8:9] neg_lo:[1,0,0] neg_hi:[1,0,0]
	v_pk_fma_f32 v[10:11], v[98:99], v[4:5], v[10:11] neg_lo:[1,0,0] neg_hi:[1,0,0]
	ds_read_b128 v[88:91], v115 offset:4512
	ds_read_b32 v92, v115 offset:4528
	s_waitcnt lgkmcnt(5)
	v_pk_fma_f32 v[8:9], v[68:69], v[6:7], v[8:9] neg_lo:[1,0,0] neg_hi:[1,0,0]
	v_pk_fma_f32 v[10:11], v[72:73], v[6:7], v[10:11] neg_lo:[1,0,0] neg_hi:[1,0,0]
	ds_read_b128 v[96:99], v115 offset:4768
	ds_read_b128 v[68:71], v115 offset:5040
	v_add_f32_e32 v8, v8, v9
	v_add_f32_e32 v10, v10, v11
	v_fma_f32 v9, -v74, v8, v10
	v_cmp_eq_u32_e32 vcc, 8, v127
	v_mov_b32_e32 v11, 0
	v_mov_b32_e32 v13, 0
	v_cndmask_b32_e64 v10, 0, 1.0, vcc
	v_cmp_eq_u32_e32 vcc, 9, v127
	s_nop 1
	v_cndmask_b32_e64 v12, 0, 1.0, vcc
	s_waitcnt lgkmcnt(5)
	v_pk_fma_f32 v[10:11], v[76:77], v[2:3], v[10:11] neg_lo:[1,0,0] neg_hi:[1,0,0]
	v_pk_fma_f32 v[12:13], v[80:81], v[2:3], v[12:13] neg_lo:[1,0,0] neg_hi:[1,0,0]
	v_pk_fma_f32 v[10:11], v[78:79], v[4:5], v[10:11] neg_lo:[1,0,0] neg_hi:[1,0,0]
	v_pk_fma_f32 v[12:13], v[82:83], v[4:5], v[12:13] neg_lo:[1,0,0] neg_hi:[1,0,0]
	ds_read_b128 v[72:75], v115 offset:4784
	ds_read_b128 v[76:79], v115 offset:5056
	s_waitcnt lgkmcnt(5)
	v_pk_fma_f32 v[10:11], v[84:85], v[6:7], v[10:11] neg_lo:[1,0,0] neg_hi:[1,0,0]
	v_pk_fma_f32 v[12:13], v[88:89], v[6:7], v[12:13] neg_lo:[1,0,0] neg_hi:[1,0,0]
	v_pk_fma_f32 v[10:11], v[86:87], v[8:9], v[10:11] neg_lo:[1,0,0] neg_hi:[1,0,0]
	v_pk_fma_f32 v[12:13], v[90:91], v[8:9], v[12:13] neg_lo:[1,0,0] neg_hi:[1,0,0]
	ds_read_b128 v[80:83], v115 offset:4800
	ds_read_b128 v[84:87], v115 offset:5072
	s_waitcnt lgkmcnt(6)
	ds_read_b128 v[88:91], v115 offset:5312
	v_add_f32_e32 v10, v10, v11
	v_add_f32_e32 v12, v12, v13
	v_fma_f32 v11, -v92, v10, v12
	v_cmp_eq_u32_e32 vcc, 10, v127
	v_mov_b32_e32 v13, 0
	v_mov_b32_e32 v15, 0
	v_cndmask_b32_e64 v12, 0, 1.0, vcc
	v_cmp_eq_u32_e32 vcc, 11, v127
	s_nop 1
	v_cndmask_b32_e64 v14, 0, 1.0, vcc
	s_waitcnt lgkmcnt(5)
	v_pk_fma_f32 v[12:13], v[96:97], v[2:3], v[12:13] neg_lo:[1,0,0] neg_hi:[1,0,0]
	v_pk_fma_f32 v[14:15], v[68:69], v[2:3], v[14:15] neg_lo:[1,0,0] neg_hi:[1,0,0]
	v_pk_fma_f32 v[12:13], v[98:99], v[4:5], v[12:13] neg_lo:[1,0,0] neg_hi:[1,0,0]
	v_pk_fma_f32 v[14:15], v[70:71], v[4:5], v[14:15] neg_lo:[1,0,0] neg_hi:[1,0,0]
	ds_read_b128 v[92:95], v115 offset:5584
	ds_read_b128 v[96:99], v115 offset:5328
	s_waitcnt lgkmcnt(5)
	v_pk_fma_f32 v[12:13], v[72:73], v[6:7], v[12:13] neg_lo:[1,0,0] neg_hi:[1,0,0]
	v_pk_fma_f32 v[14:15], v[76:77], v[6:7], v[14:15] neg_lo:[1,0,0] neg_hi:[1,0,0]
	v_pk_fma_f32 v[12:13], v[74:75], v[8:9], v[12:13] neg_lo:[1,0,0] neg_hi:[1,0,0]
	v_pk_fma_f32 v[14:15], v[78:79], v[8:9], v[14:15] neg_lo:[1,0,0] neg_hi:[1,0,0]
	ds_read_b128 v[68:71], v115 offset:5600
	ds_read_b128 v[72:75], v115 offset:5344
	s_waitcnt lgkmcnt(5)
	v_pk_fma_f32 v[12:13], v[80:81], v[10:11], v[12:13] neg_lo:[1,0,0] neg_hi:[1,0,0]
	v_pk_fma_f32 v[14:15], v[84:85], v[10:11], v[14:15] neg_lo:[1,0,0] neg_hi:[1,0,0]
	ds_read_b128 v[76:79], v115 offset:5616
	ds_read_b32 v80, v115 offset:5632
	v_add_f32_e32 v12, v12, v13
	v_add_f32_e32 v14, v14, v15
	v_fma_f32 v13, -v86, v12, v14
	v_cmp_eq_u32_e32 vcc, 12, v127
	v_mov_b32_e32 v15, 0
	v_mov_b32_e32 v17, 0
	v_cndmask_b32_e64 v14, 0, 1.0, vcc
	v_cmp_eq_u32_e32 vcc, 13, v127
	s_nop 1
	v_cndmask_b32_e64 v16, 0, 1.0, vcc
	s_waitcnt lgkmcnt(5)
; __device__ __forceinline__ void gdn_chunk_prep(Frame& F) {
;     ...
;         if (wave == 0) {
;             float T[64];
; #pragma unroll
;             for (int i = 0; i < 50; i += 2) {
;                 float a = (i == lane) ? 1.f : 0.f, bq = (i + 1 == lane) ? 1.f : 0.f;
; #pragma unroll
;                 for (int j = 0; j < i; ++j) { a = fmaf(-Amat[i * 68 + j], T[j], a); bq = fmaf(-Amat[(i + 1) * 68 + j], T[j], bq); }
;                 T[i] = a;
;                 T[i + 1] = fmaf(-Amat[(i + 1) * 68 + i], a, bq);
;                 asm volatile("" ::: "memory");
;             }
	v_pk_fma_f32 v[14:15], v[88:89], v[2:3], v[14:15] neg_lo:[1,0,0] neg_hi:[1,0,0]
	v_pk_fma_f32 v[16:17], v[92:93], v[2:3], v[16:17] neg_lo:[1,0,0] neg_hi:[1,0,0]
	v_pk_fma_f32 v[14:15], v[90:91], v[4:5], v[14:15] neg_lo:[1,0,0] neg_hi:[1,0,0]
	v_pk_fma_f32 v[16:17], v[94:95], v[4:5], v[16:17] neg_lo:[1,0,0] neg_hi:[1,0,0]
	ds_read_b128 v[84:87], v115 offset:5856
	ds_read_b128 v[88:91], v115 offset:6128
	s_waitcnt lgkmcnt(5)
	v_pk_fma_f32 v[14:15], v[96:97], v[6:7], v[14:15] neg_lo:[1,0,0] neg_hi:[1,0,0]
	v_pk_fma_f32 v[16:17], v[68:69], v[6:7], v[16:17] neg_lo:[1,0,0] neg_hi:[1,0,0]
	v_pk_fma_f32 v[14:15], v[98:99], v[8:9], v[14:15] neg_lo:[1,0,0] neg_hi:[1,0,0]
	v_pk_fma_f32 v[16:17], v[70:71], v[8:9], v[16:17] neg_lo:[1,0,0] neg_hi:[1,0,0]
	ds_read_b128 v[92:95], v115 offset:5872
	ds_read_b128 v[96:99], v115 offset:6144
	s_waitcnt lgkmcnt(5)
	v_pk_fma_f32 v[14:15], v[72:73], v[10:11], v[14:15] neg_lo:[1,0,0] neg_hi:[1,0,0]
	v_pk_fma_f32 v[16:17], v[76:77], v[10:11], v[16:17] neg_lo:[1,0,0] neg_hi:[1,0,0]
	v_pk_fma_f32 v[14:15], v[74:75], v[12:13], v[14:15] neg_lo:[1,0,0] neg_hi:[1,0,0]
	v_pk_fma_f32 v[16:17], v[78:79], v[12:13], v[16:17] neg_lo:[1,0,0] neg_hi:[1,0,0]
	ds_read_b128 v[68:71], v115 offset:5888
	ds_read_b128 v[72:75], v115 offset:6160
	s_waitcnt lgkmcnt(6)
	ds_read_b128 v[76:79], v115 offset:5904
	v_add_f32_e32 v14, v14, v15
	v_add_f32_e32 v16, v16, v17
	v_fma_f32 v15, -v80, v14, v16
	v_cmp_eq_u32_e32 vcc, 14, v127
	v_mov_b32_e32 v17, 0
	v_mov_b32_e32 v19, 0
	v_cndmask_b32_e64 v16, 0, 1.0, vcc
	v_cmp_eq_u32_e32 vcc, 15, v127
	s_nop 1
	v_cndmask_b32_e64 v18, 0, 1.0, vcc
	s_waitcnt lgkmcnt(5)
	v_pk_fma_f32 v[16:17], v[84:85], v[2:3], v[16:17] neg_lo:[1,0,0] neg_hi:[1,0,0]
	v_pk_fma_f32 v[18:19], v[88:89], v[2:3], v[18:19] neg_lo:[1,0,0] neg_hi:[1,0,0]
	v_pk_fma_f32 v[16:17], v[86:87], v[4:5], v[16:17] neg_lo:[1,0,0] neg_hi:[1,0,0]
	v_pk_fma_f32 v[18:19], v[90:91], v[4:5], v[18:19] neg_lo:[1,0,0] neg_hi:[1,0,0]
	ds_read_b128 v[80:83], v115 offset:6176
	ds_read_b128 v[84:87], v115 offset:6400
	s_waitcnt lgkmcnt(5)
	v_pk_fma_f32 v[16:17], v[92:93], v[6:7], v[16:17] neg_lo:[1,0,0] neg_hi:[1,0,0]
	v_pk_fma_f32 v[18:19], v[96:97], v[6:7], v[18:19] neg_lo:[1,0,0] neg_hi:[1,0,0]
	v_pk_fma_f32 v[16:17], v[94:95], v[8:9], v[16:17] neg_lo:[1,0,0] neg_hi:[1,0,0]
	v_pk_fma_f32 v[18:19], v[98:99], v[8:9], v[18:19] neg_lo:[1,0,0] neg_hi:[1,0,0]
	ds_read_b128 v[88:91], v115 offset:6672
	ds_read_b128 v[92:95], v115 offset:6416
	s_waitcnt lgkmcnt(5)
	v_pk_fma_f32 v[16:17], v[68:69], v[10:11], v[16:17] neg_lo:[1,0,0] neg_hi:[1,0,0]
	v_pk_fma_f32 v[18:19], v[72:73], v[10:11], v[18:19] neg_lo:[1,0,0] neg_hi:[1,0,0]
	v_pk_fma_f32 v[16:17], v[70:71], v[12:13], v[16:17] neg_lo:[1,0,0] neg_hi:[1,0,0]
	v_pk_fma_f32 v[18:19], v[74:75], v[12:13], v[18:19] neg_lo:[1,0,0] neg_hi:[1,0,0]
	ds_read_b128 v[96:99], v115 offset:6688
	ds_read_b128 v[68:71], v115 offset:6432
	s_waitcnt lgkmcnt(5)
	v_pk_fma_f32 v[16:17], v[76:77], v[14:15], v[16:17] neg_lo:[1,0,0] neg_hi:[1,0,0]
	v_pk_fma_f32 v[18:19], v[80:81], v[14:15], v[18:19] neg_lo:[1,0,0] neg_hi:[1,0,0]
	ds_read_b128 v[72:75], v115 offset:6704
	ds_read_b128 v[76:79], v115 offset:6448
	v_add_f32_e32 v16, v16, v17
	v_add_f32_e32 v18, v18, v19
	v_fma_f32 v17, -v82, v16, v18
	v_cmp_eq_u32_e32 vcc, 16, v127
	v_mov_b32_e32 v19, 0
	v_mov_b32_e32 v21, 0
	v_cndmask_b32_e64 v18, 0, 1.0, vcc
	v_cmp_eq_u32_e32 vcc, 17, v127
	s_nop 1
	v_cndmask_b32_e64 v20, 0, 1.0, vcc
	s_waitcnt lgkmcnt(5)
	v_pk_fma_f32 v[18:19], v[84:85], v[2:3], v[18:19] neg_lo:[1,0,0] neg_hi:[1,0,0]
	v_pk_fma_f32 v[20:21], v[88:89], v[2:3], v[20:21] neg_lo:[1,0,0] neg_hi:[1,0,0]
	v_pk_fma_f32 v[18:19], v[86:87], v[4:5], v[18:19] neg_lo:[1,0,0] neg_hi:[1,0,0]
	v_pk_fma_f32 v[20:21], v[90:91], v[4:5], v[20:21] neg_lo:[1,0,0] neg_hi:[1,0,0]
	ds_read_b128 v[80:83], v115 offset:6720
	ds_read_b32 v84, v115 offset:6736
	s_waitcnt lgkmcnt(5)
	v_pk_fma_f32 v[18:19], v[92:93], v[6:7], v[18:19] neg_lo:[1,0,0] neg_hi:[1,0,0]
	v_pk_fma_f32 v[20:21], v[96:97], v[6:7], v[20:21] neg_lo:[1,0,0] neg_hi:[1,0,0]
	v_pk_fma_f32 v[18:19], v[94:95], v[8:9], v[18:19] neg_lo:[1,0,0] neg_hi:[1,0,0]
	v_pk_fma_f32 v[20:21], v[98:99], v[8:9], v[20:21] neg_lo:[1,0,0] neg_hi:[1,0,0]
	ds_read_b128 v[88:91], v115 offset:6944
	ds_read_b128 v[92:95], v115 offset:7216
	s_waitcnt lgkmcnt(5)
	v_pk_fma_f32 v[18:19], v[68:69], v[10:11], v[18:19] neg_lo:[1,0,0] neg_hi:[1,0,0]
	v_pk_fma_f32 v[20:21], v[72:73], v[10:11], v[20:21] neg_lo:[1,0,0] neg_hi:[1,0,0]
	v_pk_fma_f32 v[18:19], v[70:71], v[12:13], v[18:19] neg_lo:[1,0,0] neg_hi:[1,0,0]
	v_pk_fma_f32 v[20:21], v[74:75], v[12:13], v[20:21] neg_lo:[1,0,0] neg_hi:[1,0,0]
	ds_read_b128 v[96:99], v115 offset:6960
	ds_read_b128 v[68:71], v115 offset:7232
	s_waitcnt lgkmcnt(5)
	v_pk_fma_f32 v[18:19], v[76:77], v[14:15], v[18:19] neg_lo:[1,0,0] neg_hi:[1,0,0]
	v_pk_fma_f32 v[20:21], v[80:81], v[14:15], v[20:21] neg_lo:[1,0,0] neg_hi:[1,0,0]
	v_pk_fma_f32 v[18:19], v[78:79], v[16:17], v[18:19] neg_lo:[1,0,0] neg_hi:[1,0,0]
	v_pk_fma_f32 v[20:21], v[82:83], v[16:17], v[20:21] neg_lo:[1,0,0] neg_hi:[1,0,0]
	ds_read_b128 v[72:75], v115 offset:6976
	ds_read_b128 v[76:79], v115 offset:7248
	s_waitcnt lgkmcnt(6)
	ds_read_b128 v[80:83], v115 offset:6992
	v_add_f32_e32 v18, v18, v19
	v_add_f32_e32 v20, v20, v21
	v_fma_f32 v19, -v84, v18, v20
	v_cmp_eq_u32_e32 vcc, 18, v127
	v_mov_b32_e32 v21, 0
	v_mov_b32_e32 v23, 0
	v_cndmask_b32_e64 v20, 0, 1.0, vcc
	v_cmp_eq_u32_e32 vcc, 19, v127
	s_nop 1
	v_cndmask_b32_e64 v22, 0, 1.0, vcc
	s_waitcnt lgkmcnt(5)
; __device__ __forceinline__ void gdn_chunk_prep(Frame& F) {
;     ...
;         if (wave == 0) {
;             float T[64];
; #pragma unroll
;             for (int i = 0; i < 50; i += 2) {
;                 float a = (i == lane) ? 1.f : 0.f, bq = (i + 1 == lane) ? 1.f : 0.f;
; #pragma unroll
;                 for (int j = 0; j < i; ++j) { a = fmaf(-Amat[i * 68 + j], T[j], a); bq = fmaf(-Amat[(i + 1) * 68 + j], T[j], bq); }
;                 T[i] = a;
;                 T[i + 1] = fmaf(-Amat[(i + 1) * 68 + i], a, bq);
;                 asm volatile("" ::: "memory");
;             }
	v_pk_fma_f32 v[20:21], v[88:89], v[2:3], v[20:21] neg_lo:[1,0,0] neg_hi:[1,0,0]
	v_pk_fma_f32 v[22:23], v[92:93], v[2:3], v[22:23] neg_lo:[1,0,0] neg_hi:[1,0,0]
	v_pk_fma_f32 v[20:21], v[90:91], v[4:5], v[20:21] neg_lo:[1,0,0] neg_hi:[1,0,0]
	v_pk_fma_f32 v[22:23], v[94:95], v[4:5], v[22:23] neg_lo:[1,0,0] neg_hi:[1,0,0]
	ds_read_b128 v[84:87], v115 offset:7264
	ds_read_b128 v[88:91], v115 offset:7008
	s_waitcnt lgkmcnt(5)
	v_pk_fma_f32 v[20:21], v[96:97], v[6:7], v[20:21] neg_lo:[1,0,0] neg_hi:[1,0,0]
	v_pk_fma_f32 v[22:23], v[68:69], v[6:7], v[22:23] neg_lo:[1,0,0] neg_hi:[1,0,0]
	v_pk_fma_f32 v[20:21], v[98:99], v[8:9], v[20:21] neg_lo:[1,0,0] neg_hi:[1,0,0]
	v_pk_fma_f32 v[22:23], v[70:71], v[8:9], v[22:23] neg_lo:[1,0,0] neg_hi:[1,0,0]
	ds_read_b128 v[92:95], v115 offset:7280
	ds_read_b128 v[96:99], v115 offset:7488
	s_waitcnt lgkmcnt(5)
	v_pk_fma_f32 v[20:21], v[72:73], v[10:11], v[20:21] neg_lo:[1,0,0] neg_hi:[1,0,0]
	v_pk_fma_f32 v[22:23], v[76:77], v[10:11], v[22:23] neg_lo:[1,0,0] neg_hi:[1,0,0]
	v_pk_fma_f32 v[20:21], v[74:75], v[12:13], v[20:21] neg_lo:[1,0,0] neg_hi:[1,0,0]
	v_pk_fma_f32 v[22:23], v[78:79], v[12:13], v[22:23] neg_lo:[1,0,0] neg_hi:[1,0,0]
	ds_read_b128 v[68:71], v115 offset:7760
	ds_read_b128 v[72:75], v115 offset:7504
	s_waitcnt lgkmcnt(5)
	v_pk_fma_f32 v[20:21], v[80:81], v[14:15], v[20:21] neg_lo:[1,0,0] neg_hi:[1,0,0]
	v_pk_fma_f32 v[22:23], v[84:85], v[14:15], v[22:23] neg_lo:[1,0,0] neg_hi:[1,0,0]
	v_pk_fma_f32 v[20:21], v[82:83], v[16:17], v[20:21] neg_lo:[1,0,0] neg_hi:[1,0,0]
	v_pk_fma_f32 v[22:23], v[86:87], v[16:17], v[22:23] neg_lo:[1,0,0] neg_hi:[1,0,0]
	ds_read_b128 v[76:79], v115 offset:7776
	ds_read_b128 v[80:83], v115 offset:7520
	s_waitcnt lgkmcnt(5)
	v_pk_fma_f32 v[20:21], v[88:89], v[18:19], v[20:21] neg_lo:[1,0,0] neg_hi:[1,0,0]
	v_pk_fma_f32 v[22:23], v[92:93], v[18:19], v[22:23] neg_lo:[1,0,0] neg_hi:[1,0,0]
	ds_read_b128 v[84:87], v115 offset:7792
	ds_read_b128 v[88:91], v115 offset:7536
	v_add_f32_e32 v20, v20, v21
	v_add_f32_e32 v22, v22, v23
	v_fma_f32 v21, -v94, v20, v22
	v_cmp_eq_u32_e32 vcc, 20, v127
	v_mov_b32_e32 v23, 0
	v_mov_b32_e32 v25, 0
	v_cndmask_b32_e64 v22, 0, 1.0, vcc
	v_cmp_eq_u32_e32 vcc, 21, v127
	s_nop 1
	v_cndmask_b32_e64 v24, 0, 1.0, vcc
	s_waitcnt lgkmcnt(5)
	v_pk_fma_f32 v[22:23], v[96:97], v[2:3], v[22:23] neg_lo:[1,0,0] neg_hi:[1,0,0]
	v_pk_fma_f32 v[24:25], v[68:69], v[2:3], v[24:25] neg_lo:[1,0,0] neg_hi:[1,0,0]
	v_pk_fma_f32 v[22:23], v[98:99], v[4:5], v[22:23] neg_lo:[1,0,0] neg_hi:[1,0,0]
	v_pk_fma_f32 v[24:25], v[70:71], v[4:5], v[24:25] neg_lo:[1,0,0] neg_hi:[1,0,0]
	ds_read_b128 v[92:95], v115 offset:7808
	ds_read_b128 v[96:99], v115 offset:7552
	s_waitcnt lgkmcnt(5)
	v_pk_fma_f32 v[22:23], v[72:73], v[6:7], v[22:23] neg_lo:[1,0,0] neg_hi:[1,0,0]
	v_pk_fma_f32 v[24:25], v[76:77], v[6:7], v[24:25] neg_lo:[1,0,0] neg_hi:[1,0,0]
	v_pk_fma_f32 v[22:23], v[74:75], v[8:9], v[22:23] neg_lo:[1,0,0] neg_hi:[1,0,0]
	v_pk_fma_f32 v[24:25], v[78:79], v[8:9], v[24:25] neg_lo:[1,0,0] neg_hi:[1,0,0]
	ds_read_b128 v[68:71], v115 offset:7824
	ds_read_b32 v72, v115 offset:7840
	s_waitcnt lgkmcnt(5)
	v_pk_fma_f32 v[22:23], v[80:81], v[10:11], v[22:23] neg_lo:[1,0,0] neg_hi:[1,0,0]
	v_pk_fma_f32 v[24:25], v[84:85], v[10:11], v[24:25] neg_lo:[1,0,0] neg_hi:[1,0,0]
	v_pk_fma_f32 v[22:23], v[82:83], v[12:13], v[22:23] neg_lo:[1,0,0] neg_hi:[1,0,0]
	v_pk_fma_f32 v[24:25], v[86:87], v[12:13], v[24:25] neg_lo:[1,0,0] neg_hi:[1,0,0]
	ds_read_b128 v[76:79], v115 offset:8032
	ds_read_b128 v[80:83], v115 offset:8304
	s_waitcnt lgkmcnt(5)
	v_pk_fma_f32 v[22:23], v[88:89], v[14:15], v[22:23] neg_lo:[1,0,0] neg_hi:[1,0,0]
	v_pk_fma_f32 v[24:25], v[92:93], v[14:15], v[24:25] neg_lo:[1,0,0] neg_hi:[1,0,0]
	v_pk_fma_f32 v[22:23], v[90:91], v[16:17], v[22:23] neg_lo:[1,0,0] neg_hi:[1,0,0]
	v_pk_fma_f32 v[24:25], v[94:95], v[16:17], v[24:25] neg_lo:[1,0,0] neg_hi:[1,0,0]
	ds_read_b128 v[84:87], v115 offset:8048
	ds_read_b128 v[88:91], v115 offset:8320
	s_waitcnt lgkmcnt(5)
	v_pk_fma_f32 v[22:23], v[96:97], v[18:19], v[22:23] neg_lo:[1,0,0] neg_hi:[1,0,0]
	v_pk_fma_f32 v[24:25], v[68:69], v[18:19], v[24:25] neg_lo:[1,0,0] neg_hi:[1,0,0]
	v_pk_fma_f32 v[22:23], v[98:99], v[20:21], v[22:23] neg_lo:[1,0,0] neg_hi:[1,0,0]
	v_pk_fma_f32 v[24:25], v[70:71], v[20:21], v[24:25] neg_lo:[1,0,0] neg_hi:[1,0,0]
	ds_read_b128 v[92:95], v115 offset:8064
	ds_read_b128 v[96:99], v115 offset:8336
	s_waitcnt lgkmcnt(6)
	ds_read_b128 v[68:71], v115 offset:8080
	v_add_f32_e32 v22, v22, v23
	v_add_f32_e32 v24, v24, v25
	v_fma_f32 v23, -v72, v22, v24
	v_cmp_eq_u32_e32 vcc, 22, v127
	v_mov_b32_e32 v25, 0
	v_mov_b32_e32 v27, 0
	v_cndmask_b32_e64 v24, 0, 1.0, vcc
	v_cmp_eq_u32_e32 vcc, 23, v127
	s_nop 1
	v_cndmask_b32_e64 v26, 0, 1.0, vcc
	s_waitcnt lgkmcnt(5)
	v_pk_fma_f32 v[24:25], v[76:77], v[2:3], v[24:25] neg_lo:[1,0,0] neg_hi:[1,0,0]
	v_pk_fma_f32 v[26:27], v[80:81], v[2:3], v[26:27] neg_lo:[1,0,0] neg_hi:[1,0,0]
	v_pk_fma_f32 v[24:25], v[78:79], v[4:5], v[24:25] neg_lo:[1,0,0] neg_hi:[1,0,0]
	v_pk_fma_f32 v[26:27], v[82:83], v[4:5], v[26:27] neg_lo:[1,0,0] neg_hi:[1,0,0]
	ds_read_b128 v[72:75], v115 offset:8352
	ds_read_b128 v[76:79], v115 offset:8096
	s_waitcnt lgkmcnt(5)
	v_pk_fma_f32 v[24:25], v[84:85], v[6:7], v[24:25] neg_lo:[1,0,0] neg_hi:[1,0,0]
	v_pk_fma_f32 v[26:27], v[88:89], v[6:7], v[26:27] neg_lo:[1,0,0] neg_hi:[1,0,0]
	v_pk_fma_f32 v[24:25], v[86:87], v[8:9], v[24:25] neg_lo:[1,0,0] neg_hi:[1,0,0]
	v_pk_fma_f32 v[26:27], v[90:91], v[8:9], v[26:27] neg_lo:[1,0,0] neg_hi:[1,0,0]
	ds_read_b128 v[80:83], v115 offset:8368
	ds_read_b128 v[84:87], v115 offset:8112
	s_waitcnt lgkmcnt(5)
; __device__ __forceinline__ void gdn_chunk_prep(Frame& F) {
;     ...
;             for (int i = 0; i < 50; i += 2) {
;                 float a = (i == lane) ? 1.f : 0.f, bq = (i + 1 == lane) ? 1.f : 0.f;
; #pragma unroll
;                 for (int j = 0; j < i; ++j) { a = fmaf(-Amat[i * 68 + j], T[j], a); bq = fmaf(-Amat[(i + 1) * 68 + j], T[j], bq); }
;                 T[i] = a;
;                 T[i + 1] = fmaf(-Amat[(i + 1) * 68 + i], a, bq);
;                 asm volatile("" ::: "memory");
;             }
	v_pk_fma_f32 v[24:25], v[92:93], v[10:11], v[24:25] neg_lo:[1,0,0] neg_hi:[1,0,0]
	v_pk_fma_f32 v[26:27], v[96:97], v[10:11], v[26:27] neg_lo:[1,0,0] neg_hi:[1,0,0]
	v_pk_fma_f32 v[24:25], v[94:95], v[12:13], v[24:25] neg_lo:[1,0,0] neg_hi:[1,0,0]
	v_pk_fma_f32 v[26:27], v[98:99], v[12:13], v[26:27] neg_lo:[1,0,0] neg_hi:[1,0,0]
	ds_read_b128 v[88:91], v115 offset:8384
	ds_read_b128 v[92:95], v115 offset:8576
	s_waitcnt lgkmcnt(5)
	v_pk_fma_f32 v[24:25], v[68:69], v[14:15], v[24:25] neg_lo:[1,0,0] neg_hi:[1,0,0]
	v_pk_fma_f32 v[26:27], v[72:73], v[14:15], v[26:27] neg_lo:[1,0,0] neg_hi:[1,0,0]
	v_pk_fma_f32 v[24:25], v[70:71], v[16:17], v[24:25] neg_lo:[1,0,0] neg_hi:[1,0,0]
	v_pk_fma_f32 v[26:27], v[74:75], v[16:17], v[26:27] neg_lo:[1,0,0] neg_hi:[1,0,0]
	ds_read_b128 v[96:99], v115 offset:8848
	ds_read_b128 v[68:71], v115 offset:8592
	s_waitcnt lgkmcnt(5)
	v_pk_fma_f32 v[24:25], v[76:77], v[18:19], v[24:25] neg_lo:[1,0,0] neg_hi:[1,0,0]
	v_pk_fma_f32 v[26:27], v[80:81], v[18:19], v[26:27] neg_lo:[1,0,0] neg_hi:[1,0,0]
	v_pk_fma_f32 v[24:25], v[78:79], v[20:21], v[24:25] neg_lo:[1,0,0] neg_hi:[1,0,0]
	v_pk_fma_f32 v[26:27], v[82:83], v[20:21], v[26:27] neg_lo:[1,0,0] neg_hi:[1,0,0]
	ds_read_b128 v[72:75], v115 offset:8864
	ds_read_b128 v[76:79], v115 offset:8608
	s_waitcnt lgkmcnt(5)
	v_pk_fma_f32 v[24:25], v[84:85], v[22:23], v[24:25] neg_lo:[1,0,0] neg_hi:[1,0,0]
	v_pk_fma_f32 v[26:27], v[88:89], v[22:23], v[26:27] neg_lo:[1,0,0] neg_hi:[1,0,0]
	ds_read_b128 v[80:83], v115 offset:8880
	ds_read_b128 v[84:87], v115 offset:8624
	v_add_f32_e32 v24, v24, v25
	v_add_f32_e32 v26, v26, v27
	v_fma_f32 v25, -v90, v24, v26
	v_cmp_eq_u32_e32 vcc, 24, v127
	v_mov_b32_e32 v27, 0
	v_mov_b32_e32 v29, 0
	v_cndmask_b32_e64 v26, 0, 1.0, vcc
	v_cmp_eq_u32_e32 vcc, 25, v127
	s_nop 1
	v_cndmask_b32_e64 v28, 0, 1.0, vcc
	s_waitcnt lgkmcnt(5)
	v_pk_fma_f32 v[26:27], v[92:93], v[2:3], v[26:27] neg_lo:[1,0,0] neg_hi:[1,0,0]
	v_pk_fma_f32 v[28:29], v[96:97], v[2:3], v[28:29] neg_lo:[1,0,0] neg_hi:[1,0,0]
	v_pk_fma_f32 v[26:27], v[94:95], v[4:5], v[26:27] neg_lo:[1,0,0] neg_hi:[1,0,0]
	v_pk_fma_f32 v[28:29], v[98:99], v[4:5], v[28:29] neg_lo:[1,0,0] neg_hi:[1,0,0]
	ds_read_b128 v[88:91], v115 offset:8896
	ds_read_b128 v[92:95], v115 offset:8640
	s_waitcnt lgkmcnt(5)
	v_pk_fma_f32 v[26:27], v[68:69], v[6:7], v[26:27] neg_lo:[1,0,0] neg_hi:[1,0,0]
	v_pk_fma_f32 v[28:29], v[72:73], v[6:7], v[28:29] neg_lo:[1,0,0] neg_hi:[1,0,0]
	v_pk_fma_f32 v[26:27], v[70:71], v[8:9], v[26:27] neg_lo:[1,0,0] neg_hi:[1,0,0]
	v_pk_fma_f32 v[28:29], v[74:75], v[8:9], v[28:29] neg_lo:[1,0,0] neg_hi:[1,0,0]
	ds_read_b128 v[96:99], v115 offset:8912
	ds_read_b128 v[68:71], v115 offset:8656
	s_waitcnt lgkmcnt(5)
	v_pk_fma_f32 v[26:27], v[76:77], v[10:11], v[26:27] neg_lo:[1,0,0] neg_hi:[1,0,0]
	v_pk_fma_f32 v[28:29], v[80:81], v[10:11], v[28:29] neg_lo:[1,0,0] neg_hi:[1,0,0]
	v_pk_fma_f32 v[26:27], v[78:79], v[12:13], v[26:27] neg_lo:[1,0,0] neg_hi:[1,0,0]
	v_pk_fma_f32 v[28:29], v[82:83], v[12:13], v[28:29] neg_lo:[1,0,0] neg_hi:[1,0,0]
	ds_read_b128 v[72:75], v115 offset:8928
	ds_read_b32 v76, v115 offset:8944
	s_waitcnt lgkmcnt(5)
	v_pk_fma_f32 v[26:27], v[84:85], v[14:15], v[26:27] neg_lo:[1,0,0] neg_hi:[1,0,0]
	v_pk_fma_f32 v[28:29], v[88:89], v[14:15], v[28:29] neg_lo:[1,0,0] neg_hi:[1,0,0]
	v_pk_fma_f32 v[26:27], v[86:87], v[16:17], v[26:27] neg_lo:[1,0,0] neg_hi:[1,0,0]
	v_pk_fma_f32 v[28:29], v[90:91], v[16:17], v[28:29] neg_lo:[1,0,0] neg_hi:[1,0,0]
	ds_read_b128 v[80:83], v115 offset:9120
	ds_read_b128 v[84:87], v115 offset:9392
	s_waitcnt lgkmcnt(5)
	v_pk_fma_f32 v[26:27], v[92:93], v[18:19], v[26:27] neg_lo:[1,0,0] neg_hi:[1,0,0]
	v_pk_fma_f32 v[28:29], v[96:97], v[18:19], v[28:29] neg_lo:[1,0,0] neg_hi:[1,0,0]
	v_pk_fma_f32 v[26:27], v[94:95], v[20:21], v[26:27] neg_lo:[1,0,0] neg_hi:[1,0,0]
	v_pk_fma_f32 v[28:29], v[98:99], v[20:21], v[28:29] neg_lo:[1,0,0] neg_hi:[1,0,0]
	ds_read_b128 v[88:91], v115 offset:9136
	ds_read_b128 v[92:95], v115 offset:9408
	s_waitcnt lgkmcnt(5)
	v_pk_fma_f32 v[26:27], v[68:69], v[22:23], v[26:27] neg_lo:[1,0,0] neg_hi:[1,0,0]
	v_pk_fma_f32 v[28:29], v[72:73], v[22:23], v[28:29] neg_lo:[1,0,0] neg_hi:[1,0,0]
	v_pk_fma_f32 v[26:27], v[70:71], v[24:25], v[26:27] neg_lo:[1,0,0] neg_hi:[1,0,0]
	v_pk_fma_f32 v[28:29], v[74:75], v[24:25], v[28:29] neg_lo:[1,0,0] neg_hi:[1,0,0]
	ds_read_b128 v[96:99], v115 offset:9152
	ds_read_b128 v[68:71], v115 offset:9424
	s_waitcnt lgkmcnt(6)
	ds_read_b128 v[72:75], v115 offset:9168
	v_add_f32_e32 v26, v26, v27
	v_add_f32_e32 v28, v28, v29
	v_fma_f32 v27, -v76, v26, v28
	v_cmp_eq_u32_e32 vcc, 26, v127
	v_mov_b32_e32 v29, 0
	v_mov_b32_e32 v31, 0
	v_cndmask_b32_e64 v28, 0, 1.0, vcc
	v_cmp_eq_u32_e32 vcc, 27, v127
	s_nop 1
	v_cndmask_b32_e64 v30, 0, 1.0, vcc
	s_waitcnt lgkmcnt(5)
	v_pk_fma_f32 v[28:29], v[80:81], v[2:3], v[28:29] neg_lo:[1,0,0] neg_hi:[1,0,0]
	v_pk_fma_f32 v[30:31], v[84:85], v[2:3], v[30:31] neg_lo:[1,0,0] neg_hi:[1,0,0]
	v_pk_fma_f32 v[28:29], v[82:83], v[4:5], v[28:29] neg_lo:[1,0,0] neg_hi:[1,0,0]
	v_pk_fma_f32 v[30:31], v[86:87], v[4:5], v[30:31] neg_lo:[1,0,0] neg_hi:[1,0,0]
	ds_read_b128 v[76:79], v115 offset:9440
	ds_read_b128 v[80:83], v115 offset:9184
	s_waitcnt lgkmcnt(5)
	v_pk_fma_f32 v[28:29], v[88:89], v[6:7], v[28:29] neg_lo:[1,0,0] neg_hi:[1,0,0]
	v_pk_fma_f32 v[30:31], v[92:93], v[6:7], v[30:31] neg_lo:[1,0,0] neg_hi:[1,0,0]
	v_pk_fma_f32 v[28:29], v[90:91], v[8:9], v[28:29] neg_lo:[1,0,0] neg_hi:[1,0,0]
	v_pk_fma_f32 v[30:31], v[94:95], v[8:9], v[30:31] neg_lo:[1,0,0] neg_hi:[1,0,0]
	ds_read_b128 v[84:87], v115 offset:9456
	ds_read_b128 v[88:91], v115 offset:9200
	s_waitcnt lgkmcnt(5)
; __device__ __forceinline__ void gdn_chunk_prep(Frame& F) {
;     ...
;             for (int i = 0; i < 50; i += 2) {
;                 float a = (i == lane) ? 1.f : 0.f, bq = (i + 1 == lane) ? 1.f : 0.f;
; #pragma unroll
;                 for (int j = 0; j < i; ++j) { a = fmaf(-Amat[i * 68 + j], T[j], a); bq = fmaf(-Amat[(i + 1) * 68 + j], T[j], bq); }
;                 T[i] = a;
;                 T[i + 1] = fmaf(-Amat[(i + 1) * 68 + i], a, bq);
;                 asm volatile("" ::: "memory");
;             }
	v_pk_fma_f32 v[28:29], v[96:97], v[10:11], v[28:29] neg_lo:[1,0,0] neg_hi:[1,0,0]
	v_pk_fma_f32 v[30:31], v[68:69], v[10:11], v[30:31] neg_lo:[1,0,0] neg_hi:[1,0,0]
	v_pk_fma_f32 v[28:29], v[98:99], v[12:13], v[28:29] neg_lo:[1,0,0] neg_hi:[1,0,0]
	v_pk_fma_f32 v[30:31], v[70:71], v[12:13], v[30:31] neg_lo:[1,0,0] neg_hi:[1,0,0]
	ds_read_b128 v[92:95], v115 offset:9472
	ds_read_b128 v[96:99], v115 offset:9216
	s_waitcnt lgkmcnt(5)
	v_pk_fma_f32 v[28:29], v[72:73], v[14:15], v[28:29] neg_lo:[1,0,0] neg_hi:[1,0,0]
	v_pk_fma_f32 v[30:31], v[76:77], v[14:15], v[30:31] neg_lo:[1,0,0] neg_hi:[1,0,0]
	v_pk_fma_f32 v[28:29], v[74:75], v[16:17], v[28:29] neg_lo:[1,0,0] neg_hi:[1,0,0]
	v_pk_fma_f32 v[30:31], v[78:79], v[16:17], v[30:31] neg_lo:[1,0,0] neg_hi:[1,0,0]
	ds_read_b128 v[68:71], v115 offset:9488
	ds_read_b128 v[72:75], v115 offset:9664
	s_waitcnt lgkmcnt(5)
	v_pk_fma_f32 v[28:29], v[80:81], v[18:19], v[28:29] neg_lo:[1,0,0] neg_hi:[1,0,0]
	v_pk_fma_f32 v[30:31], v[84:85], v[18:19], v[30:31] neg_lo:[1,0,0] neg_hi:[1,0,0]
	v_pk_fma_f32 v[28:29], v[82:83], v[20:21], v[28:29] neg_lo:[1,0,0] neg_hi:[1,0,0]
	v_pk_fma_f32 v[30:31], v[86:87], v[20:21], v[30:31] neg_lo:[1,0,0] neg_hi:[1,0,0]
	ds_read_b128 v[76:79], v115 offset:9936
	ds_read_b128 v[80:83], v115 offset:9680
	s_waitcnt lgkmcnt(5)
	v_pk_fma_f32 v[28:29], v[88:89], v[22:23], v[28:29] neg_lo:[1,0,0] neg_hi:[1,0,0]
	v_pk_fma_f32 v[30:31], v[92:93], v[22:23], v[30:31] neg_lo:[1,0,0] neg_hi:[1,0,0]
	v_pk_fma_f32 v[28:29], v[90:91], v[24:25], v[28:29] neg_lo:[1,0,0] neg_hi:[1,0,0]
	v_pk_fma_f32 v[30:31], v[94:95], v[24:25], v[30:31] neg_lo:[1,0,0] neg_hi:[1,0,0]
	ds_read_b128 v[84:87], v115 offset:9952
	ds_read_b128 v[88:91], v115 offset:9696
	s_waitcnt lgkmcnt(5)
	v_pk_fma_f32 v[28:29], v[96:97], v[26:27], v[28:29] neg_lo:[1,0,0] neg_hi:[1,0,0]
	v_pk_fma_f32 v[30:31], v[68:69], v[26:27], v[30:31] neg_lo:[1,0,0] neg_hi:[1,0,0]
	ds_read_b128 v[92:95], v115 offset:9968
	ds_read_b128 v[96:99], v115 offset:9712
	v_add_f32_e32 v28, v28, v29
	v_add_f32_e32 v30, v30, v31
	v_fma_f32 v29, -v70, v28, v30
	v_cmp_eq_u32_e32 vcc, 28, v127
	v_mov_b32_e32 v31, 0
	v_mov_b32_e32 v33, 0
	v_cndmask_b32_e64 v30, 0, 1.0, vcc
	v_cmp_eq_u32_e32 vcc, 29, v127
	s_nop 1
	v_cndmask_b32_e64 v32, 0, 1.0, vcc
	s_waitcnt lgkmcnt(5)
	v_pk_fma_f32 v[30:31], v[72:73], v[2:3], v[30:31] neg_lo:[1,0,0] neg_hi:[1,0,0]
	v_pk_fma_f32 v[32:33], v[76:77], v[2:3], v[32:33] neg_lo:[1,0,0] neg_hi:[1,0,0]
	v_pk_fma_f32 v[30:31], v[74:75], v[4:5], v[30:31] neg_lo:[1,0,0] neg_hi:[1,0,0]
	v_pk_fma_f32 v[32:33], v[78:79], v[4:5], v[32:33] neg_lo:[1,0,0] neg_hi:[1,0,0]
	ds_read_b128 v[68:71], v115 offset:9984
	ds_read_b128 v[72:75], v115 offset:9728
	s_waitcnt lgkmcnt(5)
	v_pk_fma_f32 v[30:31], v[80:81], v[6:7], v[30:31] neg_lo:[1,0,0] neg_hi:[1,0,0]
	v_pk_fma_f32 v[32:33], v[84:85], v[6:7], v[32:33] neg_lo:[1,0,0] neg_hi:[1,0,0]
	v_pk_fma_f32 v[30:31], v[82:83], v[8:9], v[30:31] neg_lo:[1,0,0] neg_hi:[1,0,0]
	v_pk_fma_f32 v[32:33], v[86:87], v[8:9], v[32:33] neg_lo:[1,0,0] neg_hi:[1,0,0]
	ds_read_b128 v[76:79], v115 offset:10000
	ds_read_b128 v[80:83], v115 offset:9744
	s_waitcnt lgkmcnt(5)
	v_pk_fma_f32 v[30:31], v[88:89], v[10:11], v[30:31] neg_lo:[1,0,0] neg_hi:[1,0,0]
	v_pk_fma_f32 v[32:33], v[92:93], v[10:11], v[32:33] neg_lo:[1,0,0] neg_hi:[1,0,0]
	v_pk_fma_f32 v[30:31], v[90:91], v[12:13], v[30:31] neg_lo:[1,0,0] neg_hi:[1,0,0]
	v_pk_fma_f32 v[32:33], v[94:95], v[12:13], v[32:33] neg_lo:[1,0,0] neg_hi:[1,0,0]
	ds_read_b128 v[84:87], v115 offset:10016
	ds_read_b128 v[88:91], v115 offset:9760
	s_waitcnt lgkmcnt(5)
	v_pk_fma_f32 v[30:31], v[96:97], v[14:15], v[30:31] neg_lo:[1,0,0] neg_hi:[1,0,0]
	v_pk_fma_f32 v[32:33], v[68:69], v[14:15], v[32:33] neg_lo:[1,0,0] neg_hi:[1,0,0]
	v_pk_fma_f32 v[30:31], v[98:99], v[16:17], v[30:31] neg_lo:[1,0,0] neg_hi:[1,0,0]
	v_pk_fma_f32 v[32:33], v[70:71], v[16:17], v[32:33] neg_lo:[1,0,0] neg_hi:[1,0,0]
	ds_read_b128 v[92:95], v115 offset:10032
	ds_read_b32 v96, v115 offset:10048
	s_waitcnt lgkmcnt(5)
	v_pk_fma_f32 v[30:31], v[72:73], v[18:19], v[30:31] neg_lo:[1,0,0] neg_hi:[1,0,0]
	v_pk_fma_f32 v[32:33], v[76:77], v[18:19], v[32:33] neg_lo:[1,0,0] neg_hi:[1,0,0]
	v_pk_fma_f32 v[30:31], v[74:75], v[20:21], v[30:31] neg_lo:[1,0,0] neg_hi:[1,0,0]
	v_pk_fma_f32 v[32:33], v[78:79], v[20:21], v[32:33] neg_lo:[1,0,0] neg_hi:[1,0,0]
	ds_read_b128 v[68:71], v115 offset:10208
	ds_read_b128 v[72:75], v115 offset:10480
	s_waitcnt lgkmcnt(5)
	v_pk_fma_f32 v[30:31], v[80:81], v[22:23], v[30:31] neg_lo:[1,0,0] neg_hi:[1,0,0]
	v_pk_fma_f32 v[32:33], v[84:85], v[22:23], v[32:33] neg_lo:[1,0,0] neg_hi:[1,0,0]
	v_pk_fma_f32 v[30:31], v[82:83], v[24:25], v[30:31] neg_lo:[1,0,0] neg_hi:[1,0,0]
	v_pk_fma_f32 v[32:33], v[86:87], v[24:25], v[32:33] neg_lo:[1,0,0] neg_hi:[1,0,0]
	ds_read_b128 v[76:79], v115 offset:10224
	ds_read_b128 v[80:83], v115 offset:10496
	s_waitcnt lgkmcnt(5)
	v_pk_fma_f32 v[30:31], v[88:89], v[26:27], v[30:31] neg_lo:[1,0,0] neg_hi:[1,0,0]
	v_pk_fma_f32 v[32:33], v[92:93], v[26:27], v[32:33] neg_lo:[1,0,0] neg_hi:[1,0,0]
	v_pk_fma_f32 v[30:31], v[90:91], v[28:29], v[30:31] neg_lo:[1,0,0] neg_hi:[1,0,0]
	v_pk_fma_f32 v[32:33], v[94:95], v[28:29], v[32:33] neg_lo:[1,0,0] neg_hi:[1,0,0]
	ds_read_b128 v[84:87], v115 offset:10240
	ds_read_b128 v[88:91], v115 offset:10512
	s_waitcnt lgkmcnt(6)
	ds_read_b128 v[92:95], v115 offset:10256
	v_add_f32_e32 v30, v30, v31
	v_add_f32_e32 v32, v32, v33
	v_fma_f32 v31, -v96, v30, v32
	v_cmp_eq_u32_e32 vcc, 30, v127
	v_mov_b32_e32 v33, 0
	v_mov_b32_e32 v35, 0
	v_cndmask_b32_e64 v32, 0, 1.0, vcc
	v_cmp_eq_u32_e32 vcc, 31, v127
	s_nop 1
	v_cndmask_b32_e64 v34, 0, 1.0, vcc
	s_waitcnt lgkmcnt(5)
; __device__ __forceinline__ void gdn_chunk_prep(Frame& F) {
;     ...
;             for (int i = 0; i < 50; i += 2) {
;                 float a = (i == lane) ? 1.f : 0.f, bq = (i + 1 == lane) ? 1.f : 0.f;
; #pragma unroll
;                 for (int j = 0; j < i; ++j) { a = fmaf(-Amat[i * 68 + j], T[j], a); bq = fmaf(-Amat[(i + 1) * 68 + j], T[j], bq); }
;                 T[i] = a;
;                 T[i + 1] = fmaf(-Amat[(i + 1) * 68 + i], a, bq);
;                 asm volatile("" ::: "memory");
;             }
	v_pk_fma_f32 v[32:33], v[68:69], v[2:3], v[32:33] neg_lo:[1,0,0] neg_hi:[1,0,0]
	v_pk_fma_f32 v[34:35], v[72:73], v[2:3], v[34:35] neg_lo:[1,0,0] neg_hi:[1,0,0]
	v_pk_fma_f32 v[32:33], v[70:71], v[4:5], v[32:33] neg_lo:[1,0,0] neg_hi:[1,0,0]
	v_pk_fma_f32 v[34:35], v[74:75], v[4:5], v[34:35] neg_lo:[1,0,0] neg_hi:[1,0,0]
	ds_read_b128 v[96:99], v115 offset:10528
	ds_read_b128 v[68:71], v115 offset:10272
	s_waitcnt lgkmcnt(5)
	v_pk_fma_f32 v[32:33], v[76:77], v[6:7], v[32:33] neg_lo:[1,0,0] neg_hi:[1,0,0]
	v_pk_fma_f32 v[34:35], v[80:81], v[6:7], v[34:35] neg_lo:[1,0,0] neg_hi:[1,0,0]
	v_pk_fma_f32 v[32:33], v[78:79], v[8:9], v[32:33] neg_lo:[1,0,0] neg_hi:[1,0,0]
	v_pk_fma_f32 v[34:35], v[82:83], v[8:9], v[34:35] neg_lo:[1,0,0] neg_hi:[1,0,0]
	ds_read_b128 v[72:75], v115 offset:10544
	ds_read_b128 v[76:79], v115 offset:10288
	s_waitcnt lgkmcnt(5)
	v_pk_fma_f32 v[32:33], v[84:85], v[10:11], v[32:33] neg_lo:[1,0,0] neg_hi:[1,0,0]
	v_pk_fma_f32 v[34:35], v[88:89], v[10:11], v[34:35] neg_lo:[1,0,0] neg_hi:[1,0,0]
	v_pk_fma_f32 v[32:33], v[86:87], v[12:13], v[32:33] neg_lo:[1,0,0] neg_hi:[1,0,0]
	v_pk_fma_f32 v[34:35], v[90:91], v[12:13], v[34:35] neg_lo:[1,0,0] neg_hi:[1,0,0]
	ds_read_b128 v[80:83], v115 offset:10560
	ds_read_b128 v[84:87], v115 offset:10304
	s_waitcnt lgkmcnt(5)
	v_pk_fma_f32 v[32:33], v[92:93], v[14:15], v[32:33] neg_lo:[1,0,0] neg_hi:[1,0,0]
	v_pk_fma_f32 v[34:35], v[96:97], v[14:15], v[34:35] neg_lo:[1,0,0] neg_hi:[1,0,0]
	v_pk_fma_f32 v[32:33], v[94:95], v[16:17], v[32:33] neg_lo:[1,0,0] neg_hi:[1,0,0]
	v_pk_fma_f32 v[34:35], v[98:99], v[16:17], v[34:35] neg_lo:[1,0,0] neg_hi:[1,0,0]
	ds_read_b128 v[88:91], v115 offset:10576
	ds_read_b128 v[92:95], v115 offset:10320
	s_waitcnt lgkmcnt(5)
	v_pk_fma_f32 v[32:33], v[68:69], v[18:19], v[32:33] neg_lo:[1,0,0] neg_hi:[1,0,0]
	v_pk_fma_f32 v[34:35], v[72:73], v[18:19], v[34:35] neg_lo:[1,0,0] neg_hi:[1,0,0]
	v_pk_fma_f32 v[32:33], v[70:71], v[20:21], v[32:33] neg_lo:[1,0,0] neg_hi:[1,0,0]
	v_pk_fma_f32 v[34:35], v[74:75], v[20:21], v[34:35] neg_lo:[1,0,0] neg_hi:[1,0,0]
	ds_read_b128 v[96:99], v115 offset:10592
	ds_read_b128 v[68:71], v115 offset:10752
	s_waitcnt lgkmcnt(5)
	v_pk_fma_f32 v[32:33], v[76:77], v[22:23], v[32:33] neg_lo:[1,0,0] neg_hi:[1,0,0]
	v_pk_fma_f32 v[34:35], v[80:81], v[22:23], v[34:35] neg_lo:[1,0,0] neg_hi:[1,0,0]
	v_pk_fma_f32 v[32:33], v[78:79], v[24:25], v[32:33] neg_lo:[1,0,0] neg_hi:[1,0,0]
	v_pk_fma_f32 v[34:35], v[82:83], v[24:25], v[34:35] neg_lo:[1,0,0] neg_hi:[1,0,0]
	ds_read_b128 v[72:75], v115 offset:11024
	ds_read_b128 v[76:79], v115 offset:10768
	s_waitcnt lgkmcnt(5)
	v_pk_fma_f32 v[32:33], v[84:85], v[26:27], v[32:33] neg_lo:[1,0,0] neg_hi:[1,0,0]
	v_pk_fma_f32 v[34:35], v[88:89], v[26:27], v[34:35] neg_lo:[1,0,0] neg_hi:[1,0,0]
	v_pk_fma_f32 v[32:33], v[86:87], v[28:29], v[32:33] neg_lo:[1,0,0] neg_hi:[1,0,0]
	v_pk_fma_f32 v[34:35], v[90:91], v[28:29], v[34:35] neg_lo:[1,0,0] neg_hi:[1,0,0]
	ds_read_b128 v[80:83], v115 offset:11040
	ds_read_b128 v[84:87], v115 offset:10784
	s_waitcnt lgkmcnt(5)
	v_pk_fma_f32 v[32:33], v[92:93], v[30:31], v[32:33] neg_lo:[1,0,0] neg_hi:[1,0,0]
	v_pk_fma_f32 v[34:35], v[96:97], v[30:31], v[34:35] neg_lo:[1,0,0] neg_hi:[1,0,0]
	ds_read_b128 v[88:91], v115 offset:11056
	ds_read_b128 v[92:95], v115 offset:10800
	v_add_f32_e32 v32, v32, v33
	v_add_f32_e32 v34, v34, v35
	v_fma_f32 v33, -v98, v32, v34
	v_cmp_eq_u32_e32 vcc, 32, v127
	v_mov_b32_e32 v35, 0
	v_mov_b32_e32 v37, 0
	v_cndmask_b32_e64 v34, 0, 1.0, vcc
	v_cmp_eq_u32_e32 vcc, 33, v127
	s_nop 1
	v_cndmask_b32_e64 v36, 0, 1.0, vcc
	s_waitcnt lgkmcnt(5)
	v_pk_fma_f32 v[34:35], v[68:69], v[2:3], v[34:35] neg_lo:[1,0,0] neg_hi:[1,0,0]
	v_pk_fma_f32 v[36:37], v[72:73], v[2:3], v[36:37] neg_lo:[1,0,0] neg_hi:[1,0,0]
	v_pk_fma_f32 v[34:35], v[70:71], v[4:5], v[34:35] neg_lo:[1,0,0] neg_hi:[1,0,0]
	v_pk_fma_f32 v[36:37], v[74:75], v[4:5], v[36:37] neg_lo:[1,0,0] neg_hi:[1,0,0]
	ds_read_b128 v[96:99], v115 offset:11072
	ds_read_b128 v[68:71], v115 offset:10816
	s_waitcnt lgkmcnt(5)
	v_pk_fma_f32 v[34:35], v[76:77], v[6:7], v[34:35] neg_lo:[1,0,0] neg_hi:[1,0,0]
	v_pk_fma_f32 v[36:37], v[80:81], v[6:7], v[36:37] neg_lo:[1,0,0] neg_hi:[1,0,0]
	v_pk_fma_f32 v[34:35], v[78:79], v[8:9], v[34:35] neg_lo:[1,0,0] neg_hi:[1,0,0]
	v_pk_fma_f32 v[36:37], v[82:83], v[8:9], v[36:37] neg_lo:[1,0,0] neg_hi:[1,0,0]
	ds_read_b128 v[72:75], v115 offset:11088
	ds_read_b128 v[76:79], v115 offset:10832
	s_waitcnt lgkmcnt(5)
	v_pk_fma_f32 v[34:35], v[84:85], v[10:11], v[34:35] neg_lo:[1,0,0] neg_hi:[1,0,0]
	v_pk_fma_f32 v[36:37], v[88:89], v[10:11], v[36:37] neg_lo:[1,0,0] neg_hi:[1,0,0]
	v_pk_fma_f32 v[34:35], v[86:87], v[12:13], v[34:35] neg_lo:[1,0,0] neg_hi:[1,0,0]
	v_pk_fma_f32 v[36:37], v[90:91], v[12:13], v[36:37] neg_lo:[1,0,0] neg_hi:[1,0,0]
	ds_read_b128 v[80:83], v115 offset:11104
	ds_read_b128 v[84:87], v115 offset:10848
	s_waitcnt lgkmcnt(5)
	v_pk_fma_f32 v[34:35], v[92:93], v[14:15], v[34:35] neg_lo:[1,0,0] neg_hi:[1,0,0]
	v_pk_fma_f32 v[36:37], v[96:97], v[14:15], v[36:37] neg_lo:[1,0,0] neg_hi:[1,0,0]
	v_pk_fma_f32 v[34:35], v[94:95], v[16:17], v[34:35] neg_lo:[1,0,0] neg_hi:[1,0,0]
	v_pk_fma_f32 v[36:37], v[98:99], v[16:17], v[36:37] neg_lo:[1,0,0] neg_hi:[1,0,0]
	ds_read_b128 v[88:91], v115 offset:11120
	ds_read_b128 v[92:95], v115 offset:10864
	s_waitcnt lgkmcnt(5)
	v_pk_fma_f32 v[34:35], v[68:69], v[18:19], v[34:35] neg_lo:[1,0,0] neg_hi:[1,0,0]
	v_pk_fma_f32 v[36:37], v[72:73], v[18:19], v[36:37] neg_lo:[1,0,0] neg_hi:[1,0,0]
	v_pk_fma_f32 v[34:35], v[70:71], v[20:21], v[34:35] neg_lo:[1,0,0] neg_hi:[1,0,0]
	v_pk_fma_f32 v[36:37], v[74:75], v[20:21], v[36:37] neg_lo:[1,0,0] neg_hi:[1,0,0]
	ds_read_b128 v[96:99], v115 offset:11136
	ds_read_b32 v68, v115 offset:11152
	s_waitcnt lgkmcnt(5)
; __device__ __forceinline__ void gdn_chunk_prep(Frame& F) {
;     ...
;             for (int i = 0; i < 50; i += 2) {
;                 float a = (i == lane) ? 1.f : 0.f, bq = (i + 1 == lane) ? 1.f : 0.f;
; #pragma unroll
;                 for (int j = 0; j < i; ++j) { a = fmaf(-Amat[i * 68 + j], T[j], a); bq = fmaf(-Amat[(i + 1) * 68 + j], T[j], bq); }
;                 T[i] = a;
;                 T[i + 1] = fmaf(-Amat[(i + 1) * 68 + i], a, bq);
;                 asm volatile("" ::: "memory");
;             }
	v_pk_fma_f32 v[34:35], v[76:77], v[22:23], v[34:35] neg_lo:[1,0,0] neg_hi:[1,0,0]
	v_pk_fma_f32 v[36:37], v[80:81], v[22:23], v[36:37] neg_lo:[1,0,0] neg_hi:[1,0,0]
	v_pk_fma_f32 v[34:35], v[78:79], v[24:25], v[34:35] neg_lo:[1,0,0] neg_hi:[1,0,0]
	v_pk_fma_f32 v[36:37], v[82:83], v[24:25], v[36:37] neg_lo:[1,0,0] neg_hi:[1,0,0]
	ds_read_b128 v[72:75], v115 offset:11296
	ds_read_b128 v[76:79], v115 offset:11568
	s_waitcnt lgkmcnt(5)
	v_pk_fma_f32 v[34:35], v[84:85], v[26:27], v[34:35] neg_lo:[1,0,0] neg_hi:[1,0,0]
	v_pk_fma_f32 v[36:37], v[88:89], v[26:27], v[36:37] neg_lo:[1,0,0] neg_hi:[1,0,0]
	v_pk_fma_f32 v[34:35], v[86:87], v[28:29], v[34:35] neg_lo:[1,0,0] neg_hi:[1,0,0]
	v_pk_fma_f32 v[36:37], v[90:91], v[28:29], v[36:37] neg_lo:[1,0,0] neg_hi:[1,0,0]
	ds_read_b128 v[80:83], v115 offset:11312
	ds_read_b128 v[84:87], v115 offset:11584
	s_waitcnt lgkmcnt(5)
	v_pk_fma_f32 v[34:35], v[92:93], v[30:31], v[34:35] neg_lo:[1,0,0] neg_hi:[1,0,0]
	v_pk_fma_f32 v[36:37], v[96:97], v[30:31], v[36:37] neg_lo:[1,0,0] neg_hi:[1,0,0]
	v_pk_fma_f32 v[34:35], v[94:95], v[32:33], v[34:35] neg_lo:[1,0,0] neg_hi:[1,0,0]
	v_pk_fma_f32 v[36:37], v[98:99], v[32:33], v[36:37] neg_lo:[1,0,0] neg_hi:[1,0,0]
	ds_read_b128 v[88:91], v115 offset:11328
	ds_read_b128 v[92:95], v115 offset:11600
	s_waitcnt lgkmcnt(6)
	ds_read_b128 v[96:99], v115 offset:11344
	v_add_f32_e32 v34, v34, v35
	v_add_f32_e32 v36, v36, v37
	v_fma_f32 v35, -v68, v34, v36
	v_cmp_eq_u32_e32 vcc, 34, v127
	v_mov_b32_e32 v37, 0
	v_mov_b32_e32 v39, 0
	v_cndmask_b32_e64 v36, 0, 1.0, vcc
	v_cmp_eq_u32_e32 vcc, 35, v127
	s_nop 1
	v_cndmask_b32_e64 v38, 0, 1.0, vcc
	s_waitcnt lgkmcnt(5)
	v_pk_fma_f32 v[36:37], v[72:73], v[2:3], v[36:37] neg_lo:[1,0,0] neg_hi:[1,0,0]
	v_pk_fma_f32 v[38:39], v[76:77], v[2:3], v[38:39] neg_lo:[1,0,0] neg_hi:[1,0,0]
	v_pk_fma_f32 v[36:37], v[74:75], v[4:5], v[36:37] neg_lo:[1,0,0] neg_hi:[1,0,0]
	v_pk_fma_f32 v[38:39], v[78:79], v[4:5], v[38:39] neg_lo:[1,0,0] neg_hi:[1,0,0]
	ds_read_b128 v[68:71], v115 offset:11616
	ds_read_b128 v[72:75], v115 offset:11360
	s_waitcnt lgkmcnt(5)
	v_pk_fma_f32 v[36:37], v[80:81], v[6:7], v[36:37] neg_lo:[1,0,0] neg_hi:[1,0,0]
	v_pk_fma_f32 v[38:39], v[84:85], v[6:7], v[38:39] neg_lo:[1,0,0] neg_hi:[1,0,0]
	v_pk_fma_f32 v[36:37], v[82:83], v[8:9], v[36:37] neg_lo:[1,0,0] neg_hi:[1,0,0]
	v_pk_fma_f32 v[38:39], v[86:87], v[8:9], v[38:39] neg_lo:[1,0,0] neg_hi:[1,0,0]
	ds_read_b128 v[76:79], v115 offset:11632
	ds_read_b128 v[80:83], v115 offset:11376
	s_waitcnt lgkmcnt(5)
	v_pk_fma_f32 v[36:37], v[88:89], v[10:11], v[36:37] neg_lo:[1,0,0] neg_hi:[1,0,0]
	v_pk_fma_f32 v[38:39], v[92:93], v[10:11], v[38:39] neg_lo:[1,0,0] neg_hi:[1,0,0]
	v_pk_fma_f32 v[36:37], v[90:91], v[12:13], v[36:37] neg_lo:[1,0,0] neg_hi:[1,0,0]
	v_pk_fma_f32 v[38:39], v[94:95], v[12:13], v[38:39] neg_lo:[1,0,0] neg_hi:[1,0,0]
	ds_read_b128 v[84:87], v115 offset:11648
	ds_read_b128 v[88:91], v115 offset:11392
	s_waitcnt lgkmcnt(5)
	v_pk_fma_f32 v[36:37], v[96:97], v[14:15], v[36:37] neg_lo:[1,0,0] neg_hi:[1,0,0]
	v_pk_fma_f32 v[38:39], v[68:69], v[14:15], v[38:39] neg_lo:[1,0,0] neg_hi:[1,0,0]
	v_pk_fma_f32 v[36:37], v[98:99], v[16:17], v[36:37] neg_lo:[1,0,0] neg_hi:[1,0,0]
	v_pk_fma_f32 v[38:39], v[70:71], v[16:17], v[38:39] neg_lo:[1,0,0] neg_hi:[1,0,0]
	ds_read_b128 v[92:95], v115 offset:11664
	ds_read_b128 v[96:99], v115 offset:11408
	s_waitcnt lgkmcnt(5)
	v_pk_fma_f32 v[36:37], v[72:73], v[18:19], v[36:37] neg_lo:[1,0,0] neg_hi:[1,0,0]
	v_pk_fma_f32 v[38:39], v[76:77], v[18:19], v[38:39] neg_lo:[1,0,0] neg_hi:[1,0,0]
	v_pk_fma_f32 v[36:37], v[74:75], v[20:21], v[36:37] neg_lo:[1,0,0] neg_hi:[1,0,0]
	v_pk_fma_f32 v[38:39], v[78:79], v[20:21], v[38:39] neg_lo:[1,0,0] neg_hi:[1,0,0]
	ds_read_b128 v[68:71], v115 offset:11680
	ds_read_b128 v[72:75], v115 offset:11424
	s_waitcnt lgkmcnt(5)
	v_pk_fma_f32 v[36:37], v[80:81], v[22:23], v[36:37] neg_lo:[1,0,0] neg_hi:[1,0,0]
	v_pk_fma_f32 v[38:39], v[84:85], v[22:23], v[38:39] neg_lo:[1,0,0] neg_hi:[1,0,0]
	v_pk_fma_f32 v[36:37], v[82:83], v[24:25], v[36:37] neg_lo:[1,0,0] neg_hi:[1,0,0]
	v_pk_fma_f32 v[38:39], v[86:87], v[24:25], v[38:39] neg_lo:[1,0,0] neg_hi:[1,0,0]
	ds_read_b128 v[76:79], v115 offset:11696
	ds_read_b128 v[80:83], v115 offset:11840
	s_waitcnt lgkmcnt(5)
	v_pk_fma_f32 v[36:37], v[88:89], v[26:27], v[36:37] neg_lo:[1,0,0] neg_hi:[1,0,0]
	v_pk_fma_f32 v[38:39], v[92:93], v[26:27], v[38:39] neg_lo:[1,0,0] neg_hi:[1,0,0]
	v_pk_fma_f32 v[36:37], v[90:91], v[28:29], v[36:37] neg_lo:[1,0,0] neg_hi:[1,0,0]
	v_pk_fma_f32 v[38:39], v[94:95], v[28:29], v[38:39] neg_lo:[1,0,0] neg_hi:[1,0,0]
	ds_read_b128 v[84:87], v115 offset:12112
	ds_read_b128 v[88:91], v115 offset:11856
	s_waitcnt lgkmcnt(5)
	v_pk_fma_f32 v[36:37], v[96:97], v[30:31], v[36:37] neg_lo:[1,0,0] neg_hi:[1,0,0]
	v_pk_fma_f32 v[38:39], v[68:69], v[30:31], v[38:39] neg_lo:[1,0,0] neg_hi:[1,0,0]
	v_pk_fma_f32 v[36:37], v[98:99], v[32:33], v[36:37] neg_lo:[1,0,0] neg_hi:[1,0,0]
	v_pk_fma_f32 v[38:39], v[70:71], v[32:33], v[38:39] neg_lo:[1,0,0] neg_hi:[1,0,0]
	ds_read_b128 v[92:95], v115 offset:12128
	ds_read_b128 v[96:99], v115 offset:11872
	s_waitcnt lgkmcnt(5)
	v_pk_fma_f32 v[36:37], v[72:73], v[34:35], v[36:37] neg_lo:[1,0,0] neg_hi:[1,0,0]
	v_pk_fma_f32 v[38:39], v[76:77], v[34:35], v[38:39] neg_lo:[1,0,0] neg_hi:[1,0,0]
	ds_read_b128 v[68:71], v115 offset:12144
	ds_read_b128 v[72:75], v115 offset:11888
	v_add_f32_e32 v36, v36, v37
	v_add_f32_e32 v38, v38, v39
	v_fma_f32 v37, -v78, v36, v38
	v_cmp_eq_u32_e32 vcc, 36, v127
	v_mov_b32_e32 v39, 0
	v_mov_b32_e32 v41, 0
	v_cndmask_b32_e64 v38, 0, 1.0, vcc
	v_cmp_eq_u32_e32 vcc, 37, v127
	s_nop 1
	v_cndmask_b32_e64 v40, 0, 1.0, vcc
	s_waitcnt lgkmcnt(5)
; __device__ __forceinline__ void gdn_chunk_prep(Frame& F) {
;     ...
;             for (int i = 0; i < 50; i += 2) {
;                 float a = (i == lane) ? 1.f : 0.f, bq = (i + 1 == lane) ? 1.f : 0.f;
; #pragma unroll
;                 for (int j = 0; j < i; ++j) { a = fmaf(-Amat[i * 68 + j], T[j], a); bq = fmaf(-Amat[(i + 1) * 68 + j], T[j], bq); }
;                 T[i] = a;
;                 T[i + 1] = fmaf(-Amat[(i + 1) * 68 + i], a, bq);
;                 asm volatile("" ::: "memory");
;             }
	v_pk_fma_f32 v[38:39], v[80:81], v[2:3], v[38:39] neg_lo:[1,0,0] neg_hi:[1,0,0]
	v_pk_fma_f32 v[40:41], v[84:85], v[2:3], v[40:41] neg_lo:[1,0,0] neg_hi:[1,0,0]
	v_pk_fma_f32 v[38:39], v[82:83], v[4:5], v[38:39] neg_lo:[1,0,0] neg_hi:[1,0,0]
	v_pk_fma_f32 v[40:41], v[86:87], v[4:5], v[40:41] neg_lo:[1,0,0] neg_hi:[1,0,0]
	ds_read_b128 v[76:79], v115 offset:12160
	ds_read_b128 v[80:83], v115 offset:11904
	s_waitcnt lgkmcnt(5)
	v_pk_fma_f32 v[38:39], v[88:89], v[6:7], v[38:39] neg_lo:[1,0,0] neg_hi:[1,0,0]
	v_pk_fma_f32 v[40:41], v[92:93], v[6:7], v[40:41] neg_lo:[1,0,0] neg_hi:[1,0,0]
	v_pk_fma_f32 v[38:39], v[90:91], v[8:9], v[38:39] neg_lo:[1,0,0] neg_hi:[1,0,0]
	v_pk_fma_f32 v[40:41], v[94:95], v[8:9], v[40:41] neg_lo:[1,0,0] neg_hi:[1,0,0]
	ds_read_b128 v[84:87], v115 offset:12176
	ds_read_b128 v[88:91], v115 offset:11920
	s_waitcnt lgkmcnt(5)
	v_pk_fma_f32 v[38:39], v[96:97], v[10:11], v[38:39] neg_lo:[1,0,0] neg_hi:[1,0,0]
	v_pk_fma_f32 v[40:41], v[68:69], v[10:11], v[40:41] neg_lo:[1,0,0] neg_hi:[1,0,0]
	v_pk_fma_f32 v[38:39], v[98:99], v[12:13], v[38:39] neg_lo:[1,0,0] neg_hi:[1,0,0]
	v_pk_fma_f32 v[40:41], v[70:71], v[12:13], v[40:41] neg_lo:[1,0,0] neg_hi:[1,0,0]
	ds_read_b128 v[92:95], v115 offset:12192
	ds_read_b128 v[96:99], v115 offset:11936
	s_waitcnt lgkmcnt(5)
	v_pk_fma_f32 v[38:39], v[72:73], v[14:15], v[38:39] neg_lo:[1,0,0] neg_hi:[1,0,0]
	v_pk_fma_f32 v[40:41], v[76:77], v[14:15], v[40:41] neg_lo:[1,0,0] neg_hi:[1,0,0]
	v_pk_fma_f32 v[38:39], v[74:75], v[16:17], v[38:39] neg_lo:[1,0,0] neg_hi:[1,0,0]
	v_pk_fma_f32 v[40:41], v[78:79], v[16:17], v[40:41] neg_lo:[1,0,0] neg_hi:[1,0,0]
	ds_read_b128 v[68:71], v115 offset:12208
	ds_read_b128 v[72:75], v115 offset:11952
	s_waitcnt lgkmcnt(5)
	v_pk_fma_f32 v[38:39], v[80:81], v[18:19], v[38:39] neg_lo:[1,0,0] neg_hi:[1,0,0]
	v_pk_fma_f32 v[40:41], v[84:85], v[18:19], v[40:41] neg_lo:[1,0,0] neg_hi:[1,0,0]
	v_pk_fma_f32 v[38:39], v[82:83], v[20:21], v[38:39] neg_lo:[1,0,0] neg_hi:[1,0,0]
	v_pk_fma_f32 v[40:41], v[86:87], v[20:21], v[40:41] neg_lo:[1,0,0] neg_hi:[1,0,0]
	ds_read_b128 v[76:79], v115 offset:12224
	ds_read_b128 v[80:83], v115 offset:11968
	s_waitcnt lgkmcnt(5)
	v_pk_fma_f32 v[38:39], v[88:89], v[22:23], v[38:39] neg_lo:[1,0,0] neg_hi:[1,0,0]
	v_pk_fma_f32 v[40:41], v[92:93], v[22:23], v[40:41] neg_lo:[1,0,0] neg_hi:[1,0,0]
	v_pk_fma_f32 v[38:39], v[90:91], v[24:25], v[38:39] neg_lo:[1,0,0] neg_hi:[1,0,0]
	v_pk_fma_f32 v[40:41], v[94:95], v[24:25], v[40:41] neg_lo:[1,0,0] neg_hi:[1,0,0]
	ds_read_b128 v[84:87], v115 offset:12240
	ds_read_b32 v88, v115 offset:12256
	s_waitcnt lgkmcnt(5)
	v_pk_fma_f32 v[38:39], v[96:97], v[26:27], v[38:39] neg_lo:[1,0,0] neg_hi:[1,0,0]
	v_pk_fma_f32 v[40:41], v[68:69], v[26:27], v[40:41] neg_lo:[1,0,0] neg_hi:[1,0,0]
	v_pk_fma_f32 v[38:39], v[98:99], v[28:29], v[38:39] neg_lo:[1,0,0] neg_hi:[1,0,0]
	v_pk_fma_f32 v[40:41], v[70:71], v[28:29], v[40:41] neg_lo:[1,0,0] neg_hi:[1,0,0]
	ds_read_b128 v[92:95], v115 offset:12384
	ds_read_b128 v[96:99], v115 offset:12656
	s_waitcnt lgkmcnt(5)
	v_pk_fma_f32 v[38:39], v[72:73], v[30:31], v[38:39] neg_lo:[1,0,0] neg_hi:[1,0,0]
	v_pk_fma_f32 v[40:41], v[76:77], v[30:31], v[40:41] neg_lo:[1,0,0] neg_hi:[1,0,0]
	v_pk_fma_f32 v[38:39], v[74:75], v[32:33], v[38:39] neg_lo:[1,0,0] neg_hi:[1,0,0]
	v_pk_fma_f32 v[40:41], v[78:79], v[32:33], v[40:41] neg_lo:[1,0,0] neg_hi:[1,0,0]
	ds_read_b128 v[68:71], v115 offset:12400
	ds_read_b128 v[72:75], v115 offset:12672
	s_waitcnt lgkmcnt(5)
	v_pk_fma_f32 v[38:39], v[80:81], v[34:35], v[38:39] neg_lo:[1,0,0] neg_hi:[1,0,0]
	v_pk_fma_f32 v[40:41], v[84:85], v[34:35], v[40:41] neg_lo:[1,0,0] neg_hi:[1,0,0]
	v_pk_fma_f32 v[38:39], v[82:83], v[36:37], v[38:39] neg_lo:[1,0,0] neg_hi:[1,0,0]
	v_pk_fma_f32 v[40:41], v[86:87], v[36:37], v[40:41] neg_lo:[1,0,0] neg_hi:[1,0,0]
	ds_read_b128 v[76:79], v115 offset:12416
	ds_read_b128 v[80:83], v115 offset:12688
	s_waitcnt lgkmcnt(6)
	ds_read_b128 v[84:87], v115 offset:12432
	v_add_f32_e32 v38, v38, v39
	v_add_f32_e32 v40, v40, v41
	v_fma_f32 v39, -v88, v38, v40
	v_cmp_eq_u32_e32 vcc, 38, v127
	v_mov_b32_e32 v41, 0
	v_mov_b32_e32 v43, 0
	v_cndmask_b32_e64 v40, 0, 1.0, vcc
	v_cmp_eq_u32_e32 vcc, 39, v127
	s_nop 1
	v_cndmask_b32_e64 v42, 0, 1.0, vcc
	s_waitcnt lgkmcnt(5)
	v_pk_fma_f32 v[40:41], v[92:93], v[2:3], v[40:41] neg_lo:[1,0,0] neg_hi:[1,0,0]
	v_pk_fma_f32 v[42:43], v[96:97], v[2:3], v[42:43] neg_lo:[1,0,0] neg_hi:[1,0,0]
	v_pk_fma_f32 v[40:41], v[94:95], v[4:5], v[40:41] neg_lo:[1,0,0] neg_hi:[1,0,0]
	v_pk_fma_f32 v[42:43], v[98:99], v[4:5], v[42:43] neg_lo:[1,0,0] neg_hi:[1,0,0]
	ds_read_b128 v[88:91], v115 offset:12704
	ds_read_b128 v[92:95], v115 offset:12448
	s_waitcnt lgkmcnt(5)
	v_pk_fma_f32 v[40:41], v[68:69], v[6:7], v[40:41] neg_lo:[1,0,0] neg_hi:[1,0,0]
	v_pk_fma_f32 v[42:43], v[72:73], v[6:7], v[42:43] neg_lo:[1,0,0] neg_hi:[1,0,0]
	v_pk_fma_f32 v[40:41], v[70:71], v[8:9], v[40:41] neg_lo:[1,0,0] neg_hi:[1,0,0]
	v_pk_fma_f32 v[42:43], v[74:75], v[8:9], v[42:43] neg_lo:[1,0,0] neg_hi:[1,0,0]
	ds_read_b128 v[96:99], v115 offset:12720
	ds_read_b128 v[68:71], v115 offset:12464
	s_waitcnt lgkmcnt(5)
	v_pk_fma_f32 v[40:41], v[76:77], v[10:11], v[40:41] neg_lo:[1,0,0] neg_hi:[1,0,0]
	v_pk_fma_f32 v[42:43], v[80:81], v[10:11], v[42:43] neg_lo:[1,0,0] neg_hi:[1,0,0]
	v_pk_fma_f32 v[40:41], v[78:79], v[12:13], v[40:41] neg_lo:[1,0,0] neg_hi:[1,0,0]
	v_pk_fma_f32 v[42:43], v[82:83], v[12:13], v[42:43] neg_lo:[1,0,0] neg_hi:[1,0,0]
	ds_read_b128 v[72:75], v115 offset:12736
	ds_read_b128 v[76:79], v115 offset:12480
	s_waitcnt lgkmcnt(5)
; __device__ __forceinline__ void gdn_chunk_prep(Frame& F) {
;     ...
;             for (int i = 0; i < 50; i += 2) {
;                 float a = (i == lane) ? 1.f : 0.f, bq = (i + 1 == lane) ? 1.f : 0.f;
; #pragma unroll
;                 for (int j = 0; j < i; ++j) { a = fmaf(-Amat[i * 68 + j], T[j], a); bq = fmaf(-Amat[(i + 1) * 68 + j], T[j], bq); }
;                 T[i] = a;
;                 T[i + 1] = fmaf(-Amat[(i + 1) * 68 + i], a, bq);
;                 asm volatile("" ::: "memory");
;             }
	v_pk_fma_f32 v[40:41], v[84:85], v[14:15], v[40:41] neg_lo:[1,0,0] neg_hi:[1,0,0]
	v_pk_fma_f32 v[42:43], v[88:89], v[14:15], v[42:43] neg_lo:[1,0,0] neg_hi:[1,0,0]
	v_pk_fma_f32 v[40:41], v[86:87], v[16:17], v[40:41] neg_lo:[1,0,0] neg_hi:[1,0,0]
	v_pk_fma_f32 v[42:43], v[90:91], v[16:17], v[42:43] neg_lo:[1,0,0] neg_hi:[1,0,0]
	ds_read_b128 v[80:83], v115 offset:12752
	ds_read_b128 v[84:87], v115 offset:12496
	s_waitcnt lgkmcnt(5)
	v_pk_fma_f32 v[40:41], v[92:93], v[18:19], v[40:41] neg_lo:[1,0,0] neg_hi:[1,0,0]
	v_pk_fma_f32 v[42:43], v[96:97], v[18:19], v[42:43] neg_lo:[1,0,0] neg_hi:[1,0,0]
	v_pk_fma_f32 v[40:41], v[94:95], v[20:21], v[40:41] neg_lo:[1,0,0] neg_hi:[1,0,0]
	v_pk_fma_f32 v[42:43], v[98:99], v[20:21], v[42:43] neg_lo:[1,0,0] neg_hi:[1,0,0]
	ds_read_b128 v[88:91], v115 offset:12768
	ds_read_b128 v[92:95], v115 offset:12512
	s_waitcnt lgkmcnt(5)
	v_pk_fma_f32 v[40:41], v[68:69], v[22:23], v[40:41] neg_lo:[1,0,0] neg_hi:[1,0,0]
	v_pk_fma_f32 v[42:43], v[72:73], v[22:23], v[42:43] neg_lo:[1,0,0] neg_hi:[1,0,0]
	v_pk_fma_f32 v[40:41], v[70:71], v[24:25], v[40:41] neg_lo:[1,0,0] neg_hi:[1,0,0]
	v_pk_fma_f32 v[42:43], v[74:75], v[24:25], v[42:43] neg_lo:[1,0,0] neg_hi:[1,0,0]
	ds_read_b128 v[96:99], v115 offset:12784
	ds_read_b128 v[68:71], v115 offset:12528
	s_waitcnt lgkmcnt(5)
	v_pk_fma_f32 v[40:41], v[76:77], v[26:27], v[40:41] neg_lo:[1,0,0] neg_hi:[1,0,0]
	v_pk_fma_f32 v[42:43], v[80:81], v[26:27], v[42:43] neg_lo:[1,0,0] neg_hi:[1,0,0]
	v_pk_fma_f32 v[40:41], v[78:79], v[28:29], v[40:41] neg_lo:[1,0,0] neg_hi:[1,0,0]
	v_pk_fma_f32 v[42:43], v[82:83], v[28:29], v[42:43] neg_lo:[1,0,0] neg_hi:[1,0,0]
	ds_read_b128 v[72:75], v115 offset:12800
	ds_read_b128 v[76:79], v115 offset:12928
	s_waitcnt lgkmcnt(5)
	v_pk_fma_f32 v[40:41], v[84:85], v[30:31], v[40:41] neg_lo:[1,0,0] neg_hi:[1,0,0]
	v_pk_fma_f32 v[42:43], v[88:89], v[30:31], v[42:43] neg_lo:[1,0,0] neg_hi:[1,0,0]
	v_pk_fma_f32 v[40:41], v[86:87], v[32:33], v[40:41] neg_lo:[1,0,0] neg_hi:[1,0,0]
	v_pk_fma_f32 v[42:43], v[90:91], v[32:33], v[42:43] neg_lo:[1,0,0] neg_hi:[1,0,0]
	ds_read_b128 v[80:83], v115 offset:13200
	ds_read_b128 v[84:87], v115 offset:12944
	s_waitcnt lgkmcnt(5)
	v_pk_fma_f32 v[40:41], v[92:93], v[34:35], v[40:41] neg_lo:[1,0,0] neg_hi:[1,0,0]
	v_pk_fma_f32 v[42:43], v[96:97], v[34:35], v[42:43] neg_lo:[1,0,0] neg_hi:[1,0,0]
	v_pk_fma_f32 v[40:41], v[94:95], v[36:37], v[40:41] neg_lo:[1,0,0] neg_hi:[1,0,0]
	v_pk_fma_f32 v[42:43], v[98:99], v[36:37], v[42:43] neg_lo:[1,0,0] neg_hi:[1,0,0]
	ds_read_b128 v[88:91], v115 offset:13216
	ds_read_b128 v[92:95], v115 offset:12960
	s_waitcnt lgkmcnt(5)
	v_pk_fma_f32 v[40:41], v[68:69], v[38:39], v[40:41] neg_lo:[1,0,0] neg_hi:[1,0,0]
	v_pk_fma_f32 v[42:43], v[72:73], v[38:39], v[42:43] neg_lo:[1,0,0] neg_hi:[1,0,0]
	ds_read_b128 v[96:99], v115 offset:13232
	ds_read_b128 v[68:71], v115 offset:12976
	v_add_f32_e32 v40, v40, v41
	v_add_f32_e32 v42, v42, v43
	v_fma_f32 v41, -v74, v40, v42
	v_cmp_eq_u32_e32 vcc, 40, v127
	v_mov_b32_e32 v43, 0
	v_mov_b32_e32 v45, 0
	v_cndmask_b32_e64 v42, 0, 1.0, vcc
	v_cmp_eq_u32_e32 vcc, 41, v127
	s_nop 1
	v_cndmask_b32_e64 v44, 0, 1.0, vcc
	s_waitcnt lgkmcnt(5)
	v_pk_fma_f32 v[42:43], v[76:77], v[2:3], v[42:43] neg_lo:[1,0,0] neg_hi:[1,0,0]
	v_pk_fma_f32 v[44:45], v[80:81], v[2:3], v[44:45] neg_lo:[1,0,0] neg_hi:[1,0,0]
	v_pk_fma_f32 v[42:43], v[78:79], v[4:5], v[42:43] neg_lo:[1,0,0] neg_hi:[1,0,0]
	v_pk_fma_f32 v[44:45], v[82:83], v[4:5], v[44:45] neg_lo:[1,0,0] neg_hi:[1,0,0]
	ds_read_b128 v[72:75], v115 offset:13248
	ds_read_b128 v[76:79], v115 offset:12992
	s_waitcnt lgkmcnt(5)
	v_pk_fma_f32 v[42:43], v[84:85], v[6:7], v[42:43] neg_lo:[1,0,0] neg_hi:[1,0,0]
	v_pk_fma_f32 v[44:45], v[88:89], v[6:7], v[44:45] neg_lo:[1,0,0] neg_hi:[1,0,0]
	v_pk_fma_f32 v[42:43], v[86:87], v[8:9], v[42:43] neg_lo:[1,0,0] neg_hi:[1,0,0]
	v_pk_fma_f32 v[44:45], v[90:91], v[8:9], v[44:45] neg_lo:[1,0,0] neg_hi:[1,0,0]
	ds_read_b128 v[80:83], v115 offset:13264
	ds_read_b128 v[84:87], v115 offset:13008
	s_waitcnt lgkmcnt(5)
	v_pk_fma_f32 v[42:43], v[92:93], v[10:11], v[42:43] neg_lo:[1,0,0] neg_hi:[1,0,0]
	v_pk_fma_f32 v[44:45], v[96:97], v[10:11], v[44:45] neg_lo:[1,0,0] neg_hi:[1,0,0]
	v_pk_fma_f32 v[42:43], v[94:95], v[12:13], v[42:43] neg_lo:[1,0,0] neg_hi:[1,0,0]
	v_pk_fma_f32 v[44:45], v[98:99], v[12:13], v[44:45] neg_lo:[1,0,0] neg_hi:[1,0,0]
	ds_read_b128 v[88:91], v115 offset:13280
	ds_read_b128 v[92:95], v115 offset:13024
	s_waitcnt lgkmcnt(5)
	v_pk_fma_f32 v[42:43], v[68:69], v[14:15], v[42:43] neg_lo:[1,0,0] neg_hi:[1,0,0]
	v_pk_fma_f32 v[44:45], v[72:73], v[14:15], v[44:45] neg_lo:[1,0,0] neg_hi:[1,0,0]
	v_pk_fma_f32 v[42:43], v[70:71], v[16:17], v[42:43] neg_lo:[1,0,0] neg_hi:[1,0,0]
	v_pk_fma_f32 v[44:45], v[74:75], v[16:17], v[44:45] neg_lo:[1,0,0] neg_hi:[1,0,0]
	ds_read_b128 v[96:99], v115 offset:13296
	ds_read_b128 v[68:71], v115 offset:13040
	s_waitcnt lgkmcnt(5)
	v_pk_fma_f32 v[42:43], v[76:77], v[18:19], v[42:43] neg_lo:[1,0,0] neg_hi:[1,0,0]
	v_pk_fma_f32 v[44:45], v[80:81], v[18:19], v[44:45] neg_lo:[1,0,0] neg_hi:[1,0,0]
	v_pk_fma_f32 v[42:43], v[78:79], v[20:21], v[42:43] neg_lo:[1,0,0] neg_hi:[1,0,0]
	v_pk_fma_f32 v[44:45], v[82:83], v[20:21], v[44:45] neg_lo:[1,0,0] neg_hi:[1,0,0]
	ds_read_b128 v[72:75], v115 offset:13312
	ds_read_b128 v[76:79], v115 offset:13056
	s_waitcnt lgkmcnt(5)
	v_pk_fma_f32 v[42:43], v[84:85], v[22:23], v[42:43] neg_lo:[1,0,0] neg_hi:[1,0,0]
	v_pk_fma_f32 v[44:45], v[88:89], v[22:23], v[44:45] neg_lo:[1,0,0] neg_hi:[1,0,0]
	v_pk_fma_f32 v[42:43], v[86:87], v[24:25], v[42:43] neg_lo:[1,0,0] neg_hi:[1,0,0]
	v_pk_fma_f32 v[44:45], v[90:91], v[24:25], v[44:45] neg_lo:[1,0,0] neg_hi:[1,0,0]
	ds_read_b128 v[80:83], v115 offset:13328
	ds_read_b128 v[84:87], v115 offset:13072
	s_waitcnt lgkmcnt(5)
; __device__ __forceinline__ void gdn_chunk_prep(Frame& F) {
;     ...
;             for (int i = 0; i < 50; i += 2) {
;                 float a = (i == lane) ? 1.f : 0.f, bq = (i + 1 == lane) ? 1.f : 0.f;
; #pragma unroll
;                 for (int j = 0; j < i; ++j) { a = fmaf(-Amat[i * 68 + j], T[j], a); bq = fmaf(-Amat[(i + 1) * 68 + j], T[j], bq); }
;                 T[i] = a;
;                 T[i + 1] = fmaf(-Amat[(i + 1) * 68 + i], a, bq);
;                 asm volatile("" ::: "memory");
;             }
	v_pk_fma_f32 v[42:43], v[92:93], v[26:27], v[42:43] neg_lo:[1,0,0] neg_hi:[1,0,0]
	v_pk_fma_f32 v[44:45], v[96:97], v[26:27], v[44:45] neg_lo:[1,0,0] neg_hi:[1,0,0]
	v_pk_fma_f32 v[42:43], v[94:95], v[28:29], v[42:43] neg_lo:[1,0,0] neg_hi:[1,0,0]
	v_pk_fma_f32 v[44:45], v[98:99], v[28:29], v[44:45] neg_lo:[1,0,0] neg_hi:[1,0,0]
	ds_read_b128 v[88:91], v115 offset:13344
	ds_read_b32 v92, v115 offset:13360
	s_waitcnt lgkmcnt(5)
	v_pk_fma_f32 v[42:43], v[68:69], v[30:31], v[42:43] neg_lo:[1,0,0] neg_hi:[1,0,0]
	v_pk_fma_f32 v[44:45], v[72:73], v[30:31], v[44:45] neg_lo:[1,0,0] neg_hi:[1,0,0]
	v_pk_fma_f32 v[42:43], v[70:71], v[32:33], v[42:43] neg_lo:[1,0,0] neg_hi:[1,0,0]
	v_pk_fma_f32 v[44:45], v[74:75], v[32:33], v[44:45] neg_lo:[1,0,0] neg_hi:[1,0,0]
	ds_read_b128 v[96:99], v115 offset:13472
	ds_read_b128 v[68:71], v115 offset:13744
	s_waitcnt lgkmcnt(5)
	v_pk_fma_f32 v[42:43], v[76:77], v[34:35], v[42:43] neg_lo:[1,0,0] neg_hi:[1,0,0]
	v_pk_fma_f32 v[44:45], v[80:81], v[34:35], v[44:45] neg_lo:[1,0,0] neg_hi:[1,0,0]
	v_pk_fma_f32 v[42:43], v[78:79], v[36:37], v[42:43] neg_lo:[1,0,0] neg_hi:[1,0,0]
	v_pk_fma_f32 v[44:45], v[82:83], v[36:37], v[44:45] neg_lo:[1,0,0] neg_hi:[1,0,0]
	ds_read_b128 v[72:75], v115 offset:13488
	ds_read_b128 v[76:79], v115 offset:13760
	s_waitcnt lgkmcnt(5)
	v_pk_fma_f32 v[42:43], v[84:85], v[38:39], v[42:43] neg_lo:[1,0,0] neg_hi:[1,0,0]
	v_pk_fma_f32 v[44:45], v[88:89], v[38:39], v[44:45] neg_lo:[1,0,0] neg_hi:[1,0,0]
	v_pk_fma_f32 v[42:43], v[86:87], v[40:41], v[42:43] neg_lo:[1,0,0] neg_hi:[1,0,0]
	v_pk_fma_f32 v[44:45], v[90:91], v[40:41], v[44:45] neg_lo:[1,0,0] neg_hi:[1,0,0]
	ds_read_b128 v[80:83], v115 offset:13504
	ds_read_b128 v[84:87], v115 offset:13776
	s_waitcnt lgkmcnt(6)
	ds_read_b128 v[88:91], v115 offset:13520
	v_add_f32_e32 v42, v42, v43
	v_add_f32_e32 v44, v44, v45
	v_fma_f32 v43, -v92, v42, v44
	v_cmp_eq_u32_e32 vcc, 42, v127
	v_mov_b32_e32 v45, 0
	v_mov_b32_e32 v47, 0
	v_cndmask_b32_e64 v44, 0, 1.0, vcc
	v_cmp_eq_u32_e32 vcc, 43, v127
	s_nop 1
	v_cndmask_b32_e64 v46, 0, 1.0, vcc
	s_waitcnt lgkmcnt(5)
	v_pk_fma_f32 v[44:45], v[96:97], v[2:3], v[44:45] neg_lo:[1,0,0] neg_hi:[1,0,0]
	v_pk_fma_f32 v[46:47], v[68:69], v[2:3], v[46:47] neg_lo:[1,0,0] neg_hi:[1,0,0]
	v_pk_fma_f32 v[44:45], v[98:99], v[4:5], v[44:45] neg_lo:[1,0,0] neg_hi:[1,0,0]
	v_pk_fma_f32 v[46:47], v[70:71], v[4:5], v[46:47] neg_lo:[1,0,0] neg_hi:[1,0,0]
	ds_read_b128 v[92:95], v115 offset:13792
	ds_read_b128 v[96:99], v115 offset:13536
	s_waitcnt lgkmcnt(5)
	v_pk_fma_f32 v[44:45], v[72:73], v[6:7], v[44:45] neg_lo:[1,0,0] neg_hi:[1,0,0]
	v_pk_fma_f32 v[46:47], v[76:77], v[6:7], v[46:47] neg_lo:[1,0,0] neg_hi:[1,0,0]
	v_pk_fma_f32 v[44:45], v[74:75], v[8:9], v[44:45] neg_lo:[1,0,0] neg_hi:[1,0,0]
	v_pk_fma_f32 v[46:47], v[78:79], v[8:9], v[46:47] neg_lo:[1,0,0] neg_hi:[1,0,0]
	ds_read_b128 v[68:71], v115 offset:13808
	ds_read_b128 v[72:75], v115 offset:13552
	s_waitcnt lgkmcnt(5)
	v_pk_fma_f32 v[44:45], v[80:81], v[10:11], v[44:45] neg_lo:[1,0,0] neg_hi:[1,0,0]
	v_pk_fma_f32 v[46:47], v[84:85], v[10:11], v[46:47] neg_lo:[1,0,0] neg_hi:[1,0,0]
	v_pk_fma_f32 v[44:45], v[82:83], v[12:13], v[44:45] neg_lo:[1,0,0] neg_hi:[1,0,0]
	v_pk_fma_f32 v[46:47], v[86:87], v[12:13], v[46:47] neg_lo:[1,0,0] neg_hi:[1,0,0]
	ds_read_b128 v[76:79], v115 offset:13824
	ds_read_b128 v[80:83], v115 offset:13568
	s_waitcnt lgkmcnt(5)
	v_pk_fma_f32 v[44:45], v[88:89], v[14:15], v[44:45] neg_lo:[1,0,0] neg_hi:[1,0,0]
	v_pk_fma_f32 v[46:47], v[92:93], v[14:15], v[46:47] neg_lo:[1,0,0] neg_hi:[1,0,0]
	v_pk_fma_f32 v[44:45], v[90:91], v[16:17], v[44:45] neg_lo:[1,0,0] neg_hi:[1,0,0]
	v_pk_fma_f32 v[46:47], v[94:95], v[16:17], v[46:47] neg_lo:[1,0,0] neg_hi:[1,0,0]
	ds_read_b128 v[84:87], v115 offset:13840
	ds_read_b128 v[88:91], v115 offset:13584
	s_waitcnt lgkmcnt(5)
	v_pk_fma_f32 v[44:45], v[96:97], v[18:19], v[44:45] neg_lo:[1,0,0] neg_hi:[1,0,0]
	v_pk_fma_f32 v[46:47], v[68:69], v[18:19], v[46:47] neg_lo:[1,0,0] neg_hi:[1,0,0]
	v_pk_fma_f32 v[44:45], v[98:99], v[20:21], v[44:45] neg_lo:[1,0,0] neg_hi:[1,0,0]
	v_pk_fma_f32 v[46:47], v[70:71], v[20:21], v[46:47] neg_lo:[1,0,0] neg_hi:[1,0,0]
	ds_read_b128 v[92:95], v115 offset:13856
	ds_read_b128 v[96:99], v115 offset:13600
	s_waitcnt lgkmcnt(5)
	v_pk_fma_f32 v[44:45], v[72:73], v[22:23], v[44:45] neg_lo:[1,0,0] neg_hi:[1,0,0]
	v_pk_fma_f32 v[46:47], v[76:77], v[22:23], v[46:47] neg_lo:[1,0,0] neg_hi:[1,0,0]
	v_pk_fma_f32 v[44:45], v[74:75], v[24:25], v[44:45] neg_lo:[1,0,0] neg_hi:[1,0,0]
	v_pk_fma_f32 v[46:47], v[78:79], v[24:25], v[46:47] neg_lo:[1,0,0] neg_hi:[1,0,0]
	ds_read_b128 v[68:71], v115 offset:13872
	ds_read_b128 v[72:75], v115 offset:13616
	s_waitcnt lgkmcnt(5)
	v_pk_fma_f32 v[44:45], v[80:81], v[26:27], v[44:45] neg_lo:[1,0,0] neg_hi:[1,0,0]
	v_pk_fma_f32 v[46:47], v[84:85], v[26:27], v[46:47] neg_lo:[1,0,0] neg_hi:[1,0,0]
	v_pk_fma_f32 v[44:45], v[82:83], v[28:29], v[44:45] neg_lo:[1,0,0] neg_hi:[1,0,0]
	v_pk_fma_f32 v[46:47], v[86:87], v[28:29], v[46:47] neg_lo:[1,0,0] neg_hi:[1,0,0]
	ds_read_b128 v[76:79], v115 offset:13888
	ds_read_b128 v[80:83], v115 offset:13632
	s_waitcnt lgkmcnt(5)
	v_pk_fma_f32 v[44:45], v[88:89], v[30:31], v[44:45] neg_lo:[1,0,0] neg_hi:[1,0,0]
	v_pk_fma_f32 v[46:47], v[92:93], v[30:31], v[46:47] neg_lo:[1,0,0] neg_hi:[1,0,0]
	v_pk_fma_f32 v[44:45], v[90:91], v[32:33], v[44:45] neg_lo:[1,0,0] neg_hi:[1,0,0]
	v_pk_fma_f32 v[46:47], v[94:95], v[32:33], v[46:47] neg_lo:[1,0,0] neg_hi:[1,0,0]
	ds_read_b128 v[84:87], v115 offset:13904
	ds_read_b128 v[88:91], v115 offset:14016
	s_waitcnt lgkmcnt(5)
; __device__ __forceinline__ void gdn_chunk_prep(Frame& F) {
;     ...
;             for (int i = 0; i < 50; i += 2) {
;                 float a = (i == lane) ? 1.f : 0.f, bq = (i + 1 == lane) ? 1.f : 0.f;
; #pragma unroll
;                 for (int j = 0; j < i; ++j) { a = fmaf(-Amat[i * 68 + j], T[j], a); bq = fmaf(-Amat[(i + 1) * 68 + j], T[j], bq); }
;                 T[i] = a;
;                 T[i + 1] = fmaf(-Amat[(i + 1) * 68 + i], a, bq);
;                 asm volatile("" ::: "memory");
;             }
	v_pk_fma_f32 v[44:45], v[96:97], v[34:35], v[44:45] neg_lo:[1,0,0] neg_hi:[1,0,0]
	v_pk_fma_f32 v[46:47], v[68:69], v[34:35], v[46:47] neg_lo:[1,0,0] neg_hi:[1,0,0]
	v_pk_fma_f32 v[44:45], v[98:99], v[36:37], v[44:45] neg_lo:[1,0,0] neg_hi:[1,0,0]
	v_pk_fma_f32 v[46:47], v[70:71], v[36:37], v[46:47] neg_lo:[1,0,0] neg_hi:[1,0,0]
	ds_read_b128 v[92:95], v115 offset:14288
	ds_read_b128 v[96:99], v115 offset:14032
	s_waitcnt lgkmcnt(5)
	v_pk_fma_f32 v[44:45], v[72:73], v[38:39], v[44:45] neg_lo:[1,0,0] neg_hi:[1,0,0]
	v_pk_fma_f32 v[46:47], v[76:77], v[38:39], v[46:47] neg_lo:[1,0,0] neg_hi:[1,0,0]
	v_pk_fma_f32 v[44:45], v[74:75], v[40:41], v[44:45] neg_lo:[1,0,0] neg_hi:[1,0,0]
	v_pk_fma_f32 v[46:47], v[78:79], v[40:41], v[46:47] neg_lo:[1,0,0] neg_hi:[1,0,0]
	ds_read_b128 v[68:71], v115 offset:14304
	ds_read_b128 v[72:75], v115 offset:14048
	s_waitcnt lgkmcnt(5)
	v_pk_fma_f32 v[44:45], v[80:81], v[42:43], v[44:45] neg_lo:[1,0,0] neg_hi:[1,0,0]
	v_pk_fma_f32 v[46:47], v[84:85], v[42:43], v[46:47] neg_lo:[1,0,0] neg_hi:[1,0,0]
	ds_read_b128 v[76:79], v115 offset:14320
	ds_read_b128 v[80:83], v115 offset:14064
	v_add_f32_e32 v44, v44, v45
	v_add_f32_e32 v46, v46, v47
	v_fma_f32 v45, -v86, v44, v46
	v_cmp_eq_u32_e32 vcc, 44, v127
	v_mov_b32_e32 v47, 0
	v_mov_b32_e32 v49, 0
	v_cndmask_b32_e64 v46, 0, 1.0, vcc
	v_cmp_eq_u32_e32 vcc, 45, v127
	s_nop 1
	v_cndmask_b32_e64 v48, 0, 1.0, vcc
	s_waitcnt lgkmcnt(5)
	v_pk_fma_f32 v[46:47], v[88:89], v[2:3], v[46:47] neg_lo:[1,0,0] neg_hi:[1,0,0]
	v_pk_fma_f32 v[48:49], v[92:93], v[2:3], v[48:49] neg_lo:[1,0,0] neg_hi:[1,0,0]
	v_pk_fma_f32 v[46:47], v[90:91], v[4:5], v[46:47] neg_lo:[1,0,0] neg_hi:[1,0,0]
	v_pk_fma_f32 v[48:49], v[94:95], v[4:5], v[48:49] neg_lo:[1,0,0] neg_hi:[1,0,0]
	ds_read_b128 v[84:87], v115 offset:14336
	ds_read_b128 v[88:91], v115 offset:14080
	s_waitcnt lgkmcnt(5)
	v_pk_fma_f32 v[46:47], v[96:97], v[6:7], v[46:47] neg_lo:[1,0,0] neg_hi:[1,0,0]
	v_pk_fma_f32 v[48:49], v[68:69], v[6:7], v[48:49] neg_lo:[1,0,0] neg_hi:[1,0,0]
	v_pk_fma_f32 v[46:47], v[98:99], v[8:9], v[46:47] neg_lo:[1,0,0] neg_hi:[1,0,0]
	v_pk_fma_f32 v[48:49], v[70:71], v[8:9], v[48:49] neg_lo:[1,0,0] neg_hi:[1,0,0]
	ds_read_b128 v[92:95], v115 offset:14352
	ds_read_b128 v[96:99], v115 offset:14096
	s_waitcnt lgkmcnt(5)
	v_pk_fma_f32 v[46:47], v[72:73], v[10:11], v[46:47] neg_lo:[1,0,0] neg_hi:[1,0,0]
	v_pk_fma_f32 v[48:49], v[76:77], v[10:11], v[48:49] neg_lo:[1,0,0] neg_hi:[1,0,0]
	v_pk_fma_f32 v[46:47], v[74:75], v[12:13], v[46:47] neg_lo:[1,0,0] neg_hi:[1,0,0]
	v_pk_fma_f32 v[48:49], v[78:79], v[12:13], v[48:49] neg_lo:[1,0,0] neg_hi:[1,0,0]
	ds_read_b128 v[68:71], v115 offset:14368
	ds_read_b128 v[72:75], v115 offset:14112
	s_waitcnt lgkmcnt(5)
	v_pk_fma_f32 v[46:47], v[80:81], v[14:15], v[46:47] neg_lo:[1,0,0] neg_hi:[1,0,0]
	v_pk_fma_f32 v[48:49], v[84:85], v[14:15], v[48:49] neg_lo:[1,0,0] neg_hi:[1,0,0]
	v_pk_fma_f32 v[46:47], v[82:83], v[16:17], v[46:47] neg_lo:[1,0,0] neg_hi:[1,0,0]
	v_pk_fma_f32 v[48:49], v[86:87], v[16:17], v[48:49] neg_lo:[1,0,0] neg_hi:[1,0,0]
	ds_read_b128 v[76:79], v115 offset:14384
	ds_read_b128 v[80:83], v115 offset:14128
	s_waitcnt lgkmcnt(5)
	v_pk_fma_f32 v[46:47], v[88:89], v[18:19], v[46:47] neg_lo:[1,0,0] neg_hi:[1,0,0]
	v_pk_fma_f32 v[48:49], v[92:93], v[18:19], v[48:49] neg_lo:[1,0,0] neg_hi:[1,0,0]
	v_pk_fma_f32 v[46:47], v[90:91], v[20:21], v[46:47] neg_lo:[1,0,0] neg_hi:[1,0,0]
	v_pk_fma_f32 v[48:49], v[94:95], v[20:21], v[48:49] neg_lo:[1,0,0] neg_hi:[1,0,0]
	ds_read_b128 v[84:87], v115 offset:14400
	ds_read_b128 v[88:91], v115 offset:14144
	s_waitcnt lgkmcnt(5)
	v_pk_fma_f32 v[46:47], v[96:97], v[22:23], v[46:47] neg_lo:[1,0,0] neg_hi:[1,0,0]
	v_pk_fma_f32 v[48:49], v[68:69], v[22:23], v[48:49] neg_lo:[1,0,0] neg_hi:[1,0,0]
	v_pk_fma_f32 v[46:47], v[98:99], v[24:25], v[46:47] neg_lo:[1,0,0] neg_hi:[1,0,0]
	v_pk_fma_f32 v[48:49], v[70:71], v[24:25], v[48:49] neg_lo:[1,0,0] neg_hi:[1,0,0]
	ds_read_b128 v[92:95], v115 offset:14416
	ds_read_b128 v[96:99], v115 offset:14160
	s_waitcnt lgkmcnt(5)
	v_pk_fma_f32 v[46:47], v[72:73], v[26:27], v[46:47] neg_lo:[1,0,0] neg_hi:[1,0,0]
	v_pk_fma_f32 v[48:49], v[76:77], v[26:27], v[48:49] neg_lo:[1,0,0] neg_hi:[1,0,0]
	v_pk_fma_f32 v[46:47], v[74:75], v[28:29], v[46:47] neg_lo:[1,0,0] neg_hi:[1,0,0]
	v_pk_fma_f32 v[48:49], v[78:79], v[28:29], v[48:49] neg_lo:[1,0,0] neg_hi:[1,0,0]
	ds_read_b128 v[68:71], v115 offset:14432
	ds_read_b128 v[72:75], v115 offset:14176
	s_waitcnt lgkmcnt(5)
	v_pk_fma_f32 v[46:47], v[80:81], v[30:31], v[46:47] neg_lo:[1,0,0] neg_hi:[1,0,0]
	v_pk_fma_f32 v[48:49], v[84:85], v[30:31], v[48:49] neg_lo:[1,0,0] neg_hi:[1,0,0]
	v_pk_fma_f32 v[46:47], v[82:83], v[32:33], v[46:47] neg_lo:[1,0,0] neg_hi:[1,0,0]
	v_pk_fma_f32 v[48:49], v[86:87], v[32:33], v[48:49] neg_lo:[1,0,0] neg_hi:[1,0,0]
	ds_read_b128 v[76:79], v115 offset:14448
	ds_read_b32 v80, v115 offset:14464
	s_waitcnt lgkmcnt(5)
	v_pk_fma_f32 v[46:47], v[88:89], v[34:35], v[46:47] neg_lo:[1,0,0] neg_hi:[1,0,0]
	v_pk_fma_f32 v[48:49], v[92:93], v[34:35], v[48:49] neg_lo:[1,0,0] neg_hi:[1,0,0]
	v_pk_fma_f32 v[46:47], v[90:91], v[36:37], v[46:47] neg_lo:[1,0,0] neg_hi:[1,0,0]
	v_pk_fma_f32 v[48:49], v[94:95], v[36:37], v[48:49] neg_lo:[1,0,0] neg_hi:[1,0,0]
	ds_read_b128 v[84:87], v115 offset:14560
	ds_read_b128 v[88:91], v115 offset:14832
	s_waitcnt lgkmcnt(5)
	v_pk_fma_f32 v[46:47], v[96:97], v[38:39], v[46:47] neg_lo:[1,0,0] neg_hi:[1,0,0]
	v_pk_fma_f32 v[48:49], v[68:69], v[38:39], v[48:49] neg_lo:[1,0,0] neg_hi:[1,0,0]
	v_pk_fma_f32 v[46:47], v[98:99], v[40:41], v[46:47] neg_lo:[1,0,0] neg_hi:[1,0,0]
	v_pk_fma_f32 v[48:49], v[70:71], v[40:41], v[48:49] neg_lo:[1,0,0] neg_hi:[1,0,0]
	ds_read_b128 v[92:95], v115 offset:14576
	ds_read_b128 v[96:99], v115 offset:14848
	s_waitcnt lgkmcnt(5)
; __device__ __forceinline__ void gdn_chunk_prep(Frame& F) {
;     ...
;             for (int i = 0; i < 50; i += 2) {
;                 float a = (i == lane) ? 1.f : 0.f, bq = (i + 1 == lane) ? 1.f : 0.f;
; #pragma unroll
;                 for (int j = 0; j < i; ++j) { a = fmaf(-Amat[i * 68 + j], T[j], a); bq = fmaf(-Amat[(i + 1) * 68 + j], T[j], bq); }
;                 T[i] = a;
;                 T[i + 1] = fmaf(-Amat[(i + 1) * 68 + i], a, bq);
;                 asm volatile("" ::: "memory");
;             }
	v_pk_fma_f32 v[46:47], v[72:73], v[42:43], v[46:47] neg_lo:[1,0,0] neg_hi:[1,0,0]
	v_pk_fma_f32 v[48:49], v[76:77], v[42:43], v[48:49] neg_lo:[1,0,0] neg_hi:[1,0,0]
	v_pk_fma_f32 v[46:47], v[74:75], v[44:45], v[46:47] neg_lo:[1,0,0] neg_hi:[1,0,0]
	v_pk_fma_f32 v[48:49], v[78:79], v[44:45], v[48:49] neg_lo:[1,0,0] neg_hi:[1,0,0]
	ds_read_b128 v[68:71], v115 offset:14592
	ds_read_b128 v[72:75], v115 offset:14864
	s_waitcnt lgkmcnt(6)
	ds_read_b128 v[76:79], v115 offset:14608
	v_add_f32_e32 v46, v46, v47
	v_add_f32_e32 v48, v48, v49
	v_fma_f32 v47, -v80, v46, v48
	v_cmp_eq_u32_e32 vcc, 46, v127
	v_mov_b32_e32 v49, 0
	v_mov_b32_e32 v51, 0
	v_cndmask_b32_e64 v48, 0, 1.0, vcc
	v_cmp_eq_u32_e32 vcc, 47, v127
	s_nop 1
	v_cndmask_b32_e64 v50, 0, 1.0, vcc
	s_waitcnt lgkmcnt(5)
	v_pk_fma_f32 v[48:49], v[84:85], v[2:3], v[48:49] neg_lo:[1,0,0] neg_hi:[1,0,0]
	v_pk_fma_f32 v[50:51], v[88:89], v[2:3], v[50:51] neg_lo:[1,0,0] neg_hi:[1,0,0]
	v_pk_fma_f32 v[48:49], v[86:87], v[4:5], v[48:49] neg_lo:[1,0,0] neg_hi:[1,0,0]
	v_pk_fma_f32 v[50:51], v[90:91], v[4:5], v[50:51] neg_lo:[1,0,0] neg_hi:[1,0,0]
	ds_read_b128 v[80:83], v115 offset:14880
	ds_read_b128 v[84:87], v115 offset:14624
	s_waitcnt lgkmcnt(5)
	v_pk_fma_f32 v[48:49], v[92:93], v[6:7], v[48:49] neg_lo:[1,0,0] neg_hi:[1,0,0]
	v_pk_fma_f32 v[50:51], v[96:97], v[6:7], v[50:51] neg_lo:[1,0,0] neg_hi:[1,0,0]
	v_pk_fma_f32 v[48:49], v[94:95], v[8:9], v[48:49] neg_lo:[1,0,0] neg_hi:[1,0,0]
	v_pk_fma_f32 v[50:51], v[98:99], v[8:9], v[50:51] neg_lo:[1,0,0] neg_hi:[1,0,0]
	ds_read_b128 v[88:91], v115 offset:14896
	ds_read_b128 v[92:95], v115 offset:14640
	s_waitcnt lgkmcnt(5)
	v_pk_fma_f32 v[48:49], v[68:69], v[10:11], v[48:49] neg_lo:[1,0,0] neg_hi:[1,0,0]
	v_pk_fma_f32 v[50:51], v[72:73], v[10:11], v[50:51] neg_lo:[1,0,0] neg_hi:[1,0,0]
	v_pk_fma_f32 v[48:49], v[70:71], v[12:13], v[48:49] neg_lo:[1,0,0] neg_hi:[1,0,0]
	v_pk_fma_f32 v[50:51], v[74:75], v[12:13], v[50:51] neg_lo:[1,0,0] neg_hi:[1,0,0]
	ds_read_b128 v[96:99], v115 offset:14912
	ds_read_b128 v[68:71], v115 offset:14656
	s_waitcnt lgkmcnt(5)
	v_pk_fma_f32 v[48:49], v[76:77], v[14:15], v[48:49] neg_lo:[1,0,0] neg_hi:[1,0,0]
	v_pk_fma_f32 v[50:51], v[80:81], v[14:15], v[50:51] neg_lo:[1,0,0] neg_hi:[1,0,0]
	v_pk_fma_f32 v[48:49], v[78:79], v[16:17], v[48:49] neg_lo:[1,0,0] neg_hi:[1,0,0]
	v_pk_fma_f32 v[50:51], v[82:83], v[16:17], v[50:51] neg_lo:[1,0,0] neg_hi:[1,0,0]
	ds_read_b128 v[72:75], v115 offset:14928
	ds_read_b128 v[76:79], v115 offset:14672
	s_waitcnt lgkmcnt(5)
	v_pk_fma_f32 v[48:49], v[84:85], v[18:19], v[48:49] neg_lo:[1,0,0] neg_hi:[1,0,0]
	v_pk_fma_f32 v[50:51], v[88:89], v[18:19], v[50:51] neg_lo:[1,0,0] neg_hi:[1,0,0]
	v_pk_fma_f32 v[48:49], v[86:87], v[20:21], v[48:49] neg_lo:[1,0,0] neg_hi:[1,0,0]
	v_pk_fma_f32 v[50:51], v[90:91], v[20:21], v[50:51] neg_lo:[1,0,0] neg_hi:[1,0,0]
	ds_read_b128 v[80:83], v115 offset:14944
	ds_read_b128 v[84:87], v115 offset:14688
	s_waitcnt lgkmcnt(5)
	v_pk_fma_f32 v[48:49], v[92:93], v[22:23], v[48:49] neg_lo:[1,0,0] neg_hi:[1,0,0]
	v_pk_fma_f32 v[50:51], v[96:97], v[22:23], v[50:51] neg_lo:[1,0,0] neg_hi:[1,0,0]
	v_pk_fma_f32 v[48:49], v[94:95], v[24:25], v[48:49] neg_lo:[1,0,0] neg_hi:[1,0,0]
	v_pk_fma_f32 v[50:51], v[98:99], v[24:25], v[50:51] neg_lo:[1,0,0] neg_hi:[1,0,0]
	ds_read_b128 v[88:91], v115 offset:14960
	ds_read_b128 v[92:95], v115 offset:14704
	s_waitcnt lgkmcnt(5)
	v_pk_fma_f32 v[48:49], v[68:69], v[26:27], v[48:49] neg_lo:[1,0,0] neg_hi:[1,0,0]
	v_pk_fma_f32 v[50:51], v[72:73], v[26:27], v[50:51] neg_lo:[1,0,0] neg_hi:[1,0,0]
	v_pk_fma_f32 v[48:49], v[70:71], v[28:29], v[48:49] neg_lo:[1,0,0] neg_hi:[1,0,0]
	v_pk_fma_f32 v[50:51], v[74:75], v[28:29], v[50:51] neg_lo:[1,0,0] neg_hi:[1,0,0]
	ds_read_b128 v[96:99], v115 offset:14976
	ds_read_b128 v[68:71], v115 offset:14720
	s_waitcnt lgkmcnt(5)
	v_pk_fma_f32 v[48:49], v[76:77], v[30:31], v[48:49] neg_lo:[1,0,0] neg_hi:[1,0,0]
	v_pk_fma_f32 v[50:51], v[80:81], v[30:31], v[50:51] neg_lo:[1,0,0] neg_hi:[1,0,0]
	v_pk_fma_f32 v[48:49], v[78:79], v[32:33], v[48:49] neg_lo:[1,0,0] neg_hi:[1,0,0]
	v_pk_fma_f32 v[50:51], v[82:83], v[32:33], v[50:51] neg_lo:[1,0,0] neg_hi:[1,0,0]
	ds_read_b128 v[72:75], v115 offset:14992
	ds_read_b128 v[76:79], v115 offset:14736
	s_waitcnt lgkmcnt(5)
	v_pk_fma_f32 v[48:49], v[84:85], v[34:35], v[48:49] neg_lo:[1,0,0] neg_hi:[1,0,0]
	v_pk_fma_f32 v[50:51], v[88:89], v[34:35], v[50:51] neg_lo:[1,0,0] neg_hi:[1,0,0]
	v_pk_fma_f32 v[48:49], v[86:87], v[36:37], v[48:49] neg_lo:[1,0,0] neg_hi:[1,0,0]
	v_pk_fma_f32 v[50:51], v[90:91], v[36:37], v[50:51] neg_lo:[1,0,0] neg_hi:[1,0,0]
	ds_read_b128 v[80:83], v115 offset:15008
	ds_read_b128 v[84:87], v115 offset:15104
	s_waitcnt lgkmcnt(5)
	v_pk_fma_f32 v[48:49], v[92:93], v[38:39], v[48:49] neg_lo:[1,0,0] neg_hi:[1,0,0]
	v_pk_fma_f32 v[50:51], v[96:97], v[38:39], v[50:51] neg_lo:[1,0,0] neg_hi:[1,0,0]
	v_pk_fma_f32 v[48:49], v[94:95], v[40:41], v[48:49] neg_lo:[1,0,0] neg_hi:[1,0,0]
	v_pk_fma_f32 v[50:51], v[98:99], v[40:41], v[50:51] neg_lo:[1,0,0] neg_hi:[1,0,0]
	ds_read_b128 v[88:91], v115 offset:15376
	ds_read_b128 v[92:95], v115 offset:15120
	s_waitcnt lgkmcnt(5)
	v_pk_fma_f32 v[48:49], v[68:69], v[42:43], v[48:49] neg_lo:[1,0,0] neg_hi:[1,0,0]
	v_pk_fma_f32 v[50:51], v[72:73], v[42:43], v[50:51] neg_lo:[1,0,0] neg_hi:[1,0,0]
	v_pk_fma_f32 v[48:49], v[70:71], v[44:45], v[48:49] neg_lo:[1,0,0] neg_hi:[1,0,0]
	v_pk_fma_f32 v[50:51], v[74:75], v[44:45], v[50:51] neg_lo:[1,0,0] neg_hi:[1,0,0]
	ds_read_b128 v[96:99], v115 offset:15392
	ds_read_b128 v[68:71], v115 offset:15136
	s_waitcnt lgkmcnt(5)
; #define GP_BAR() do { asm volatile("s_waitcnt lgkmcnt(0)" ::: "memory"); __builtin_amdgcn_s_barrier(); asm volatile("" ::: "memory"); } while (0)
; __device__ __forceinline__ void gdn_chunk_prep(Frame& F) {
;     ...
;             for (int i = 0; i < 50; i += 2) {
;                 float a = (i == lane) ? 1.f : 0.f, bq = (i + 1 == lane) ? 1.f : 0.f;
; #pragma unroll
;                 for (int j = 0; j < i; ++j) { a = fmaf(-Amat[i * 68 + j], T[j], a); bq = fmaf(-Amat[(i + 1) * 68 + j], T[j], bq); }
;                 T[i] = a;
;                 T[i + 1] = fmaf(-Amat[(i + 1) * 68 + i], a, bq);
;                 asm volatile("" ::: "memory");
;             }
;             GP_BAR();
	v_pk_fma_f32 v[48:49], v[76:77], v[46:47], v[48:49] neg_lo:[1,0,0] neg_hi:[1,0,0]
	v_pk_fma_f32 v[50:51], v[80:81], v[46:47], v[50:51] neg_lo:[1,0,0] neg_hi:[1,0,0]
	ds_read_b128 v[72:75], v115 offset:15408
	ds_read_b128 v[76:79], v115 offset:15152
	v_add_f32_e32 v48, v48, v49
	v_add_f32_e32 v50, v50, v51
	v_fma_f32 v49, -v82, v48, v50
	v_cmp_eq_u32_e32 vcc, 48, v127
	v_mov_b32_e32 v51, 0
	v_mov_b32_e32 v53, 0
	v_cndmask_b32_e64 v50, 0, 1.0, vcc
	v_cmp_eq_u32_e32 vcc, 49, v127
	s_nop 1
	v_cndmask_b32_e64 v52, 0, 1.0, vcc
	s_waitcnt lgkmcnt(5)
	v_pk_fma_f32 v[50:51], v[84:85], v[2:3], v[50:51] neg_lo:[1,0,0] neg_hi:[1,0,0]
	v_pk_fma_f32 v[52:53], v[88:89], v[2:3], v[52:53] neg_lo:[1,0,0] neg_hi:[1,0,0]
	v_pk_fma_f32 v[50:51], v[86:87], v[4:5], v[50:51] neg_lo:[1,0,0] neg_hi:[1,0,0]
	v_pk_fma_f32 v[52:53], v[90:91], v[4:5], v[52:53] neg_lo:[1,0,0] neg_hi:[1,0,0]
	ds_read_b128 v[80:83], v115 offset:15424
	ds_read_b128 v[84:87], v115 offset:15168
	s_waitcnt lgkmcnt(5)
	v_pk_fma_f32 v[50:51], v[92:93], v[6:7], v[50:51] neg_lo:[1,0,0] neg_hi:[1,0,0]
	v_pk_fma_f32 v[52:53], v[96:97], v[6:7], v[52:53] neg_lo:[1,0,0] neg_hi:[1,0,0]
	v_pk_fma_f32 v[50:51], v[94:95], v[8:9], v[50:51] neg_lo:[1,0,0] neg_hi:[1,0,0]
	v_pk_fma_f32 v[52:53], v[98:99], v[8:9], v[52:53] neg_lo:[1,0,0] neg_hi:[1,0,0]
	ds_read_b128 v[88:91], v115 offset:15440
	ds_read_b128 v[92:95], v115 offset:15184
	s_waitcnt lgkmcnt(5)
	v_pk_fma_f32 v[50:51], v[68:69], v[10:11], v[50:51] neg_lo:[1,0,0] neg_hi:[1,0,0]
	v_pk_fma_f32 v[52:53], v[72:73], v[10:11], v[52:53] neg_lo:[1,0,0] neg_hi:[1,0,0]
	v_pk_fma_f32 v[50:51], v[70:71], v[12:13], v[50:51] neg_lo:[1,0,0] neg_hi:[1,0,0]
	v_pk_fma_f32 v[52:53], v[74:75], v[12:13], v[52:53] neg_lo:[1,0,0] neg_hi:[1,0,0]
	ds_read_b128 v[96:99], v115 offset:15456
	ds_read_b128 v[68:71], v115 offset:15200
	s_waitcnt lgkmcnt(5)
	v_pk_fma_f32 v[50:51], v[76:77], v[14:15], v[50:51] neg_lo:[1,0,0] neg_hi:[1,0,0]
	v_pk_fma_f32 v[52:53], v[80:81], v[14:15], v[52:53] neg_lo:[1,0,0] neg_hi:[1,0,0]
	v_pk_fma_f32 v[50:51], v[78:79], v[16:17], v[50:51] neg_lo:[1,0,0] neg_hi:[1,0,0]
	v_pk_fma_f32 v[52:53], v[82:83], v[16:17], v[52:53] neg_lo:[1,0,0] neg_hi:[1,0,0]
	ds_read_b128 v[72:75], v115 offset:15472
	ds_read_b128 v[76:79], v115 offset:15216
	s_waitcnt lgkmcnt(5)
	v_pk_fma_f32 v[50:51], v[84:85], v[18:19], v[50:51] neg_lo:[1,0,0] neg_hi:[1,0,0]
	v_pk_fma_f32 v[52:53], v[88:89], v[18:19], v[52:53] neg_lo:[1,0,0] neg_hi:[1,0,0]
	v_pk_fma_f32 v[50:51], v[86:87], v[20:21], v[50:51] neg_lo:[1,0,0] neg_hi:[1,0,0]
	v_pk_fma_f32 v[52:53], v[90:91], v[20:21], v[52:53] neg_lo:[1,0,0] neg_hi:[1,0,0]
	ds_read_b128 v[80:83], v115 offset:15488
	ds_read_b128 v[84:87], v115 offset:15232
	s_waitcnt lgkmcnt(5)
	v_pk_fma_f32 v[50:51], v[92:93], v[22:23], v[50:51] neg_lo:[1,0,0] neg_hi:[1,0,0]
	v_pk_fma_f32 v[52:53], v[96:97], v[22:23], v[52:53] neg_lo:[1,0,0] neg_hi:[1,0,0]
	v_pk_fma_f32 v[50:51], v[94:95], v[24:25], v[50:51] neg_lo:[1,0,0] neg_hi:[1,0,0]
	v_pk_fma_f32 v[52:53], v[98:99], v[24:25], v[52:53] neg_lo:[1,0,0] neg_hi:[1,0,0]
	ds_read_b128 v[88:91], v115 offset:15504
	ds_read_b128 v[92:95], v115 offset:15248
	s_waitcnt lgkmcnt(5)
	v_pk_fma_f32 v[50:51], v[68:69], v[26:27], v[50:51] neg_lo:[1,0,0] neg_hi:[1,0,0]
	v_pk_fma_f32 v[52:53], v[72:73], v[26:27], v[52:53] neg_lo:[1,0,0] neg_hi:[1,0,0]
	v_pk_fma_f32 v[50:51], v[70:71], v[28:29], v[50:51] neg_lo:[1,0,0] neg_hi:[1,0,0]
	v_pk_fma_f32 v[52:53], v[74:75], v[28:29], v[52:53] neg_lo:[1,0,0] neg_hi:[1,0,0]
	ds_read_b128 v[96:99], v115 offset:15520
	ds_read_b128 v[68:71], v115 offset:15264
	s_waitcnt lgkmcnt(5)
	v_pk_fma_f32 v[50:51], v[76:77], v[30:31], v[50:51] neg_lo:[1,0,0] neg_hi:[1,0,0]
	v_pk_fma_f32 v[52:53], v[80:81], v[30:31], v[52:53] neg_lo:[1,0,0] neg_hi:[1,0,0]
	v_pk_fma_f32 v[50:51], v[78:79], v[32:33], v[50:51] neg_lo:[1,0,0] neg_hi:[1,0,0]
	v_pk_fma_f32 v[52:53], v[82:83], v[32:33], v[52:53] neg_lo:[1,0,0] neg_hi:[1,0,0]
	ds_read_b128 v[72:75], v115 offset:15536
	ds_read_b128 v[76:79], v115 offset:15280
	s_waitcnt lgkmcnt(5)
	v_pk_fma_f32 v[50:51], v[84:85], v[34:35], v[50:51] neg_lo:[1,0,0] neg_hi:[1,0,0]
	v_pk_fma_f32 v[52:53], v[88:89], v[34:35], v[52:53] neg_lo:[1,0,0] neg_hi:[1,0,0]
	v_pk_fma_f32 v[50:51], v[86:87], v[36:37], v[50:51] neg_lo:[1,0,0] neg_hi:[1,0,0]
	v_pk_fma_f32 v[52:53], v[90:91], v[36:37], v[52:53] neg_lo:[1,0,0] neg_hi:[1,0,0]
	ds_read_b128 v[80:83], v115 offset:15552
	ds_read_b32 v84, v115 offset:15568
	s_waitcnt lgkmcnt(5)
	v_pk_fma_f32 v[50:51], v[92:93], v[38:39], v[50:51] neg_lo:[1,0,0] neg_hi:[1,0,0]
	v_pk_fma_f32 v[52:53], v[96:97], v[38:39], v[52:53] neg_lo:[1,0,0] neg_hi:[1,0,0]
	v_pk_fma_f32 v[50:51], v[94:95], v[40:41], v[50:51] neg_lo:[1,0,0] neg_hi:[1,0,0]
	v_pk_fma_f32 v[52:53], v[98:99], v[40:41], v[52:53] neg_lo:[1,0,0] neg_hi:[1,0,0]
	ds_read_b128 v[88:91], v115 offset:15648
	ds_read_b128 v[92:95], v115 offset:15920
	s_waitcnt lgkmcnt(5)
	v_pk_fma_f32 v[50:51], v[68:69], v[42:43], v[50:51] neg_lo:[1,0,0] neg_hi:[1,0,0]
	v_pk_fma_f32 v[52:53], v[72:73], v[42:43], v[52:53] neg_lo:[1,0,0] neg_hi:[1,0,0]
	v_pk_fma_f32 v[50:51], v[70:71], v[44:45], v[50:51] neg_lo:[1,0,0] neg_hi:[1,0,0]
	v_pk_fma_f32 v[52:53], v[74:75], v[44:45], v[52:53] neg_lo:[1,0,0] neg_hi:[1,0,0]
	ds_read_b128 v[96:99], v115 offset:15664
	ds_read_b128 v[68:71], v115 offset:15936
	s_waitcnt lgkmcnt(5)
	v_pk_fma_f32 v[50:51], v[76:77], v[46:47], v[50:51] neg_lo:[1,0,0] neg_hi:[1,0,0]
	v_pk_fma_f32 v[52:53], v[80:81], v[46:47], v[52:53] neg_lo:[1,0,0] neg_hi:[1,0,0]
	v_pk_fma_f32 v[50:51], v[78:79], v[48:49], v[50:51] neg_lo:[1,0,0] neg_hi:[1,0,0]
	v_pk_fma_f32 v[52:53], v[82:83], v[48:49], v[52:53] neg_lo:[1,0,0] neg_hi:[1,0,0]
	ds_read_b128 v[72:75], v115 offset:15680
	ds_read_b128 v[76:79], v115 offset:15952
	s_waitcnt lgkmcnt(6)
	ds_read_b128 v[80:83], v115 offset:15696
	v_add_f32_e32 v50, v50, v51
	v_add_f32_e32 v52, v52, v53
	v_fma_f32 v51, -v84, v50, v52
	s_waitcnt lgkmcnt(0)
	s_barrier
; __device__ __forceinline__ void gdn_chunk_prep(Frame& F) {
;     ...
;             for (int i = 50; i < 64; i += 2) {
;                 float a = (i == lane) ? 1.f : 0.f, bq = (i + 1 == lane) ? 1.f : 0.f;
; #pragma unroll
;                 for (int j = 0; j < i; ++j) { a = fmaf(-Amat[i * 68 + j], T[j], a); bq = fmaf(-Amat[(i + 1) * 68 + j], T[j], bq); }
;                 T[i] = a;
;                 T[i + 1] = fmaf(-Amat[(i + 1) * 68 + i], a, bq);
;                 asm volatile("" ::: "memory");
;             }
	v_cmp_eq_u32_e32 vcc, 50, v127
	v_mov_b32_e32 v53, 0
	v_mov_b32_e32 v55, 0
	v_cndmask_b32_e64 v52, 0, 1.0, vcc
	v_cmp_eq_u32_e32 vcc, 51, v127
	s_nop 1
	v_cndmask_b32_e64 v54, 0, 1.0, vcc
	s_waitcnt lgkmcnt(5)
	v_pk_fma_f32 v[52:53], v[88:89], v[2:3], v[52:53] neg_lo:[1,0,0] neg_hi:[1,0,0]
	v_pk_fma_f32 v[54:55], v[92:93], v[2:3], v[54:55] neg_lo:[1,0,0] neg_hi:[1,0,0]
	v_pk_fma_f32 v[52:53], v[90:91], v[4:5], v[52:53] neg_lo:[1,0,0] neg_hi:[1,0,0]
	v_pk_fma_f32 v[54:55], v[94:95], v[4:5], v[54:55] neg_lo:[1,0,0] neg_hi:[1,0,0]
	ds_read_b128 v[84:87], v115 offset:15968
	ds_read_b128 v[88:91], v115 offset:15712
	s_waitcnt lgkmcnt(5)
	v_pk_fma_f32 v[52:53], v[96:97], v[6:7], v[52:53] neg_lo:[1,0,0] neg_hi:[1,0,0]
	v_pk_fma_f32 v[54:55], v[68:69], v[6:7], v[54:55] neg_lo:[1,0,0] neg_hi:[1,0,0]
	v_pk_fma_f32 v[52:53], v[98:99], v[8:9], v[52:53] neg_lo:[1,0,0] neg_hi:[1,0,0]
	v_pk_fma_f32 v[54:55], v[70:71], v[8:9], v[54:55] neg_lo:[1,0,0] neg_hi:[1,0,0]
	ds_read_b128 v[92:95], v115 offset:15984
	ds_read_b128 v[96:99], v115 offset:15728
	s_waitcnt lgkmcnt(5)
	v_pk_fma_f32 v[52:53], v[72:73], v[10:11], v[52:53] neg_lo:[1,0,0] neg_hi:[1,0,0]
	v_pk_fma_f32 v[54:55], v[76:77], v[10:11], v[54:55] neg_lo:[1,0,0] neg_hi:[1,0,0]
	v_pk_fma_f32 v[52:53], v[74:75], v[12:13], v[52:53] neg_lo:[1,0,0] neg_hi:[1,0,0]
	v_pk_fma_f32 v[54:55], v[78:79], v[12:13], v[54:55] neg_lo:[1,0,0] neg_hi:[1,0,0]
	ds_read_b128 v[68:71], v115 offset:16000
	ds_read_b128 v[72:75], v115 offset:15744
	s_waitcnt lgkmcnt(5)
	v_pk_fma_f32 v[52:53], v[80:81], v[14:15], v[52:53] neg_lo:[1,0,0] neg_hi:[1,0,0]
	v_pk_fma_f32 v[54:55], v[84:85], v[14:15], v[54:55] neg_lo:[1,0,0] neg_hi:[1,0,0]
	v_pk_fma_f32 v[52:53], v[82:83], v[16:17], v[52:53] neg_lo:[1,0,0] neg_hi:[1,0,0]
	v_pk_fma_f32 v[54:55], v[86:87], v[16:17], v[54:55] neg_lo:[1,0,0] neg_hi:[1,0,0]
	ds_read_b128 v[76:79], v115 offset:16016
	ds_read_b128 v[80:83], v115 offset:15760
	s_waitcnt lgkmcnt(5)
	v_pk_fma_f32 v[52:53], v[88:89], v[18:19], v[52:53] neg_lo:[1,0,0] neg_hi:[1,0,0]
	v_pk_fma_f32 v[54:55], v[92:93], v[18:19], v[54:55] neg_lo:[1,0,0] neg_hi:[1,0,0]
	v_pk_fma_f32 v[52:53], v[90:91], v[20:21], v[52:53] neg_lo:[1,0,0] neg_hi:[1,0,0]
	v_pk_fma_f32 v[54:55], v[94:95], v[20:21], v[54:55] neg_lo:[1,0,0] neg_hi:[1,0,0]
	ds_read_b128 v[84:87], v115 offset:16032
	ds_read_b128 v[88:91], v115 offset:15776
	s_waitcnt lgkmcnt(5)
	v_pk_fma_f32 v[52:53], v[96:97], v[22:23], v[52:53] neg_lo:[1,0,0] neg_hi:[1,0,0]
	v_pk_fma_f32 v[54:55], v[68:69], v[22:23], v[54:55] neg_lo:[1,0,0] neg_hi:[1,0,0]
	v_pk_fma_f32 v[52:53], v[98:99], v[24:25], v[52:53] neg_lo:[1,0,0] neg_hi:[1,0,0]
	v_pk_fma_f32 v[54:55], v[70:71], v[24:25], v[54:55] neg_lo:[1,0,0] neg_hi:[1,0,0]
	ds_read_b128 v[92:95], v115 offset:16048
	ds_read_b128 v[96:99], v115 offset:15792
	s_waitcnt lgkmcnt(5)
	v_pk_fma_f32 v[52:53], v[72:73], v[26:27], v[52:53] neg_lo:[1,0,0] neg_hi:[1,0,0]
	v_pk_fma_f32 v[54:55], v[76:77], v[26:27], v[54:55] neg_lo:[1,0,0] neg_hi:[1,0,0]
	v_pk_fma_f32 v[52:53], v[74:75], v[28:29], v[52:53] neg_lo:[1,0,0] neg_hi:[1,0,0]
	v_pk_fma_f32 v[54:55], v[78:79], v[28:29], v[54:55] neg_lo:[1,0,0] neg_hi:[1,0,0]
	ds_read_b128 v[68:71], v115 offset:16064
	ds_read_b128 v[72:75], v115 offset:15808
	s_waitcnt lgkmcnt(5)
	v_pk_fma_f32 v[52:53], v[80:81], v[30:31], v[52:53] neg_lo:[1,0,0] neg_hi:[1,0,0]
	v_pk_fma_f32 v[54:55], v[84:85], v[30:31], v[54:55] neg_lo:[1,0,0] neg_hi:[1,0,0]
	v_pk_fma_f32 v[52:53], v[82:83], v[32:33], v[52:53] neg_lo:[1,0,0] neg_hi:[1,0,0]
	v_pk_fma_f32 v[54:55], v[86:87], v[32:33], v[54:55] neg_lo:[1,0,0] neg_hi:[1,0,0]
	ds_read_b128 v[76:79], v115 offset:16080
	ds_read_b128 v[80:83], v115 offset:15824
	s_waitcnt lgkmcnt(5)
	v_pk_fma_f32 v[52:53], v[88:89], v[34:35], v[52:53] neg_lo:[1,0,0] neg_hi:[1,0,0]
	v_pk_fma_f32 v[54:55], v[92:93], v[34:35], v[54:55] neg_lo:[1,0,0] neg_hi:[1,0,0]
	v_pk_fma_f32 v[52:53], v[90:91], v[36:37], v[52:53] neg_lo:[1,0,0] neg_hi:[1,0,0]
	v_pk_fma_f32 v[54:55], v[94:95], v[36:37], v[54:55] neg_lo:[1,0,0] neg_hi:[1,0,0]
	ds_read_b128 v[84:87], v115 offset:16096
	ds_read_b128 v[88:91], v115 offset:15840
	s_waitcnt lgkmcnt(5)
	v_pk_fma_f32 v[52:53], v[96:97], v[38:39], v[52:53] neg_lo:[1,0,0] neg_hi:[1,0,0]
	v_pk_fma_f32 v[54:55], v[68:69], v[38:39], v[54:55] neg_lo:[1,0,0] neg_hi:[1,0,0]
	v_pk_fma_f32 v[52:53], v[98:99], v[40:41], v[52:53] neg_lo:[1,0,0] neg_hi:[1,0,0]
	v_pk_fma_f32 v[54:55], v[70:71], v[40:41], v[54:55] neg_lo:[1,0,0] neg_hi:[1,0,0]
	ds_read_b128 v[92:95], v115 offset:16112
	ds_read_b128 v[96:99], v115 offset:16192
	s_waitcnt lgkmcnt(5)
	v_pk_fma_f32 v[52:53], v[72:73], v[42:43], v[52:53] neg_lo:[1,0,0] neg_hi:[1,0,0]
	v_pk_fma_f32 v[54:55], v[76:77], v[42:43], v[54:55] neg_lo:[1,0,0] neg_hi:[1,0,0]
	v_pk_fma_f32 v[52:53], v[74:75], v[44:45], v[52:53] neg_lo:[1,0,0] neg_hi:[1,0,0]
	v_pk_fma_f32 v[54:55], v[78:79], v[44:45], v[54:55] neg_lo:[1,0,0] neg_hi:[1,0,0]
	ds_read_b128 v[68:71], v115 offset:16464
	ds_read_b128 v[72:75], v115 offset:16208
	s_waitcnt lgkmcnt(5)
	v_pk_fma_f32 v[52:53], v[80:81], v[46:47], v[52:53] neg_lo:[1,0,0] neg_hi:[1,0,0]
	v_pk_fma_f32 v[54:55], v[84:85], v[46:47], v[54:55] neg_lo:[1,0,0] neg_hi:[1,0,0]
	v_pk_fma_f32 v[52:53], v[82:83], v[48:49], v[52:53] neg_lo:[1,0,0] neg_hi:[1,0,0]
	v_pk_fma_f32 v[54:55], v[86:87], v[48:49], v[54:55] neg_lo:[1,0,0] neg_hi:[1,0,0]
	ds_read_b128 v[76:79], v115 offset:16480
	ds_read_b128 v[80:83], v115 offset:16224
	s_waitcnt lgkmcnt(5)
; __device__ __forceinline__ void gdn_chunk_prep(Frame& F) {
;     ...
;             for (int i = 50; i < 64; i += 2) {
;                 float a = (i == lane) ? 1.f : 0.f, bq = (i + 1 == lane) ? 1.f : 0.f;
; #pragma unroll
;                 for (int j = 0; j < i; ++j) { a = fmaf(-Amat[i * 68 + j], T[j], a); bq = fmaf(-Amat[(i + 1) * 68 + j], T[j], bq); }
;                 T[i] = a;
;                 T[i + 1] = fmaf(-Amat[(i + 1) * 68 + i], a, bq);
;                 asm volatile("" ::: "memory");
;             }
	v_pk_fma_f32 v[52:53], v[88:89], v[50:51], v[52:53] neg_lo:[1,0,0] neg_hi:[1,0,0]
	v_pk_fma_f32 v[54:55], v[92:93], v[50:51], v[54:55] neg_lo:[1,0,0] neg_hi:[1,0,0]
	ds_read_b128 v[84:87], v115 offset:16496
	ds_read_b128 v[88:91], v115 offset:16240
	v_add_f32_e32 v52, v52, v53
	v_add_f32_e32 v54, v54, v55
	v_fma_f32 v53, -v94, v52, v54
	v_cmp_eq_u32_e32 vcc, 52, v127
	v_mov_b32_e32 v55, 0
	v_mov_b32_e32 v57, 0
	v_cndmask_b32_e64 v54, 0, 1.0, vcc
	v_cmp_eq_u32_e32 vcc, 53, v127
	s_nop 1
	v_cndmask_b32_e64 v56, 0, 1.0, vcc
	s_waitcnt lgkmcnt(5)
	v_pk_fma_f32 v[54:55], v[96:97], v[2:3], v[54:55] neg_lo:[1,0,0] neg_hi:[1,0,0]
	v_pk_fma_f32 v[56:57], v[68:69], v[2:3], v[56:57] neg_lo:[1,0,0] neg_hi:[1,0,0]
	v_pk_fma_f32 v[54:55], v[98:99], v[4:5], v[54:55] neg_lo:[1,0,0] neg_hi:[1,0,0]
	v_pk_fma_f32 v[56:57], v[70:71], v[4:5], v[56:57] neg_lo:[1,0,0] neg_hi:[1,0,0]
	ds_read_b128 v[92:95], v115 offset:16512
	ds_read_b128 v[96:99], v115 offset:16256
	s_waitcnt lgkmcnt(5)
	v_pk_fma_f32 v[54:55], v[72:73], v[6:7], v[54:55] neg_lo:[1,0,0] neg_hi:[1,0,0]
	v_pk_fma_f32 v[56:57], v[76:77], v[6:7], v[56:57] neg_lo:[1,0,0] neg_hi:[1,0,0]
	v_pk_fma_f32 v[54:55], v[74:75], v[8:9], v[54:55] neg_lo:[1,0,0] neg_hi:[1,0,0]
	v_pk_fma_f32 v[56:57], v[78:79], v[8:9], v[56:57] neg_lo:[1,0,0] neg_hi:[1,0,0]
	ds_read_b128 v[68:71], v115 offset:16528
	ds_read_b128 v[72:75], v115 offset:16272
	s_waitcnt lgkmcnt(5)
	v_pk_fma_f32 v[54:55], v[80:81], v[10:11], v[54:55] neg_lo:[1,0,0] neg_hi:[1,0,0]
	v_pk_fma_f32 v[56:57], v[84:85], v[10:11], v[56:57] neg_lo:[1,0,0] neg_hi:[1,0,0]
	v_pk_fma_f32 v[54:55], v[82:83], v[12:13], v[54:55] neg_lo:[1,0,0] neg_hi:[1,0,0]
	v_pk_fma_f32 v[56:57], v[86:87], v[12:13], v[56:57] neg_lo:[1,0,0] neg_hi:[1,0,0]
	ds_read_b128 v[76:79], v115 offset:16544
	ds_read_b128 v[80:83], v115 offset:16288
	s_waitcnt lgkmcnt(5)
	v_pk_fma_f32 v[54:55], v[88:89], v[14:15], v[54:55] neg_lo:[1,0,0] neg_hi:[1,0,0]
	v_pk_fma_f32 v[56:57], v[92:93], v[14:15], v[56:57] neg_lo:[1,0,0] neg_hi:[1,0,0]
	v_pk_fma_f32 v[54:55], v[90:91], v[16:17], v[54:55] neg_lo:[1,0,0] neg_hi:[1,0,0]
	v_pk_fma_f32 v[56:57], v[94:95], v[16:17], v[56:57] neg_lo:[1,0,0] neg_hi:[1,0,0]
	ds_read_b128 v[84:87], v115 offset:16560
	ds_read_b128 v[88:91], v115 offset:16304
	s_waitcnt lgkmcnt(5)
	v_pk_fma_f32 v[54:55], v[96:97], v[18:19], v[54:55] neg_lo:[1,0,0] neg_hi:[1,0,0]
	v_pk_fma_f32 v[56:57], v[68:69], v[18:19], v[56:57] neg_lo:[1,0,0] neg_hi:[1,0,0]
	v_pk_fma_f32 v[54:55], v[98:99], v[20:21], v[54:55] neg_lo:[1,0,0] neg_hi:[1,0,0]
	v_pk_fma_f32 v[56:57], v[70:71], v[20:21], v[56:57] neg_lo:[1,0,0] neg_hi:[1,0,0]
	ds_read_b128 v[92:95], v115 offset:16576
	ds_read_b128 v[96:99], v115 offset:16320
	s_waitcnt lgkmcnt(5)
	v_pk_fma_f32 v[54:55], v[72:73], v[22:23], v[54:55] neg_lo:[1,0,0] neg_hi:[1,0,0]
	v_pk_fma_f32 v[56:57], v[76:77], v[22:23], v[56:57] neg_lo:[1,0,0] neg_hi:[1,0,0]
	v_pk_fma_f32 v[54:55], v[74:75], v[24:25], v[54:55] neg_lo:[1,0,0] neg_hi:[1,0,0]
	v_pk_fma_f32 v[56:57], v[78:79], v[24:25], v[56:57] neg_lo:[1,0,0] neg_hi:[1,0,0]
	ds_read_b128 v[68:71], v115 offset:16592
	ds_read_b128 v[72:75], v115 offset:16336
	s_waitcnt lgkmcnt(5)
	v_pk_fma_f32 v[54:55], v[80:81], v[26:27], v[54:55] neg_lo:[1,0,0] neg_hi:[1,0,0]
	v_pk_fma_f32 v[56:57], v[84:85], v[26:27], v[56:57] neg_lo:[1,0,0] neg_hi:[1,0,0]
	v_pk_fma_f32 v[54:55], v[82:83], v[28:29], v[54:55] neg_lo:[1,0,0] neg_hi:[1,0,0]
	v_pk_fma_f32 v[56:57], v[86:87], v[28:29], v[56:57] neg_lo:[1,0,0] neg_hi:[1,0,0]
	ds_read_b128 v[76:79], v115 offset:16608
	ds_read_b128 v[80:83], v115 offset:16352
	s_waitcnt lgkmcnt(5)
	v_pk_fma_f32 v[54:55], v[88:89], v[30:31], v[54:55] neg_lo:[1,0,0] neg_hi:[1,0,0]
	v_pk_fma_f32 v[56:57], v[92:93], v[30:31], v[56:57] neg_lo:[1,0,0] neg_hi:[1,0,0]
	v_pk_fma_f32 v[54:55], v[90:91], v[32:33], v[54:55] neg_lo:[1,0,0] neg_hi:[1,0,0]
	v_pk_fma_f32 v[56:57], v[94:95], v[32:33], v[56:57] neg_lo:[1,0,0] neg_hi:[1,0,0]
	ds_read_b128 v[84:87], v115 offset:16624
	ds_read_b128 v[88:91], v115 offset:16368
	s_waitcnt lgkmcnt(5)
	v_pk_fma_f32 v[54:55], v[96:97], v[34:35], v[54:55] neg_lo:[1,0,0] neg_hi:[1,0,0]
	v_pk_fma_f32 v[56:57], v[68:69], v[34:35], v[56:57] neg_lo:[1,0,0] neg_hi:[1,0,0]
	v_pk_fma_f32 v[54:55], v[98:99], v[36:37], v[54:55] neg_lo:[1,0,0] neg_hi:[1,0,0]
	v_pk_fma_f32 v[56:57], v[70:71], v[36:37], v[56:57] neg_lo:[1,0,0] neg_hi:[1,0,0]
	ds_read_b128 v[92:95], v115 offset:16640
	ds_read_b128 v[96:99], v115 offset:16384
	s_waitcnt lgkmcnt(5)
	v_pk_fma_f32 v[54:55], v[72:73], v[38:39], v[54:55] neg_lo:[1,0,0] neg_hi:[1,0,0]
	v_pk_fma_f32 v[56:57], v[76:77], v[38:39], v[56:57] neg_lo:[1,0,0] neg_hi:[1,0,0]
	v_pk_fma_f32 v[54:55], v[74:75], v[40:41], v[54:55] neg_lo:[1,0,0] neg_hi:[1,0,0]
	v_pk_fma_f32 v[56:57], v[78:79], v[40:41], v[56:57] neg_lo:[1,0,0] neg_hi:[1,0,0]
	ds_read_b128 v[68:71], v115 offset:16656
	ds_read_b32 v72, v115 offset:16672
	s_waitcnt lgkmcnt(5)
	v_pk_fma_f32 v[54:55], v[80:81], v[42:43], v[54:55] neg_lo:[1,0,0] neg_hi:[1,0,0]
	v_pk_fma_f32 v[56:57], v[84:85], v[42:43], v[56:57] neg_lo:[1,0,0] neg_hi:[1,0,0]
	v_pk_fma_f32 v[54:55], v[82:83], v[44:45], v[54:55] neg_lo:[1,0,0] neg_hi:[1,0,0]
	v_pk_fma_f32 v[56:57], v[86:87], v[44:45], v[56:57] neg_lo:[1,0,0] neg_hi:[1,0,0]
	ds_read_b128 v[76:79], v115 offset:16736
	ds_read_b128 v[80:83], v115 offset:17008
	s_waitcnt lgkmcnt(5)
	v_pk_fma_f32 v[54:55], v[88:89], v[46:47], v[54:55] neg_lo:[1,0,0] neg_hi:[1,0,0]
	v_pk_fma_f32 v[56:57], v[92:93], v[46:47], v[56:57] neg_lo:[1,0,0] neg_hi:[1,0,0]
	v_pk_fma_f32 v[54:55], v[90:91], v[48:49], v[54:55] neg_lo:[1,0,0] neg_hi:[1,0,0]
	v_pk_fma_f32 v[56:57], v[94:95], v[48:49], v[56:57] neg_lo:[1,0,0] neg_hi:[1,0,0]
	ds_read_b128 v[84:87], v115 offset:16752
	ds_read_b128 v[88:91], v115 offset:17024
	s_waitcnt lgkmcnt(5)
; __device__ __forceinline__ void gdn_chunk_prep(Frame& F) {
;     ...
;             for (int i = 50; i < 64; i += 2) {
;                 float a = (i == lane) ? 1.f : 0.f, bq = (i + 1 == lane) ? 1.f : 0.f;
; #pragma unroll
;                 for (int j = 0; j < i; ++j) { a = fmaf(-Amat[i * 68 + j], T[j], a); bq = fmaf(-Amat[(i + 1) * 68 + j], T[j], bq); }
;                 T[i] = a;
;                 T[i + 1] = fmaf(-Amat[(i + 1) * 68 + i], a, bq);
;                 asm volatile("" ::: "memory");
;             }
	v_pk_fma_f32 v[54:55], v[96:97], v[50:51], v[54:55] neg_lo:[1,0,0] neg_hi:[1,0,0]
	v_pk_fma_f32 v[56:57], v[68:69], v[50:51], v[56:57] neg_lo:[1,0,0] neg_hi:[1,0,0]
	v_pk_fma_f32 v[54:55], v[98:99], v[52:53], v[54:55] neg_lo:[1,0,0] neg_hi:[1,0,0]
	v_pk_fma_f32 v[56:57], v[70:71], v[52:53], v[56:57] neg_lo:[1,0,0] neg_hi:[1,0,0]
	ds_read_b128 v[92:95], v115 offset:16768
	ds_read_b128 v[96:99], v115 offset:17040
	s_waitcnt lgkmcnt(6)
	ds_read_b128 v[68:71], v115 offset:16784
	v_add_f32_e32 v54, v54, v55
	v_add_f32_e32 v56, v56, v57
	v_fma_f32 v55, -v72, v54, v56
	v_cmp_eq_u32_e32 vcc, 54, v127
	v_mov_b32_e32 v57, 0
	v_mov_b32_e32 v59, 0
	v_cndmask_b32_e64 v56, 0, 1.0, vcc
	v_cmp_eq_u32_e32 vcc, 55, v127
	s_nop 1
	v_cndmask_b32_e64 v58, 0, 1.0, vcc
	s_waitcnt lgkmcnt(5)
	v_pk_fma_f32 v[56:57], v[76:77], v[2:3], v[56:57] neg_lo:[1,0,0] neg_hi:[1,0,0]
	v_pk_fma_f32 v[58:59], v[80:81], v[2:3], v[58:59] neg_lo:[1,0,0] neg_hi:[1,0,0]
	v_pk_fma_f32 v[56:57], v[78:79], v[4:5], v[56:57] neg_lo:[1,0,0] neg_hi:[1,0,0]
	v_pk_fma_f32 v[58:59], v[82:83], v[4:5], v[58:59] neg_lo:[1,0,0] neg_hi:[1,0,0]
	ds_read_b128 v[72:75], v115 offset:17056
	ds_read_b128 v[76:79], v115 offset:16800
	s_waitcnt lgkmcnt(5)
	v_pk_fma_f32 v[56:57], v[84:85], v[6:7], v[56:57] neg_lo:[1,0,0] neg_hi:[1,0,0]
	v_pk_fma_f32 v[58:59], v[88:89], v[6:7], v[58:59] neg_lo:[1,0,0] neg_hi:[1,0,0]
	v_pk_fma_f32 v[56:57], v[86:87], v[8:9], v[56:57] neg_lo:[1,0,0] neg_hi:[1,0,0]
	v_pk_fma_f32 v[58:59], v[90:91], v[8:9], v[58:59] neg_lo:[1,0,0] neg_hi:[1,0,0]
	ds_read_b128 v[80:83], v115 offset:17072
	ds_read_b128 v[84:87], v115 offset:16816
	s_waitcnt lgkmcnt(5)
	v_pk_fma_f32 v[56:57], v[92:93], v[10:11], v[56:57] neg_lo:[1,0,0] neg_hi:[1,0,0]
	v_pk_fma_f32 v[58:59], v[96:97], v[10:11], v[58:59] neg_lo:[1,0,0] neg_hi:[1,0,0]
	v_pk_fma_f32 v[56:57], v[94:95], v[12:13], v[56:57] neg_lo:[1,0,0] neg_hi:[1,0,0]
	v_pk_fma_f32 v[58:59], v[98:99], v[12:13], v[58:59] neg_lo:[1,0,0] neg_hi:[1,0,0]
	ds_read_b128 v[88:91], v115 offset:17088
	ds_read_b128 v[92:95], v115 offset:16832
	s_waitcnt lgkmcnt(5)
	v_pk_fma_f32 v[56:57], v[68:69], v[14:15], v[56:57] neg_lo:[1,0,0] neg_hi:[1,0,0]
	v_pk_fma_f32 v[58:59], v[72:73], v[14:15], v[58:59] neg_lo:[1,0,0] neg_hi:[1,0,0]
	v_pk_fma_f32 v[56:57], v[70:71], v[16:17], v[56:57] neg_lo:[1,0,0] neg_hi:[1,0,0]
	v_pk_fma_f32 v[58:59], v[74:75], v[16:17], v[58:59] neg_lo:[1,0,0] neg_hi:[1,0,0]
	ds_read_b128 v[96:99], v115 offset:17104
	ds_read_b128 v[68:71], v115 offset:16848
	s_waitcnt lgkmcnt(5)
	v_pk_fma_f32 v[56:57], v[76:77], v[18:19], v[56:57] neg_lo:[1,0,0] neg_hi:[1,0,0]
	v_pk_fma_f32 v[58:59], v[80:81], v[18:19], v[58:59] neg_lo:[1,0,0] neg_hi:[1,0,0]
	v_pk_fma_f32 v[56:57], v[78:79], v[20:21], v[56:57] neg_lo:[1,0,0] neg_hi:[1,0,0]
	v_pk_fma_f32 v[58:59], v[82:83], v[20:21], v[58:59] neg_lo:[1,0,0] neg_hi:[1,0,0]
	ds_read_b128 v[72:75], v115 offset:17120
	ds_read_b128 v[76:79], v115 offset:16864
	s_waitcnt lgkmcnt(5)
	v_pk_fma_f32 v[56:57], v[84:85], v[22:23], v[56:57] neg_lo:[1,0,0] neg_hi:[1,0,0]
	v_pk_fma_f32 v[58:59], v[88:89], v[22:23], v[58:59] neg_lo:[1,0,0] neg_hi:[1,0,0]
	v_pk_fma_f32 v[56:57], v[86:87], v[24:25], v[56:57] neg_lo:[1,0,0] neg_hi:[1,0,0]
	v_pk_fma_f32 v[58:59], v[90:91], v[24:25], v[58:59] neg_lo:[1,0,0] neg_hi:[1,0,0]
	ds_read_b128 v[80:83], v115 offset:17136
	ds_read_b128 v[84:87], v115 offset:16880
	s_waitcnt lgkmcnt(5)
	v_pk_fma_f32 v[56:57], v[92:93], v[26:27], v[56:57] neg_lo:[1,0,0] neg_hi:[1,0,0]
	v_pk_fma_f32 v[58:59], v[96:97], v[26:27], v[58:59] neg_lo:[1,0,0] neg_hi:[1,0,0]
	v_pk_fma_f32 v[56:57], v[94:95], v[28:29], v[56:57] neg_lo:[1,0,0] neg_hi:[1,0,0]
	v_pk_fma_f32 v[58:59], v[98:99], v[28:29], v[58:59] neg_lo:[1,0,0] neg_hi:[1,0,0]
	ds_read_b128 v[88:91], v115 offset:17152
	ds_read_b128 v[92:95], v115 offset:16896
	s_waitcnt lgkmcnt(5)
	v_pk_fma_f32 v[56:57], v[68:69], v[30:31], v[56:57] neg_lo:[1,0,0] neg_hi:[1,0,0]
	v_pk_fma_f32 v[58:59], v[72:73], v[30:31], v[58:59] neg_lo:[1,0,0] neg_hi:[1,0,0]
	v_pk_fma_f32 v[56:57], v[70:71], v[32:33], v[56:57] neg_lo:[1,0,0] neg_hi:[1,0,0]
	v_pk_fma_f32 v[58:59], v[74:75], v[32:33], v[58:59] neg_lo:[1,0,0] neg_hi:[1,0,0]
	ds_read_b128 v[96:99], v115 offset:17168
	ds_read_b128 v[68:71], v115 offset:16912
	s_waitcnt lgkmcnt(5)
	v_pk_fma_f32 v[56:57], v[76:77], v[34:35], v[56:57] neg_lo:[1,0,0] neg_hi:[1,0,0]
	v_pk_fma_f32 v[58:59], v[80:81], v[34:35], v[58:59] neg_lo:[1,0,0] neg_hi:[1,0,0]
	v_pk_fma_f32 v[56:57], v[78:79], v[36:37], v[56:57] neg_lo:[1,0,0] neg_hi:[1,0,0]
	v_pk_fma_f32 v[58:59], v[82:83], v[36:37], v[58:59] neg_lo:[1,0,0] neg_hi:[1,0,0]
	ds_read_b128 v[72:75], v115 offset:17184
	ds_read_b128 v[76:79], v115 offset:16928
	s_waitcnt lgkmcnt(5)
	v_pk_fma_f32 v[56:57], v[84:85], v[38:39], v[56:57] neg_lo:[1,0,0] neg_hi:[1,0,0]
	v_pk_fma_f32 v[58:59], v[88:89], v[38:39], v[58:59] neg_lo:[1,0,0] neg_hi:[1,0,0]
	v_pk_fma_f32 v[56:57], v[86:87], v[40:41], v[56:57] neg_lo:[1,0,0] neg_hi:[1,0,0]
	v_pk_fma_f32 v[58:59], v[90:91], v[40:41], v[58:59] neg_lo:[1,0,0] neg_hi:[1,0,0]
	ds_read_b128 v[80:83], v115 offset:17200
	ds_read_b128 v[84:87], v115 offset:16944
	s_waitcnt lgkmcnt(5)
	v_pk_fma_f32 v[56:57], v[92:93], v[42:43], v[56:57] neg_lo:[1,0,0] neg_hi:[1,0,0]
	v_pk_fma_f32 v[58:59], v[96:97], v[42:43], v[58:59] neg_lo:[1,0,0] neg_hi:[1,0,0]
	v_pk_fma_f32 v[56:57], v[94:95], v[44:45], v[56:57] neg_lo:[1,0,0] neg_hi:[1,0,0]
	v_pk_fma_f32 v[58:59], v[98:99], v[44:45], v[58:59] neg_lo:[1,0,0] neg_hi:[1,0,0]
	ds_read_b128 v[88:91], v115 offset:17216
	ds_read_b128 v[92:95], v115 offset:17280
	s_waitcnt lgkmcnt(5)
; __device__ __forceinline__ void gdn_chunk_prep(Frame& F) {
;     ...
;             for (int i = 50; i < 64; i += 2) {
;                 float a = (i == lane) ? 1.f : 0.f, bq = (i + 1 == lane) ? 1.f : 0.f;
; #pragma unroll
;                 for (int j = 0; j < i; ++j) { a = fmaf(-Amat[i * 68 + j], T[j], a); bq = fmaf(-Amat[(i + 1) * 68 + j], T[j], bq); }
;                 T[i] = a;
;                 T[i + 1] = fmaf(-Amat[(i + 1) * 68 + i], a, bq);
;                 asm volatile("" ::: "memory");
;             }
	v_pk_fma_f32 v[56:57], v[68:69], v[46:47], v[56:57] neg_lo:[1,0,0] neg_hi:[1,0,0]
	v_pk_fma_f32 v[58:59], v[72:73], v[46:47], v[58:59] neg_lo:[1,0,0] neg_hi:[1,0,0]
	v_pk_fma_f32 v[56:57], v[70:71], v[48:49], v[56:57] neg_lo:[1,0,0] neg_hi:[1,0,0]
	v_pk_fma_f32 v[58:59], v[74:75], v[48:49], v[58:59] neg_lo:[1,0,0] neg_hi:[1,0,0]
	ds_read_b128 v[96:99], v115 offset:17552
	ds_read_b128 v[68:71], v115 offset:17296
	s_waitcnt lgkmcnt(5)
	v_pk_fma_f32 v[56:57], v[76:77], v[50:51], v[56:57] neg_lo:[1,0,0] neg_hi:[1,0,0]
	v_pk_fma_f32 v[58:59], v[80:81], v[50:51], v[58:59] neg_lo:[1,0,0] neg_hi:[1,0,0]
	v_pk_fma_f32 v[56:57], v[78:79], v[52:53], v[56:57] neg_lo:[1,0,0] neg_hi:[1,0,0]
	v_pk_fma_f32 v[58:59], v[82:83], v[52:53], v[58:59] neg_lo:[1,0,0] neg_hi:[1,0,0]
	ds_read_b128 v[72:75], v115 offset:17568
	ds_read_b128 v[76:79], v115 offset:17312
	s_waitcnt lgkmcnt(5)
	v_pk_fma_f32 v[56:57], v[84:85], v[54:55], v[56:57] neg_lo:[1,0,0] neg_hi:[1,0,0]
	v_pk_fma_f32 v[58:59], v[88:89], v[54:55], v[58:59] neg_lo:[1,0,0] neg_hi:[1,0,0]
	ds_read_b128 v[80:83], v115 offset:17584
	ds_read_b128 v[84:87], v115 offset:17328
	v_add_f32_e32 v56, v56, v57
	v_add_f32_e32 v58, v58, v59
	v_fma_f32 v57, -v90, v56, v58
	v_cmp_eq_u32_e32 vcc, 56, v127
	v_mov_b32_e32 v59, 0
	v_mov_b32_e32 v61, 0
	v_cndmask_b32_e64 v58, 0, 1.0, vcc
	v_cmp_eq_u32_e32 vcc, 57, v127
	s_nop 1
	v_cndmask_b32_e64 v60, 0, 1.0, vcc
	s_waitcnt lgkmcnt(5)
	v_pk_fma_f32 v[58:59], v[92:93], v[2:3], v[58:59] neg_lo:[1,0,0] neg_hi:[1,0,0]
	v_pk_fma_f32 v[60:61], v[96:97], v[2:3], v[60:61] neg_lo:[1,0,0] neg_hi:[1,0,0]
	v_pk_fma_f32 v[58:59], v[94:95], v[4:5], v[58:59] neg_lo:[1,0,0] neg_hi:[1,0,0]
	v_pk_fma_f32 v[60:61], v[98:99], v[4:5], v[60:61] neg_lo:[1,0,0] neg_hi:[1,0,0]
	ds_read_b128 v[88:91], v115 offset:17600
	ds_read_b128 v[92:95], v115 offset:17344
	s_waitcnt lgkmcnt(5)
	v_pk_fma_f32 v[58:59], v[68:69], v[6:7], v[58:59] neg_lo:[1,0,0] neg_hi:[1,0,0]
	v_pk_fma_f32 v[60:61], v[72:73], v[6:7], v[60:61] neg_lo:[1,0,0] neg_hi:[1,0,0]
	v_pk_fma_f32 v[58:59], v[70:71], v[8:9], v[58:59] neg_lo:[1,0,0] neg_hi:[1,0,0]
	v_pk_fma_f32 v[60:61], v[74:75], v[8:9], v[60:61] neg_lo:[1,0,0] neg_hi:[1,0,0]
	ds_read_b128 v[96:99], v115 offset:17616
	ds_read_b128 v[68:71], v115 offset:17360
	s_waitcnt lgkmcnt(5)
	v_pk_fma_f32 v[58:59], v[76:77], v[10:11], v[58:59] neg_lo:[1,0,0] neg_hi:[1,0,0]
	v_pk_fma_f32 v[60:61], v[80:81], v[10:11], v[60:61] neg_lo:[1,0,0] neg_hi:[1,0,0]
	v_pk_fma_f32 v[58:59], v[78:79], v[12:13], v[58:59] neg_lo:[1,0,0] neg_hi:[1,0,0]
	v_pk_fma_f32 v[60:61], v[82:83], v[12:13], v[60:61] neg_lo:[1,0,0] neg_hi:[1,0,0]
	ds_read_b128 v[72:75], v115 offset:17632
	ds_read_b128 v[76:79], v115 offset:17376
	s_waitcnt lgkmcnt(5)
	v_pk_fma_f32 v[58:59], v[84:85], v[14:15], v[58:59] neg_lo:[1,0,0] neg_hi:[1,0,0]
	v_pk_fma_f32 v[60:61], v[88:89], v[14:15], v[60:61] neg_lo:[1,0,0] neg_hi:[1,0,0]
	v_pk_fma_f32 v[58:59], v[86:87], v[16:17], v[58:59] neg_lo:[1,0,0] neg_hi:[1,0,0]
	v_pk_fma_f32 v[60:61], v[90:91], v[16:17], v[60:61] neg_lo:[1,0,0] neg_hi:[1,0,0]
	ds_read_b128 v[80:83], v115 offset:17648
	ds_read_b128 v[84:87], v115 offset:17392
	s_waitcnt lgkmcnt(5)
	v_pk_fma_f32 v[58:59], v[92:93], v[18:19], v[58:59] neg_lo:[1,0,0] neg_hi:[1,0,0]
	v_pk_fma_f32 v[60:61], v[96:97], v[18:19], v[60:61] neg_lo:[1,0,0] neg_hi:[1,0,0]
	v_pk_fma_f32 v[58:59], v[94:95], v[20:21], v[58:59] neg_lo:[1,0,0] neg_hi:[1,0,0]
	v_pk_fma_f32 v[60:61], v[98:99], v[20:21], v[60:61] neg_lo:[1,0,0] neg_hi:[1,0,0]
	ds_read_b128 v[88:91], v115 offset:17664
	ds_read_b128 v[92:95], v115 offset:17408
	s_waitcnt lgkmcnt(5)
	v_pk_fma_f32 v[58:59], v[68:69], v[22:23], v[58:59] neg_lo:[1,0,0] neg_hi:[1,0,0]
	v_pk_fma_f32 v[60:61], v[72:73], v[22:23], v[60:61] neg_lo:[1,0,0] neg_hi:[1,0,0]
	v_pk_fma_f32 v[58:59], v[70:71], v[24:25], v[58:59] neg_lo:[1,0,0] neg_hi:[1,0,0]
	v_pk_fma_f32 v[60:61], v[74:75], v[24:25], v[60:61] neg_lo:[1,0,0] neg_hi:[1,0,0]
	ds_read_b128 v[96:99], v115 offset:17680
	ds_read_b128 v[68:71], v115 offset:17424
	s_waitcnt lgkmcnt(5)
	v_pk_fma_f32 v[58:59], v[76:77], v[26:27], v[58:59] neg_lo:[1,0,0] neg_hi:[1,0,0]
	v_pk_fma_f32 v[60:61], v[80:81], v[26:27], v[60:61] neg_lo:[1,0,0] neg_hi:[1,0,0]
	v_pk_fma_f32 v[58:59], v[78:79], v[28:29], v[58:59] neg_lo:[1,0,0] neg_hi:[1,0,0]
	v_pk_fma_f32 v[60:61], v[82:83], v[28:29], v[60:61] neg_lo:[1,0,0] neg_hi:[1,0,0]
	ds_read_b128 v[72:75], v115 offset:17696
	ds_read_b128 v[76:79], v115 offset:17440
	s_waitcnt lgkmcnt(5)
	v_pk_fma_f32 v[58:59], v[84:85], v[30:31], v[58:59] neg_lo:[1,0,0] neg_hi:[1,0,0]
	v_pk_fma_f32 v[60:61], v[88:89], v[30:31], v[60:61] neg_lo:[1,0,0] neg_hi:[1,0,0]
	v_pk_fma_f32 v[58:59], v[86:87], v[32:33], v[58:59] neg_lo:[1,0,0] neg_hi:[1,0,0]
	v_pk_fma_f32 v[60:61], v[90:91], v[32:33], v[60:61] neg_lo:[1,0,0] neg_hi:[1,0,0]
	ds_read_b128 v[80:83], v115 offset:17712
	ds_read_b128 v[84:87], v115 offset:17456
	s_waitcnt lgkmcnt(5)
	v_pk_fma_f32 v[58:59], v[92:93], v[34:35], v[58:59] neg_lo:[1,0,0] neg_hi:[1,0,0]
	v_pk_fma_f32 v[60:61], v[96:97], v[34:35], v[60:61] neg_lo:[1,0,0] neg_hi:[1,0,0]
	v_pk_fma_f32 v[58:59], v[94:95], v[36:37], v[58:59] neg_lo:[1,0,0] neg_hi:[1,0,0]
	v_pk_fma_f32 v[60:61], v[98:99], v[36:37], v[60:61] neg_lo:[1,0,0] neg_hi:[1,0,0]
	ds_read_b128 v[88:91], v115 offset:17728
	ds_read_b128 v[92:95], v115 offset:17472
	s_waitcnt lgkmcnt(5)
	v_pk_fma_f32 v[58:59], v[68:69], v[38:39], v[58:59] neg_lo:[1,0,0] neg_hi:[1,0,0]
	v_pk_fma_f32 v[60:61], v[72:73], v[38:39], v[60:61] neg_lo:[1,0,0] neg_hi:[1,0,0]
	v_pk_fma_f32 v[58:59], v[70:71], v[40:41], v[58:59] neg_lo:[1,0,0] neg_hi:[1,0,0]
	v_pk_fma_f32 v[60:61], v[74:75], v[40:41], v[60:61] neg_lo:[1,0,0] neg_hi:[1,0,0]
	ds_read_b128 v[96:99], v115 offset:17744
	ds_read_b128 v[68:71], v115 offset:17488
	s_waitcnt lgkmcnt(5)
; __device__ __forceinline__ void gdn_chunk_prep(Frame& F) {
;     ...
;             for (int i = 50; i < 64; i += 2) {
;                 float a = (i == lane) ? 1.f : 0.f, bq = (i + 1 == lane) ? 1.f : 0.f;
; #pragma unroll
;                 for (int j = 0; j < i; ++j) { a = fmaf(-Amat[i * 68 + j], T[j], a); bq = fmaf(-Amat[(i + 1) * 68 + j], T[j], bq); }
;                 T[i] = a;
;                 T[i + 1] = fmaf(-Amat[(i + 1) * 68 + i], a, bq);
;                 asm volatile("" ::: "memory");
;             }
	v_pk_fma_f32 v[58:59], v[76:77], v[42:43], v[58:59] neg_lo:[1,0,0] neg_hi:[1,0,0]
	v_pk_fma_f32 v[60:61], v[80:81], v[42:43], v[60:61] neg_lo:[1,0,0] neg_hi:[1,0,0]
	v_pk_fma_f32 v[58:59], v[78:79], v[44:45], v[58:59] neg_lo:[1,0,0] neg_hi:[1,0,0]
	v_pk_fma_f32 v[60:61], v[82:83], v[44:45], v[60:61] neg_lo:[1,0,0] neg_hi:[1,0,0]
	ds_read_b128 v[72:75], v115 offset:17760
	ds_read_b32 v76, v115 offset:17776
	s_waitcnt lgkmcnt(5)
	v_pk_fma_f32 v[58:59], v[84:85], v[46:47], v[58:59] neg_lo:[1,0,0] neg_hi:[1,0,0]
	v_pk_fma_f32 v[60:61], v[88:89], v[46:47], v[60:61] neg_lo:[1,0,0] neg_hi:[1,0,0]
	v_pk_fma_f32 v[58:59], v[86:87], v[48:49], v[58:59] neg_lo:[1,0,0] neg_hi:[1,0,0]
	v_pk_fma_f32 v[60:61], v[90:91], v[48:49], v[60:61] neg_lo:[1,0,0] neg_hi:[1,0,0]
	ds_read_b128 v[80:83], v115 offset:17824
	ds_read_b128 v[84:87], v115 offset:18096
	s_waitcnt lgkmcnt(5)
	v_pk_fma_f32 v[58:59], v[92:93], v[50:51], v[58:59] neg_lo:[1,0,0] neg_hi:[1,0,0]
	v_pk_fma_f32 v[60:61], v[96:97], v[50:51], v[60:61] neg_lo:[1,0,0] neg_hi:[1,0,0]
	v_pk_fma_f32 v[58:59], v[94:95], v[52:53], v[58:59] neg_lo:[1,0,0] neg_hi:[1,0,0]
	v_pk_fma_f32 v[60:61], v[98:99], v[52:53], v[60:61] neg_lo:[1,0,0] neg_hi:[1,0,0]
	ds_read_b128 v[88:91], v115 offset:17840
	ds_read_b128 v[92:95], v115 offset:18112
	s_waitcnt lgkmcnt(5)
	v_pk_fma_f32 v[58:59], v[68:69], v[54:55], v[58:59] neg_lo:[1,0,0] neg_hi:[1,0,0]
	v_pk_fma_f32 v[60:61], v[72:73], v[54:55], v[60:61] neg_lo:[1,0,0] neg_hi:[1,0,0]
	v_pk_fma_f32 v[58:59], v[70:71], v[56:57], v[58:59] neg_lo:[1,0,0] neg_hi:[1,0,0]
	v_pk_fma_f32 v[60:61], v[74:75], v[56:57], v[60:61] neg_lo:[1,0,0] neg_hi:[1,0,0]
	ds_read_b128 v[96:99], v115 offset:17856
	ds_read_b128 v[68:71], v115 offset:18128
	s_waitcnt lgkmcnt(6)
	ds_read_b128 v[72:75], v115 offset:17872
	v_add_f32_e32 v58, v58, v59
	v_add_f32_e32 v60, v60, v61
	v_fma_f32 v59, -v76, v58, v60
	v_cmp_eq_u32_e32 vcc, 58, v127
	v_mov_b32_e32 v61, 0
	v_mov_b32_e32 v63, 0
	v_cndmask_b32_e64 v60, 0, 1.0, vcc
	v_cmp_eq_u32_e32 vcc, 59, v127
	s_nop 1
	v_cndmask_b32_e64 v62, 0, 1.0, vcc
	s_waitcnt lgkmcnt(5)
	v_pk_fma_f32 v[60:61], v[80:81], v[2:3], v[60:61] neg_lo:[1,0,0] neg_hi:[1,0,0]
	v_pk_fma_f32 v[62:63], v[84:85], v[2:3], v[62:63] neg_lo:[1,0,0] neg_hi:[1,0,0]
	v_pk_fma_f32 v[60:61], v[82:83], v[4:5], v[60:61] neg_lo:[1,0,0] neg_hi:[1,0,0]
	v_pk_fma_f32 v[62:63], v[86:87], v[4:5], v[62:63] neg_lo:[1,0,0] neg_hi:[1,0,0]
	ds_read_b128 v[76:79], v115 offset:18144
	ds_read_b128 v[80:83], v115 offset:17888
	s_waitcnt lgkmcnt(5)
	v_pk_fma_f32 v[60:61], v[88:89], v[6:7], v[60:61] neg_lo:[1,0,0] neg_hi:[1,0,0]
	v_pk_fma_f32 v[62:63], v[92:93], v[6:7], v[62:63] neg_lo:[1,0,0] neg_hi:[1,0,0]
	v_pk_fma_f32 v[60:61], v[90:91], v[8:9], v[60:61] neg_lo:[1,0,0] neg_hi:[1,0,0]
	v_pk_fma_f32 v[62:63], v[94:95], v[8:9], v[62:63] neg_lo:[1,0,0] neg_hi:[1,0,0]
	ds_read_b128 v[84:87], v115 offset:18160
	ds_read_b128 v[88:91], v115 offset:17904
	s_waitcnt lgkmcnt(5)
	v_pk_fma_f32 v[60:61], v[96:97], v[10:11], v[60:61] neg_lo:[1,0,0] neg_hi:[1,0,0]
	v_pk_fma_f32 v[62:63], v[68:69], v[10:11], v[62:63] neg_lo:[1,0,0] neg_hi:[1,0,0]
	v_pk_fma_f32 v[60:61], v[98:99], v[12:13], v[60:61] neg_lo:[1,0,0] neg_hi:[1,0,0]
	v_pk_fma_f32 v[62:63], v[70:71], v[12:13], v[62:63] neg_lo:[1,0,0] neg_hi:[1,0,0]
	ds_read_b128 v[92:95], v115 offset:18176
	ds_read_b128 v[96:99], v115 offset:17920
	s_waitcnt lgkmcnt(5)
	v_pk_fma_f32 v[60:61], v[72:73], v[14:15], v[60:61] neg_lo:[1,0,0] neg_hi:[1,0,0]
	v_pk_fma_f32 v[62:63], v[76:77], v[14:15], v[62:63] neg_lo:[1,0,0] neg_hi:[1,0,0]
	v_pk_fma_f32 v[60:61], v[74:75], v[16:17], v[60:61] neg_lo:[1,0,0] neg_hi:[1,0,0]
	v_pk_fma_f32 v[62:63], v[78:79], v[16:17], v[62:63] neg_lo:[1,0,0] neg_hi:[1,0,0]
	ds_read_b128 v[68:71], v115 offset:18192
	ds_read_b128 v[72:75], v115 offset:17936
	s_waitcnt lgkmcnt(5)
	v_pk_fma_f32 v[60:61], v[80:81], v[18:19], v[60:61] neg_lo:[1,0,0] neg_hi:[1,0,0]
	v_pk_fma_f32 v[62:63], v[84:85], v[18:19], v[62:63] neg_lo:[1,0,0] neg_hi:[1,0,0]
	v_pk_fma_f32 v[60:61], v[82:83], v[20:21], v[60:61] neg_lo:[1,0,0] neg_hi:[1,0,0]
	v_pk_fma_f32 v[62:63], v[86:87], v[20:21], v[62:63] neg_lo:[1,0,0] neg_hi:[1,0,0]
	ds_read_b128 v[76:79], v115 offset:18208
	ds_read_b128 v[80:83], v115 offset:17952
	s_waitcnt lgkmcnt(5)
	v_pk_fma_f32 v[60:61], v[88:89], v[22:23], v[60:61] neg_lo:[1,0,0] neg_hi:[1,0,0]
	v_pk_fma_f32 v[62:63], v[92:93], v[22:23], v[62:63] neg_lo:[1,0,0] neg_hi:[1,0,0]
	v_pk_fma_f32 v[60:61], v[90:91], v[24:25], v[60:61] neg_lo:[1,0,0] neg_hi:[1,0,0]
	v_pk_fma_f32 v[62:63], v[94:95], v[24:25], v[62:63] neg_lo:[1,0,0] neg_hi:[1,0,0]
	ds_read_b128 v[84:87], v115 offset:18224
	ds_read_b128 v[88:91], v115 offset:17968
	s_waitcnt lgkmcnt(5)
	v_pk_fma_f32 v[60:61], v[96:97], v[26:27], v[60:61] neg_lo:[1,0,0] neg_hi:[1,0,0]
	v_pk_fma_f32 v[62:63], v[68:69], v[26:27], v[62:63] neg_lo:[1,0,0] neg_hi:[1,0,0]
	v_pk_fma_f32 v[60:61], v[98:99], v[28:29], v[60:61] neg_lo:[1,0,0] neg_hi:[1,0,0]
	v_pk_fma_f32 v[62:63], v[70:71], v[28:29], v[62:63] neg_lo:[1,0,0] neg_hi:[1,0,0]
	ds_read_b128 v[92:95], v115 offset:18240
	ds_read_b128 v[96:99], v115 offset:17984
	s_waitcnt lgkmcnt(5)
	v_pk_fma_f32 v[60:61], v[72:73], v[30:31], v[60:61] neg_lo:[1,0,0] neg_hi:[1,0,0]
	v_pk_fma_f32 v[62:63], v[76:77], v[30:31], v[62:63] neg_lo:[1,0,0] neg_hi:[1,0,0]
	v_pk_fma_f32 v[60:61], v[74:75], v[32:33], v[60:61] neg_lo:[1,0,0] neg_hi:[1,0,0]
	v_pk_fma_f32 v[62:63], v[78:79], v[32:33], v[62:63] neg_lo:[1,0,0] neg_hi:[1,0,0]
	ds_read_b128 v[68:71], v115 offset:18256
	ds_read_b128 v[72:75], v115 offset:18000
	s_waitcnt lgkmcnt(5)
; __device__ __forceinline__ void gdn_chunk_prep(Frame& F) {
;     ...
;             for (int i = 50; i < 64; i += 2) {
;                 float a = (i == lane) ? 1.f : 0.f, bq = (i + 1 == lane) ? 1.f : 0.f;
; #pragma unroll
;                 for (int j = 0; j < i; ++j) { a = fmaf(-Amat[i * 68 + j], T[j], a); bq = fmaf(-Amat[(i + 1) * 68 + j], T[j], bq); }
;                 T[i] = a;
;                 T[i + 1] = fmaf(-Amat[(i + 1) * 68 + i], a, bq);
;                 asm volatile("" ::: "memory");
;             }
	v_pk_fma_f32 v[60:61], v[80:81], v[34:35], v[60:61] neg_lo:[1,0,0] neg_hi:[1,0,0]
	v_pk_fma_f32 v[62:63], v[84:85], v[34:35], v[62:63] neg_lo:[1,0,0] neg_hi:[1,0,0]
	v_pk_fma_f32 v[60:61], v[82:83], v[36:37], v[60:61] neg_lo:[1,0,0] neg_hi:[1,0,0]
	v_pk_fma_f32 v[62:63], v[86:87], v[36:37], v[62:63] neg_lo:[1,0,0] neg_hi:[1,0,0]
	ds_read_b128 v[76:79], v115 offset:18272
	ds_read_b128 v[80:83], v115 offset:18016
	s_waitcnt lgkmcnt(5)
	v_pk_fma_f32 v[60:61], v[88:89], v[38:39], v[60:61] neg_lo:[1,0,0] neg_hi:[1,0,0]
	v_pk_fma_f32 v[62:63], v[92:93], v[38:39], v[62:63] neg_lo:[1,0,0] neg_hi:[1,0,0]
	v_pk_fma_f32 v[60:61], v[90:91], v[40:41], v[60:61] neg_lo:[1,0,0] neg_hi:[1,0,0]
	v_pk_fma_f32 v[62:63], v[94:95], v[40:41], v[62:63] neg_lo:[1,0,0] neg_hi:[1,0,0]
	ds_read_b128 v[84:87], v115 offset:18288
	ds_read_b128 v[88:91], v115 offset:18032
	s_waitcnt lgkmcnt(5)
	v_pk_fma_f32 v[60:61], v[96:97], v[42:43], v[60:61] neg_lo:[1,0,0] neg_hi:[1,0,0]
	v_pk_fma_f32 v[62:63], v[68:69], v[42:43], v[62:63] neg_lo:[1,0,0] neg_hi:[1,0,0]
	v_pk_fma_f32 v[60:61], v[98:99], v[44:45], v[60:61] neg_lo:[1,0,0] neg_hi:[1,0,0]
	v_pk_fma_f32 v[62:63], v[70:71], v[44:45], v[62:63] neg_lo:[1,0,0] neg_hi:[1,0,0]
	ds_read_b128 v[92:95], v115 offset:18304
	ds_read_b128 v[96:99], v115 offset:18048
	s_waitcnt lgkmcnt(5)
	v_pk_fma_f32 v[60:61], v[72:73], v[46:47], v[60:61] neg_lo:[1,0,0] neg_hi:[1,0,0]
	v_pk_fma_f32 v[62:63], v[76:77], v[46:47], v[62:63] neg_lo:[1,0,0] neg_hi:[1,0,0]
	v_pk_fma_f32 v[60:61], v[74:75], v[48:49], v[60:61] neg_lo:[1,0,0] neg_hi:[1,0,0]
	v_pk_fma_f32 v[62:63], v[78:79], v[48:49], v[62:63] neg_lo:[1,0,0] neg_hi:[1,0,0]
	ds_read_b128 v[68:71], v115 offset:18320
	ds_read_b128 v[72:75], v115 offset:18368
	s_waitcnt lgkmcnt(5)
	v_pk_fma_f32 v[60:61], v[80:81], v[50:51], v[60:61] neg_lo:[1,0,0] neg_hi:[1,0,0]
	v_pk_fma_f32 v[62:63], v[84:85], v[50:51], v[62:63] neg_lo:[1,0,0] neg_hi:[1,0,0]
	v_pk_fma_f32 v[60:61], v[82:83], v[52:53], v[60:61] neg_lo:[1,0,0] neg_hi:[1,0,0]
	v_pk_fma_f32 v[62:63], v[86:87], v[52:53], v[62:63] neg_lo:[1,0,0] neg_hi:[1,0,0]
	ds_read_b128 v[76:79], v115 offset:18640
	ds_read_b128 v[80:83], v115 offset:18384
	s_waitcnt lgkmcnt(5)
	v_pk_fma_f32 v[60:61], v[88:89], v[54:55], v[60:61] neg_lo:[1,0,0] neg_hi:[1,0,0]
	v_pk_fma_f32 v[62:63], v[92:93], v[54:55], v[62:63] neg_lo:[1,0,0] neg_hi:[1,0,0]
	v_pk_fma_f32 v[60:61], v[90:91], v[56:57], v[60:61] neg_lo:[1,0,0] neg_hi:[1,0,0]
	v_pk_fma_f32 v[62:63], v[94:95], v[56:57], v[62:63] neg_lo:[1,0,0] neg_hi:[1,0,0]
	ds_read_b128 v[84:87], v115 offset:18656
	ds_read_b128 v[88:91], v115 offset:18400
	s_waitcnt lgkmcnt(5)
	v_pk_fma_f32 v[60:61], v[96:97], v[58:59], v[60:61] neg_lo:[1,0,0] neg_hi:[1,0,0]
	v_pk_fma_f32 v[62:63], v[68:69], v[58:59], v[62:63] neg_lo:[1,0,0] neg_hi:[1,0,0]
	ds_read_b128 v[92:95], v115 offset:18672
	ds_read_b128 v[96:99], v115 offset:18416
	v_add_f32_e32 v60, v60, v61
	v_add_f32_e32 v62, v62, v63
	v_fma_f32 v61, -v70, v60, v62
	v_cmp_eq_u32_e32 vcc, 60, v127
	v_mov_b32_e32 v63, 0
	v_mov_b32_e32 v65, 0
	v_cndmask_b32_e64 v62, 0, 1.0, vcc
	v_cmp_eq_u32_e32 vcc, 61, v127
	s_nop 1
	v_cndmask_b32_e64 v64, 0, 1.0, vcc
	s_waitcnt lgkmcnt(5)
	v_pk_fma_f32 v[62:63], v[72:73], v[2:3], v[62:63] neg_lo:[1,0,0] neg_hi:[1,0,0]
	v_pk_fma_f32 v[64:65], v[76:77], v[2:3], v[64:65] neg_lo:[1,0,0] neg_hi:[1,0,0]
	v_pk_fma_f32 v[62:63], v[74:75], v[4:5], v[62:63] neg_lo:[1,0,0] neg_hi:[1,0,0]
	v_pk_fma_f32 v[64:65], v[78:79], v[4:5], v[64:65] neg_lo:[1,0,0] neg_hi:[1,0,0]
	ds_read_b128 v[68:71], v115 offset:18688
	ds_read_b128 v[72:75], v115 offset:18432
	s_waitcnt lgkmcnt(5)
	v_pk_fma_f32 v[62:63], v[80:81], v[6:7], v[62:63] neg_lo:[1,0,0] neg_hi:[1,0,0]
	v_pk_fma_f32 v[64:65], v[84:85], v[6:7], v[64:65] neg_lo:[1,0,0] neg_hi:[1,0,0]
	v_pk_fma_f32 v[62:63], v[82:83], v[8:9], v[62:63] neg_lo:[1,0,0] neg_hi:[1,0,0]
	v_pk_fma_f32 v[64:65], v[86:87], v[8:9], v[64:65] neg_lo:[1,0,0] neg_hi:[1,0,0]
	ds_read_b128 v[76:79], v115 offset:18704
	ds_read_b128 v[80:83], v115 offset:18448
	s_waitcnt lgkmcnt(5)
	v_pk_fma_f32 v[62:63], v[88:89], v[10:11], v[62:63] neg_lo:[1,0,0] neg_hi:[1,0,0]
	v_pk_fma_f32 v[64:65], v[92:93], v[10:11], v[64:65] neg_lo:[1,0,0] neg_hi:[1,0,0]
	v_pk_fma_f32 v[62:63], v[90:91], v[12:13], v[62:63] neg_lo:[1,0,0] neg_hi:[1,0,0]
	v_pk_fma_f32 v[64:65], v[94:95], v[12:13], v[64:65] neg_lo:[1,0,0] neg_hi:[1,0,0]
	ds_read_b128 v[84:87], v115 offset:18720
	ds_read_b128 v[88:91], v115 offset:18464
	s_waitcnt lgkmcnt(5)
	v_pk_fma_f32 v[62:63], v[96:97], v[14:15], v[62:63] neg_lo:[1,0,0] neg_hi:[1,0,0]
	v_pk_fma_f32 v[64:65], v[68:69], v[14:15], v[64:65] neg_lo:[1,0,0] neg_hi:[1,0,0]
	v_pk_fma_f32 v[62:63], v[98:99], v[16:17], v[62:63] neg_lo:[1,0,0] neg_hi:[1,0,0]
	v_pk_fma_f32 v[64:65], v[70:71], v[16:17], v[64:65] neg_lo:[1,0,0] neg_hi:[1,0,0]
	ds_read_b128 v[92:95], v115 offset:18736
	ds_read_b128 v[96:99], v115 offset:18480
	s_waitcnt lgkmcnt(5)
	v_pk_fma_f32 v[62:63], v[72:73], v[18:19], v[62:63] neg_lo:[1,0,0] neg_hi:[1,0,0]
	v_pk_fma_f32 v[64:65], v[76:77], v[18:19], v[64:65] neg_lo:[1,0,0] neg_hi:[1,0,0]
	v_pk_fma_f32 v[62:63], v[74:75], v[20:21], v[62:63] neg_lo:[1,0,0] neg_hi:[1,0,0]
	v_pk_fma_f32 v[64:65], v[78:79], v[20:21], v[64:65] neg_lo:[1,0,0] neg_hi:[1,0,0]
	ds_read_b128 v[68:71], v115 offset:18752
	ds_read_b128 v[72:75], v115 offset:18496
	s_waitcnt lgkmcnt(5)
	v_pk_fma_f32 v[62:63], v[80:81], v[22:23], v[62:63] neg_lo:[1,0,0] neg_hi:[1,0,0]
	v_pk_fma_f32 v[64:65], v[84:85], v[22:23], v[64:65] neg_lo:[1,0,0] neg_hi:[1,0,0]
	v_pk_fma_f32 v[62:63], v[82:83], v[24:25], v[62:63] neg_lo:[1,0,0] neg_hi:[1,0,0]
	v_pk_fma_f32 v[64:65], v[86:87], v[24:25], v[64:65] neg_lo:[1,0,0] neg_hi:[1,0,0]
	ds_read_b128 v[76:79], v115 offset:18768
	ds_read_b128 v[80:83], v115 offset:18512
	s_waitcnt lgkmcnt(5)
; __device__ __forceinline__ void gdn_chunk_prep(Frame& F) {
;     ...
;             for (int i = 50; i < 64; i += 2) {
;                 float a = (i == lane) ? 1.f : 0.f, bq = (i + 1 == lane) ? 1.f : 0.f;
; #pragma unroll
;                 for (int j = 0; j < i; ++j) { a = fmaf(-Amat[i * 68 + j], T[j], a); bq = fmaf(-Amat[(i + 1) * 68 + j], T[j], bq); }
;                 T[i] = a;
;                 T[i + 1] = fmaf(-Amat[(i + 1) * 68 + i], a, bq);
;                 asm volatile("" ::: "memory");
;             }
	v_pk_fma_f32 v[62:63], v[88:89], v[26:27], v[62:63] neg_lo:[1,0,0] neg_hi:[1,0,0]
	v_pk_fma_f32 v[64:65], v[92:93], v[26:27], v[64:65] neg_lo:[1,0,0] neg_hi:[1,0,0]
	v_pk_fma_f32 v[62:63], v[90:91], v[28:29], v[62:63] neg_lo:[1,0,0] neg_hi:[1,0,0]
	v_pk_fma_f32 v[64:65], v[94:95], v[28:29], v[64:65] neg_lo:[1,0,0] neg_hi:[1,0,0]
	ds_read_b128 v[84:87], v115 offset:18784
	ds_read_b128 v[88:91], v115 offset:18528
	s_waitcnt lgkmcnt(5)
	v_pk_fma_f32 v[62:63], v[96:97], v[30:31], v[62:63] neg_lo:[1,0,0] neg_hi:[1,0,0]
	v_pk_fma_f32 v[64:65], v[68:69], v[30:31], v[64:65] neg_lo:[1,0,0] neg_hi:[1,0,0]
	v_pk_fma_f32 v[62:63], v[98:99], v[32:33], v[62:63] neg_lo:[1,0,0] neg_hi:[1,0,0]
	v_pk_fma_f32 v[64:65], v[70:71], v[32:33], v[64:65] neg_lo:[1,0,0] neg_hi:[1,0,0]
	ds_read_b128 v[92:95], v115 offset:18800
	ds_read_b128 v[96:99], v115 offset:18544
	s_waitcnt lgkmcnt(5)
	v_pk_fma_f32 v[62:63], v[72:73], v[34:35], v[62:63] neg_lo:[1,0,0] neg_hi:[1,0,0]
	v_pk_fma_f32 v[64:65], v[76:77], v[34:35], v[64:65] neg_lo:[1,0,0] neg_hi:[1,0,0]
	v_pk_fma_f32 v[62:63], v[74:75], v[36:37], v[62:63] neg_lo:[1,0,0] neg_hi:[1,0,0]
	v_pk_fma_f32 v[64:65], v[78:79], v[36:37], v[64:65] neg_lo:[1,0,0] neg_hi:[1,0,0]
	ds_read_b128 v[68:71], v115 offset:18816
	ds_read_b128 v[72:75], v115 offset:18560
	s_waitcnt lgkmcnt(5)
	v_pk_fma_f32 v[62:63], v[80:81], v[38:39], v[62:63] neg_lo:[1,0,0] neg_hi:[1,0,0]
	v_pk_fma_f32 v[64:65], v[84:85], v[38:39], v[64:65] neg_lo:[1,0,0] neg_hi:[1,0,0]
	v_pk_fma_f32 v[62:63], v[82:83], v[40:41], v[62:63] neg_lo:[1,0,0] neg_hi:[1,0,0]
	v_pk_fma_f32 v[64:65], v[86:87], v[40:41], v[64:65] neg_lo:[1,0,0] neg_hi:[1,0,0]
	ds_read_b128 v[76:79], v115 offset:18832
	ds_read_b128 v[80:83], v115 offset:18576
	s_waitcnt lgkmcnt(5)
	v_pk_fma_f32 v[62:63], v[88:89], v[42:43], v[62:63] neg_lo:[1,0,0] neg_hi:[1,0,0]
	v_pk_fma_f32 v[64:65], v[92:93], v[42:43], v[64:65] neg_lo:[1,0,0] neg_hi:[1,0,0]
	v_pk_fma_f32 v[62:63], v[90:91], v[44:45], v[62:63] neg_lo:[1,0,0] neg_hi:[1,0,0]
	v_pk_fma_f32 v[64:65], v[94:95], v[44:45], v[64:65] neg_lo:[1,0,0] neg_hi:[1,0,0]
	ds_read_b128 v[84:87], v115 offset:18848
	ds_read_b128 v[88:91], v115 offset:18592
	s_waitcnt lgkmcnt(5)
	v_pk_fma_f32 v[62:63], v[96:97], v[46:47], v[62:63] neg_lo:[1,0,0] neg_hi:[1,0,0]
	v_pk_fma_f32 v[64:65], v[68:69], v[46:47], v[64:65] neg_lo:[1,0,0] neg_hi:[1,0,0]
	v_pk_fma_f32 v[62:63], v[98:99], v[48:49], v[62:63] neg_lo:[1,0,0] neg_hi:[1,0,0]
	v_pk_fma_f32 v[64:65], v[70:71], v[48:49], v[64:65] neg_lo:[1,0,0] neg_hi:[1,0,0]
	ds_read_b128 v[92:95], v115 offset:18864
	ds_read_b32 v96, v115 offset:18880
	s_waitcnt lgkmcnt(5)
	v_pk_fma_f32 v[62:63], v[72:73], v[50:51], v[62:63] neg_lo:[1,0,0] neg_hi:[1,0,0]
	v_pk_fma_f32 v[64:65], v[76:77], v[50:51], v[64:65] neg_lo:[1,0,0] neg_hi:[1,0,0]
	v_pk_fma_f32 v[62:63], v[74:75], v[52:53], v[62:63] neg_lo:[1,0,0] neg_hi:[1,0,0]
	v_pk_fma_f32 v[64:65], v[78:79], v[52:53], v[64:65] neg_lo:[1,0,0] neg_hi:[1,0,0]
	ds_read_b128 v[68:71], v115 offset:18912
	ds_read_b128 v[72:75], v115 offset:19184
	s_waitcnt lgkmcnt(5)
	v_pk_fma_f32 v[62:63], v[80:81], v[54:55], v[62:63] neg_lo:[1,0,0] neg_hi:[1,0,0]
	v_pk_fma_f32 v[64:65], v[84:85], v[54:55], v[64:65] neg_lo:[1,0,0] neg_hi:[1,0,0]
	v_pk_fma_f32 v[62:63], v[82:83], v[56:57], v[62:63] neg_lo:[1,0,0] neg_hi:[1,0,0]
	v_pk_fma_f32 v[64:65], v[86:87], v[56:57], v[64:65] neg_lo:[1,0,0] neg_hi:[1,0,0]
	ds_read_b128 v[76:79], v115 offset:18928
	ds_read_b128 v[80:83], v115 offset:19200
	s_waitcnt lgkmcnt(5)
	v_pk_fma_f32 v[62:63], v[88:89], v[58:59], v[62:63] neg_lo:[1,0,0] neg_hi:[1,0,0]
	v_pk_fma_f32 v[64:65], v[92:93], v[58:59], v[64:65] neg_lo:[1,0,0] neg_hi:[1,0,0]
	v_pk_fma_f32 v[62:63], v[90:91], v[60:61], v[62:63] neg_lo:[1,0,0] neg_hi:[1,0,0]
	v_pk_fma_f32 v[64:65], v[94:95], v[60:61], v[64:65] neg_lo:[1,0,0] neg_hi:[1,0,0]
	ds_read_b128 v[84:87], v115 offset:18944
	ds_read_b128 v[88:91], v115 offset:19216
	s_waitcnt lgkmcnt(6)
	ds_read_b128 v[92:95], v115 offset:18960
	v_add_f32_e32 v62, v62, v63
	v_add_f32_e32 v64, v64, v65
	v_fma_f32 v63, -v96, v62, v64
	v_cmp_eq_u32_e32 vcc, 62, v127
	v_mov_b32_e32 v65, 0
	v_mov_b32_e32 v67, 0
	v_cndmask_b32_e64 v64, 0, 1.0, vcc
	v_cmp_eq_u32_e32 vcc, 63, v127
	s_nop 1
	v_cndmask_b32_e64 v66, 0, 1.0, vcc
	s_waitcnt lgkmcnt(5)
	v_pk_fma_f32 v[64:65], v[68:69], v[2:3], v[64:65] neg_lo:[1,0,0] neg_hi:[1,0,0]
	v_pk_fma_f32 v[66:67], v[72:73], v[2:3], v[66:67] neg_lo:[1,0,0] neg_hi:[1,0,0]
	v_pk_fma_f32 v[64:65], v[70:71], v[4:5], v[64:65] neg_lo:[1,0,0] neg_hi:[1,0,0]
	v_pk_fma_f32 v[66:67], v[74:75], v[4:5], v[66:67] neg_lo:[1,0,0] neg_hi:[1,0,0]
	ds_read_b128 v[96:99], v115 offset:19232
	ds_read_b128 v[68:71], v115 offset:18976
	s_waitcnt lgkmcnt(5)
	v_pk_fma_f32 v[64:65], v[76:77], v[6:7], v[64:65] neg_lo:[1,0,0] neg_hi:[1,0,0]
	v_pk_fma_f32 v[66:67], v[80:81], v[6:7], v[66:67] neg_lo:[1,0,0] neg_hi:[1,0,0]
	v_pk_fma_f32 v[64:65], v[78:79], v[8:9], v[64:65] neg_lo:[1,0,0] neg_hi:[1,0,0]
	v_pk_fma_f32 v[66:67], v[82:83], v[8:9], v[66:67] neg_lo:[1,0,0] neg_hi:[1,0,0]
	ds_read_b128 v[72:75], v115 offset:19248
	ds_read_b128 v[76:79], v115 offset:18992
	s_waitcnt lgkmcnt(5)
	v_pk_fma_f32 v[64:65], v[84:85], v[10:11], v[64:65] neg_lo:[1,0,0] neg_hi:[1,0,0]
	v_pk_fma_f32 v[66:67], v[88:89], v[10:11], v[66:67] neg_lo:[1,0,0] neg_hi:[1,0,0]
	v_pk_fma_f32 v[64:65], v[86:87], v[12:13], v[64:65] neg_lo:[1,0,0] neg_hi:[1,0,0]
	v_pk_fma_f32 v[66:67], v[90:91], v[12:13], v[66:67] neg_lo:[1,0,0] neg_hi:[1,0,0]
	ds_read_b128 v[80:83], v115 offset:19264
	ds_read_b128 v[84:87], v115 offset:19008
	s_waitcnt lgkmcnt(5)
; __device__ __forceinline__ void gdn_chunk_prep(Frame& F) {
;     ...
;             for (int i = 50; i < 64; i += 2) {
;                 float a = (i == lane) ? 1.f : 0.f, bq = (i + 1 == lane) ? 1.f : 0.f;
; #pragma unroll
;                 for (int j = 0; j < i; ++j) { a = fmaf(-Amat[i * 68 + j], T[j], a); bq = fmaf(-Amat[(i + 1) * 68 + j], T[j], bq); }
;                 T[i] = a;
;                 T[i + 1] = fmaf(-Amat[(i + 1) * 68 + i], a, bq);
;                 asm volatile("" ::: "memory");
;             }
	v_pk_fma_f32 v[64:65], v[92:93], v[14:15], v[64:65] neg_lo:[1,0,0] neg_hi:[1,0,0]
	v_pk_fma_f32 v[66:67], v[96:97], v[14:15], v[66:67] neg_lo:[1,0,0] neg_hi:[1,0,0]
	v_pk_fma_f32 v[64:65], v[94:95], v[16:17], v[64:65] neg_lo:[1,0,0] neg_hi:[1,0,0]
	v_pk_fma_f32 v[66:67], v[98:99], v[16:17], v[66:67] neg_lo:[1,0,0] neg_hi:[1,0,0]
	ds_read_b128 v[88:91], v115 offset:19280
	ds_read_b128 v[92:95], v115 offset:19024
	s_waitcnt lgkmcnt(5)
	v_pk_fma_f32 v[64:65], v[68:69], v[18:19], v[64:65] neg_lo:[1,0,0] neg_hi:[1,0,0]
	v_pk_fma_f32 v[66:67], v[72:73], v[18:19], v[66:67] neg_lo:[1,0,0] neg_hi:[1,0,0]
	v_pk_fma_f32 v[64:65], v[70:71], v[20:21], v[64:65] neg_lo:[1,0,0] neg_hi:[1,0,0]
	v_pk_fma_f32 v[66:67], v[74:75], v[20:21], v[66:67] neg_lo:[1,0,0] neg_hi:[1,0,0]
	ds_read_b128 v[96:99], v115 offset:19296
	ds_read_b128 v[68:71], v115 offset:19040
	s_waitcnt lgkmcnt(5)
	v_pk_fma_f32 v[64:65], v[76:77], v[22:23], v[64:65] neg_lo:[1,0,0] neg_hi:[1,0,0]
	v_pk_fma_f32 v[66:67], v[80:81], v[22:23], v[66:67] neg_lo:[1,0,0] neg_hi:[1,0,0]
	v_pk_fma_f32 v[64:65], v[78:79], v[24:25], v[64:65] neg_lo:[1,0,0] neg_hi:[1,0,0]
	v_pk_fma_f32 v[66:67], v[82:83], v[24:25], v[66:67] neg_lo:[1,0,0] neg_hi:[1,0,0]
	ds_read_b128 v[72:75], v115 offset:19312
	ds_read_b128 v[76:79], v115 offset:19056
	s_waitcnt lgkmcnt(5)
	v_pk_fma_f32 v[64:65], v[84:85], v[26:27], v[64:65] neg_lo:[1,0,0] neg_hi:[1,0,0]
	v_pk_fma_f32 v[66:67], v[88:89], v[26:27], v[66:67] neg_lo:[1,0,0] neg_hi:[1,0,0]
	v_pk_fma_f32 v[64:65], v[86:87], v[28:29], v[64:65] neg_lo:[1,0,0] neg_hi:[1,0,0]
	v_pk_fma_f32 v[66:67], v[90:91], v[28:29], v[66:67] neg_lo:[1,0,0] neg_hi:[1,0,0]
	ds_read_b128 v[80:83], v115 offset:19328
	ds_read_b128 v[84:87], v115 offset:19072
	s_waitcnt lgkmcnt(5)
	v_pk_fma_f32 v[64:65], v[92:93], v[30:31], v[64:65] neg_lo:[1,0,0] neg_hi:[1,0,0]
	v_pk_fma_f32 v[66:67], v[96:97], v[30:31], v[66:67] neg_lo:[1,0,0] neg_hi:[1,0,0]
	v_pk_fma_f32 v[64:65], v[94:95], v[32:33], v[64:65] neg_lo:[1,0,0] neg_hi:[1,0,0]
	v_pk_fma_f32 v[66:67], v[98:99], v[32:33], v[66:67] neg_lo:[1,0,0] neg_hi:[1,0,0]
	ds_read_b128 v[88:91], v115 offset:19344
	ds_read_b128 v[92:95], v115 offset:19088
	s_waitcnt lgkmcnt(5)
	v_pk_fma_f32 v[64:65], v[68:69], v[34:35], v[64:65] neg_lo:[1,0,0] neg_hi:[1,0,0]
	v_pk_fma_f32 v[66:67], v[72:73], v[34:35], v[66:67] neg_lo:[1,0,0] neg_hi:[1,0,0]
	v_pk_fma_f32 v[64:65], v[70:71], v[36:37], v[64:65] neg_lo:[1,0,0] neg_hi:[1,0,0]
	v_pk_fma_f32 v[66:67], v[74:75], v[36:37], v[66:67] neg_lo:[1,0,0] neg_hi:[1,0,0]
	ds_read_b128 v[96:99], v115 offset:19360
	ds_read_b128 v[68:71], v115 offset:19104
	s_waitcnt lgkmcnt(5)
	v_pk_fma_f32 v[64:65], v[76:77], v[38:39], v[64:65] neg_lo:[1,0,0] neg_hi:[1,0,0]
	v_pk_fma_f32 v[66:67], v[80:81], v[38:39], v[66:67] neg_lo:[1,0,0] neg_hi:[1,0,0]
	v_pk_fma_f32 v[64:65], v[78:79], v[40:41], v[64:65] neg_lo:[1,0,0] neg_hi:[1,0,0]
	v_pk_fma_f32 v[66:67], v[82:83], v[40:41], v[66:67] neg_lo:[1,0,0] neg_hi:[1,0,0]
	ds_read_b128 v[72:75], v115 offset:19376
	ds_read_b128 v[76:79], v115 offset:19120
	s_waitcnt lgkmcnt(5)
	v_pk_fma_f32 v[64:65], v[84:85], v[42:43], v[64:65] neg_lo:[1,0,0] neg_hi:[1,0,0]
	v_pk_fma_f32 v[66:67], v[88:89], v[42:43], v[66:67] neg_lo:[1,0,0] neg_hi:[1,0,0]
	v_pk_fma_f32 v[64:65], v[86:87], v[44:45], v[64:65] neg_lo:[1,0,0] neg_hi:[1,0,0]
	v_pk_fma_f32 v[66:67], v[90:91], v[44:45], v[66:67] neg_lo:[1,0,0] neg_hi:[1,0,0]
	ds_read_b128 v[80:83], v115 offset:19392
	ds_read_b128 v[84:87], v115 offset:19136
	s_waitcnt lgkmcnt(5)
	v_pk_fma_f32 v[64:65], v[92:93], v[46:47], v[64:65] neg_lo:[1,0,0] neg_hi:[1,0,0]
	v_pk_fma_f32 v[66:67], v[96:97], v[46:47], v[66:67] neg_lo:[1,0,0] neg_hi:[1,0,0]
	v_pk_fma_f32 v[64:65], v[94:95], v[48:49], v[64:65] neg_lo:[1,0,0] neg_hi:[1,0,0]
	v_pk_fma_f32 v[66:67], v[98:99], v[48:49], v[66:67] neg_lo:[1,0,0] neg_hi:[1,0,0]
	ds_read_b128 v[88:91], v115 offset:19408
	ds_read_b128 v[92:95], v115 offset:19152
	s_waitcnt lgkmcnt(5)
	v_pk_fma_f32 v[64:65], v[68:69], v[50:51], v[64:65] neg_lo:[1,0,0] neg_hi:[1,0,0]
	v_pk_fma_f32 v[66:67], v[72:73], v[50:51], v[66:67] neg_lo:[1,0,0] neg_hi:[1,0,0]
	v_pk_fma_f32 v[64:65], v[70:71], v[52:53], v[64:65] neg_lo:[1,0,0] neg_hi:[1,0,0]
	v_pk_fma_f32 v[66:67], v[74:75], v[52:53], v[66:67] neg_lo:[1,0,0] neg_hi:[1,0,0]
	ds_read_b128 v[96:99], v115 offset:19424
	s_waitcnt lgkmcnt(4)
	v_pk_fma_f32 v[64:65], v[76:77], v[54:55], v[64:65] neg_lo:[1,0,0] neg_hi:[1,0,0]
	v_pk_fma_f32 v[66:67], v[80:81], v[54:55], v[66:67] neg_lo:[1,0,0] neg_hi:[1,0,0]
	v_pk_fma_f32 v[64:65], v[78:79], v[56:57], v[64:65] neg_lo:[1,0,0] neg_hi:[1,0,0]
	v_pk_fma_f32 v[66:67], v[82:83], v[56:57], v[66:67] neg_lo:[1,0,0] neg_hi:[1,0,0]
	s_waitcnt lgkmcnt(2)
	v_pk_fma_f32 v[64:65], v[84:85], v[58:59], v[64:65] neg_lo:[1,0,0] neg_hi:[1,0,0]
	v_pk_fma_f32 v[66:67], v[88:89], v[58:59], v[66:67] neg_lo:[1,0,0] neg_hi:[1,0,0]
	v_pk_fma_f32 v[64:65], v[86:87], v[60:61], v[64:65] neg_lo:[1,0,0] neg_hi:[1,0,0]
	v_pk_fma_f32 v[66:67], v[90:91], v[60:61], v[66:67] neg_lo:[1,0,0] neg_hi:[1,0,0]
	s_waitcnt lgkmcnt(0)
; __device__ __forceinline__ unsigned f2bf(float f) { unsigned u = __builtin_bit_cast(unsigned, f); return (u + 0x7fffu + ((u >> 16) & 1u)) >> 16; }
; __device__ __forceinline__ void gdn_chunk_prep(Frame& F) {
;     ...
;             for (int i = 50; i < 64; i += 2) {
;                 float a = (i == lane) ? 1.f : 0.f, bq = (i + 1 == lane) ? 1.f : 0.f;
; #pragma unroll
;                 for (int j = 0; j < i; ++j) { a = fmaf(-Amat[i * 68 + j], T[j], a); bq = fmaf(-Amat[(i + 1) * 68 + j], T[j], bq); }
;                 T[i] = a;
;                 T[i + 1] = fmaf(-Amat[(i + 1) * 68 + i], a, bq);
;                 asm volatile("" ::: "memory");
;             }
; #pragma unroll
;             for (int i = 0; i < 64; ++i) Tb[i * 72 + lane] = (bf16)f2bf(T[i]);
	v_pk_fma_f32 v[64:65], v[92:93], v[62:63], v[64:65] neg_lo:[1,0,0] neg_hi:[1,0,0]
	v_pk_fma_f32 v[66:67], v[96:97], v[62:63], v[66:67] neg_lo:[1,0,0] neg_hi:[1,0,0]
	v_add_f32_e32 v64, v64, v65
	v_add_f32_e32 v66, v66, v67
	v_fma_f32 v65, -v98, v64, v66
	v_lshl_add_u32 v68, v127, 1, 0
	v_bfe_u32 v69, v2, 16, 1
	v_add3_u32 v69, v2, v69, s84
	ds_write_b16_d16_hi v68, v69 offset:19456
	v_bfe_u32 v70, v3, 16, 1
	v_add3_u32 v70, v3, v70, s84
	ds_write_b16_d16_hi v68, v70 offset:19600
	v_bfe_u32 v71, v4, 16, 1
	v_add3_u32 v71, v4, v71, s84
	ds_write_b16_d16_hi v68, v71 offset:19744
	v_bfe_u32 v72, v5, 16, 1
	v_add3_u32 v72, v5, v72, s84
	ds_write_b16_d16_hi v68, v72 offset:19888
	v_bfe_u32 v73, v6, 16, 1
	v_add3_u32 v73, v6, v73, s84
	ds_write_b16_d16_hi v68, v73 offset:20032
	v_bfe_u32 v74, v7, 16, 1
	v_add3_u32 v74, v7, v74, s84
	ds_write_b16_d16_hi v68, v74 offset:20176
	v_bfe_u32 v75, v8, 16, 1
	v_add3_u32 v75, v8, v75, s84
	ds_write_b16_d16_hi v68, v75 offset:20320
	v_bfe_u32 v76, v9, 16, 1
	v_add3_u32 v76, v9, v76, s84
	ds_write_b16_d16_hi v68, v76 offset:20464
	v_bfe_u32 v69, v10, 16, 1
	v_add3_u32 v69, v10, v69, s84
	ds_write_b16_d16_hi v68, v69 offset:20608
	v_bfe_u32 v70, v11, 16, 1
	v_add3_u32 v70, v11, v70, s84
	ds_write_b16_d16_hi v68, v70 offset:20752
	v_bfe_u32 v71, v12, 16, 1
	v_add3_u32 v71, v12, v71, s84
	ds_write_b16_d16_hi v68, v71 offset:20896
	v_bfe_u32 v72, v13, 16, 1
	v_add3_u32 v72, v13, v72, s84
	ds_write_b16_d16_hi v68, v72 offset:21040
	v_bfe_u32 v73, v14, 16, 1
	v_add3_u32 v73, v14, v73, s84
	ds_write_b16_d16_hi v68, v73 offset:21184
	v_bfe_u32 v74, v15, 16, 1
	v_add3_u32 v74, v15, v74, s84
	ds_write_b16_d16_hi v68, v74 offset:21328
	v_bfe_u32 v75, v16, 16, 1
	v_add3_u32 v75, v16, v75, s84
	ds_write_b16_d16_hi v68, v75 offset:21472
	v_bfe_u32 v76, v17, 16, 1
	v_add3_u32 v76, v17, v76, s84
	ds_write_b16_d16_hi v68, v76 offset:21616
	v_bfe_u32 v69, v18, 16, 1
	v_add3_u32 v69, v18, v69, s84
	ds_write_b16_d16_hi v68, v69 offset:21760
	v_bfe_u32 v70, v19, 16, 1
	v_add3_u32 v70, v19, v70, s84
	ds_write_b16_d16_hi v68, v70 offset:21904
	v_bfe_u32 v71, v20, 16, 1
	v_add3_u32 v71, v20, v71, s84
	ds_write_b16_d16_hi v68, v71 offset:22048
	v_bfe_u32 v72, v21, 16, 1
	v_add3_u32 v72, v21, v72, s84
	ds_write_b16_d16_hi v68, v72 offset:22192
	v_bfe_u32 v73, v22, 16, 1
	v_add3_u32 v73, v22, v73, s84
	ds_write_b16_d16_hi v68, v73 offset:22336
	v_bfe_u32 v74, v23, 16, 1
	v_add3_u32 v74, v23, v74, s84
	ds_write_b16_d16_hi v68, v74 offset:22480
	v_bfe_u32 v75, v24, 16, 1
	v_add3_u32 v75, v24, v75, s84
	ds_write_b16_d16_hi v68, v75 offset:22624
	v_bfe_u32 v76, v25, 16, 1
	v_add3_u32 v76, v25, v76, s84
	ds_write_b16_d16_hi v68, v76 offset:22768
	v_bfe_u32 v69, v26, 16, 1
	v_add3_u32 v69, v26, v69, s84
	ds_write_b16_d16_hi v68, v69 offset:22912
	v_bfe_u32 v70, v27, 16, 1
	v_add3_u32 v70, v27, v70, s84
	ds_write_b16_d16_hi v68, v70 offset:23056
	v_bfe_u32 v71, v28, 16, 1
	v_add3_u32 v71, v28, v71, s84
	ds_write_b16_d16_hi v68, v71 offset:23200
	v_bfe_u32 v72, v29, 16, 1
	v_add3_u32 v72, v29, v72, s84
	ds_write_b16_d16_hi v68, v72 offset:23344
	v_bfe_u32 v73, v30, 16, 1
	v_add3_u32 v73, v30, v73, s84
	ds_write_b16_d16_hi v68, v73 offset:23488
	v_bfe_u32 v74, v31, 16, 1
	v_add3_u32 v74, v31, v74, s84
	ds_write_b16_d16_hi v68, v74 offset:23632
	v_bfe_u32 v75, v32, 16, 1
	v_add3_u32 v75, v32, v75, s84
	ds_write_b16_d16_hi v68, v75 offset:23776
	v_bfe_u32 v76, v33, 16, 1
	v_add3_u32 v76, v33, v76, s84
	ds_write_b16_d16_hi v68, v76 offset:23920
	v_bfe_u32 v69, v34, 16, 1
	v_add3_u32 v69, v34, v69, s84
	ds_write_b16_d16_hi v68, v69 offset:24064
	v_bfe_u32 v70, v35, 16, 1
	v_add3_u32 v70, v35, v70, s84
	ds_write_b16_d16_hi v68, v70 offset:24208
	v_bfe_u32 v71, v36, 16, 1
	v_add3_u32 v71, v36, v71, s84
	ds_write_b16_d16_hi v68, v71 offset:24352
	v_bfe_u32 v72, v37, 16, 1
	v_add3_u32 v72, v37, v72, s84
	ds_write_b16_d16_hi v68, v72 offset:24496
	v_bfe_u32 v73, v38, 16, 1
	v_add3_u32 v73, v38, v73, s84
	ds_write_b16_d16_hi v68, v73 offset:24640
	v_bfe_u32 v74, v39, 16, 1
	v_add3_u32 v74, v39, v74, s84
	ds_write_b16_d16_hi v68, v74 offset:24784
	v_bfe_u32 v75, v40, 16, 1
	v_add3_u32 v75, v40, v75, s84
	ds_write_b16_d16_hi v68, v75 offset:24928
	v_bfe_u32 v76, v41, 16, 1
	v_add3_u32 v76, v41, v76, s84
	ds_write_b16_d16_hi v68, v76 offset:25072
	v_bfe_u32 v69, v42, 16, 1
	v_add3_u32 v69, v42, v69, s84
	ds_write_b16_d16_hi v68, v69 offset:25216
	v_bfe_u32 v70, v43, 16, 1
	v_add3_u32 v70, v43, v70, s84
	ds_write_b16_d16_hi v68, v70 offset:25360
	v_bfe_u32 v71, v44, 16, 1
	v_add3_u32 v71, v44, v71, s84
	ds_write_b16_d16_hi v68, v71 offset:25504
	v_bfe_u32 v72, v45, 16, 1
	v_add3_u32 v72, v45, v72, s84
	ds_write_b16_d16_hi v68, v72 offset:25648
	v_bfe_u32 v73, v46, 16, 1
	v_add3_u32 v73, v46, v73, s84
	ds_write_b16_d16_hi v68, v73 offset:25792
	v_bfe_u32 v74, v47, 16, 1
	v_add3_u32 v74, v47, v74, s84
	ds_write_b16_d16_hi v68, v74 offset:25936
	v_bfe_u32 v75, v48, 16, 1
	v_add3_u32 v75, v48, v75, s84
	ds_write_b16_d16_hi v68, v75 offset:26080
	v_bfe_u32 v76, v49, 16, 1
	v_add3_u32 v76, v49, v76, s84
	ds_write_b16_d16_hi v68, v76 offset:26224
	v_bfe_u32 v69, v50, 16, 1
	v_add3_u32 v69, v50, v69, s84
	ds_write_b16_d16_hi v68, v69 offset:26368
	v_bfe_u32 v70, v51, 16, 1
	v_add3_u32 v70, v51, v70, s84
	ds_write_b16_d16_hi v68, v70 offset:26512
	v_bfe_u32 v71, v52, 16, 1
	v_add3_u32 v71, v52, v71, s84
	ds_write_b16_d16_hi v68, v71 offset:26656
	v_bfe_u32 v72, v53, 16, 1
	v_add3_u32 v72, v53, v72, s84
	ds_write_b16_d16_hi v68, v72 offset:26800
	v_bfe_u32 v73, v54, 16, 1
	v_add3_u32 v73, v54, v73, s84
	ds_write_b16_d16_hi v68, v73 offset:26944
	v_bfe_u32 v74, v55, 16, 1
	v_add3_u32 v74, v55, v74, s84
	ds_write_b16_d16_hi v68, v74 offset:27088
	v_bfe_u32 v75, v56, 16, 1
	v_add3_u32 v75, v56, v75, s84
	ds_write_b16_d16_hi v68, v75 offset:27232
	v_bfe_u32 v76, v57, 16, 1
	v_add3_u32 v76, v57, v76, s84
	ds_write_b16_d16_hi v68, v76 offset:27376
	v_bfe_u32 v69, v58, 16, 1
	v_add3_u32 v69, v58, v69, s84
	ds_write_b16_d16_hi v68, v69 offset:27520
	v_bfe_u32 v70, v59, 16, 1
	v_add3_u32 v70, v59, v70, s84
	ds_write_b16_d16_hi v68, v70 offset:27664
	v_bfe_u32 v71, v60, 16, 1
	v_add3_u32 v71, v60, v71, s84
	ds_write_b16_d16_hi v68, v71 offset:27808
	v_bfe_u32 v72, v61, 16, 1
	v_add3_u32 v72, v61, v72, s84
	ds_write_b16_d16_hi v68, v72 offset:27952
	v_bfe_u32 v73, v62, 16, 1
	v_add3_u32 v73, v62, v73, s84
	ds_write_b16_d16_hi v68, v73 offset:28096
	v_bfe_u32 v74, v63, 16, 1
	v_add3_u32 v74, v63, v74, s84
	ds_write_b16_d16_hi v68, v74 offset:28240
	v_bfe_u32 v75, v64, 16, 1
	v_add3_u32 v75, v64, v75, s84
	ds_write_b16_d16_hi v68, v75 offset:28384
	v_bfe_u32 v76, v65, 16, 1
	v_add3_u32 v76, v65, v76, s84
	ds_write_b16_d16_hi v68, v76 offset:28528
